# MFMA issue order inside each 8-group of the 4 GEMM K-loops changed so consecutive MFMAs share the first source operand in pairs (snake), rest as v69
# speedup vs baseline: 1.0005x; 1.0005x over previous
; #define PG8_STAGE(bufoff, gbase, voff) do { _Pragma("unroll") for (int _i = 0; _i < 2; ++_i) \
;         __builtin_amdgcn_global_load_lds((const unsigned*)((const char*)(gbase) + (voff)[_i]), (LAS unsigned*)(lds + (bufoff) + ldsw + _i * 8192), 16, 0, 0); } while (0)
; #define PG8_LDA(dst, b, h) do { _Pragma("unroll") for (int m = 0; m < 4; ++m) _Pragma("unroll") for (int k = 0; k < 2; ++k) dst[m][k] = *(const LAS bf16x8*)(lds + PG8_SA(b, h) + aoff + m * 2048 + k * 1024); } while (0)
; #define PG8_LDB(dst, b, h) do { _Pragma("unroll") for (int n = 0; n < 2; ++n) _Pragma("unroll") for (int k = 0; k < 2; ++k) dst[n][k] = *(const LAS bf16x8*)(lds + PG8_SB(b, h) + boff + n * 2048 + k * 1024); } while (0)
; #define PG8_SCHED __builtin_amdgcn_sched_barrier(0)
; template <class Epi, bool ALIGN_EPI>
; __device__ __forceinline__ void gemm_phase(LAS unsigned char* lds, const Gemm g, const StaticOrder& S, const Epi& E, const int tid) {
;     ...
;             const bool last = (t == nt - 2);
;             const char* a1 = cA + (size_t)(t + 1) * kstepA;
;             const char* a2 = last ? nA : cA + (size_t)(t + 2) * kstepA; const char* b2 = last ? nB : cB + (size_t)(t + 2) * kstepB;
;             const char* a3 = a2 + kstepA; const char* b3 = b2 + kstepB;
;             PG8_LDB(B0, 0, 0); PG8_LDB(B1, 0, 1); PG8_SCHED; PG8_LDA(At, 0, 0); PG8_STAGE(PG8_SA(1, 1), a1 + hstepA, voffA);
.LBB0_211:
	s_add_u32 s50, s48, 0x4000
	s_addc_u32 s51, s49, 0
	s_cmp_eq_u32 s89, 28
	s_cselect_b32 s54, s87, s50
	s_cselect_b32 s55, s43, s51
	s_cselect_b32 s52, vcc_lo, vcc_hi
	s_cselect_b32 s53, s35, s88
	s_add_u32 s50, s54, 0x8000
	s_addc_u32 s51, s55, 0
	s_add_i32 s90, 0, 0x10000
	v_add_u32_e32 v0, s90, v160
	s_add_i32 s92, 0, 0x14000
	ds_read_b128 v[132:135], v0
	ds_read_b128 v[136:139], v0 offset:1024
	ds_read_b128 v[152:155], v0 offset:2048
	ds_read_b128 v[156:159], v0 offset:3072
	v_add_u32_e32 v0, s92, v160
	ds_read_b128 v[162:165], v0
	ds_read_b128 v[166:169], v0 offset:1024
	ds_read_b128 v[170:173], v0 offset:2048
	ds_read_b128 v[174:177], v0 offset:3072
	s_add_i32 m0, s72, 0xc000
	ds_read_b128 v[178:181], v161
	ds_read_b128 v[182:185], v161 offset:1024
	ds_read_b128 v[186:189], v161 offset:2048
	ds_read_b128 v[190:193], v161 offset:3072
	ds_read_b128 v[194:197], v161 offset:4096
	ds_read_b128 v[198:201], v161 offset:5120
	ds_read_b128 v[214:217], v161 offset:6144

; #define PG8_STAGE(bufoff, gbase, voff) do { _Pragma("unroll") for (int _i = 0; _i < 2; ++_i) \
;         __builtin_amdgcn_global_load_lds((const unsigned*)((const char*)(gbase) + (voff)[_i]), (LAS unsigned*)(lds + (bufoff) + ldsw + _i * 8192), 16, 0, 0); } while (0)
; #define PG8_LDA(dst, b, h) do { _Pragma("unroll") for (int m = 0; m < 4; ++m) _Pragma("unroll") for (int k = 0; k < 2; ++k) dst[m][k] = *(const LAS bf16x8*)(lds + PG8_SA(b, h) + aoff + m * 2048 + k * 1024); } while (0)
; #define PG8_LDB(dst, b, h) do { _Pragma("unroll") for (int n = 0; n < 2; ++n) _Pragma("unroll") for (int k = 0; k < 2; ++k) dst[n][k] = *(const LAS bf16x8*)(lds + PG8_SB(b, h) + boff + n * 2048 + k * 1024); } while (0)
; #define PG8_MMA(ai, bj, At, Bt) do { __builtin_amdgcn_s_setprio(1); _Pragma("unroll") for (int m = 0; m < 4; ++m) _Pragma("unroll") for (int n = 0; n < 2; ++n) _Pragma("unroll") for (int k = 0; k < 2; ++k) \
;         acc[ai][bj][m][n] = __builtin_amdgcn_mfma_f32_16x16x32_bf16(Bt[n][k], At[m][k], acc[ai][bj][m][n], 0, 0, 0); __builtin_amdgcn_s_setprio(0); } while (0)
; #define PG8_WAIT_V(n) asm volatile("s_waitcnt vmcnt(" #n ")" ::: "memory")
; #define PG8_WAIT_L(n) asm volatile("s_waitcnt lgkmcnt(" #n ")" ::: "memory")
; #define PG8_BAR __builtin_amdgcn_s_barrier()
; #define PG8_SCHED __builtin_amdgcn_sched_barrier(0)
; template <class Epi, bool ALIGN_EPI>
; __device__ __forceinline__ void gemm_phase(LAS unsigned char* lds, const Gemm g, const StaticOrder& S, const Epi& E, const int tid) {
;     ...
;             PG8_LDB(B0, 0, 0); PG8_LDB(B1, 0, 1); PG8_SCHED; PG8_LDA(At, 0, 0); PG8_STAGE(PG8_SA(1, 1), a1 + hstepA, voffA);
;             PG8_WAIT_V(8); PG8_WAIT_L(0); PG8_BAR; PG8_MMA(0, 0, At, B0); PG8_MMA(0, 1, At, B1); PG8_BAR; PG8_SCHED;
	global_load_lds_dwordx4 v148, s[48:49]
	s_add_i32 m0, s72, 0xe000
	ds_read_b128 v[218:221], v161 offset:7168
	global_load_lds_dwordx4 v150, s[48:49]
	s_waitcnt vmcnt(8)
	s_waitcnt lgkmcnt(0)
	s_barrier


; #define PG8_MMA(ai, bj, At, Bt) do { __builtin_amdgcn_s_setprio(1); _Pragma("unroll") for (int m = 0; m < 4; ++m) _Pragma("unroll") for (int n = 0; n < 2; ++n) _Pragma("unroll") for (int k = 0; k < 2; ++k) \
;         acc[ai][bj][m][n] = __builtin_amdgcn_mfma_f32_16x16x32_bf16(Bt[n][k], At[m][k], acc[ai][bj][m][n], 0, 0, 0); __builtin_amdgcn_s_setprio(0); } while (0)
; #define PG8_WAIT_V(n) asm volatile("s_waitcnt vmcnt(" #n ")" ::: "memory")
; #define PG8_WAIT_L(n) asm volatile("s_waitcnt lgkmcnt(" #n ")" ::: "memory")
; #define PG8_BAR __builtin_amdgcn_s_barrier()
; #define PG8_SCHED __builtin_amdgcn_sched_barrier(0)
; template <class Epi, bool ALIGN_EPI>
; __device__ __forceinline__ void gemm_phase(LAS unsigned char* lds, const Gemm g, const StaticOrder& S, const Epi& E, const int tid) {
;     ...
;             PG8_WAIT_V(8); PG8_WAIT_L(0); PG8_BAR; PG8_MMA(0, 0, At, B0); PG8_MMA(0, 1, At, B1); PG8_BAR; PG8_SCHED;
	v_mfma_f32_16x16x32_bf16 v[88:91], v[132:135], v[178:181], v[88:91]
	v_mfma_f32_16x16x32_bf16 v[52:55], v[132:135], v[186:189], v[52:55]
	v_mfma_f32_16x16x32_bf16 v[120:123], v[152:155], v[186:189], v[120:123]
	v_mfma_f32_16x16x32_bf16 v[124:127], v[152:155], v[178:181], v[124:127]
	v_mfma_f32_16x16x32_bf16 v[40:43], v[132:135], v[194:197], v[40:43]
	v_mfma_f32_16x16x32_bf16 v[36:39], v[132:135], v[214:217], v[36:39]
	v_mfma_f32_16x16x32_bf16 v[112:115], v[152:155], v[214:217], v[112:115]
	v_mfma_f32_16x16x32_bf16 v[116:119], v[152:155], v[194:197], v[116:119]
	v_mfma_f32_16x16x32_bf16 v[88:91], v[136:139], v[182:185], v[88:91]
	v_mfma_f32_16x16x32_bf16 v[52:55], v[136:139], v[190:193], v[52:55]
	v_mfma_f32_16x16x32_bf16 v[120:123], v[156:159], v[190:193], v[120:123]
	v_mfma_f32_16x16x32_bf16 v[124:127], v[156:159], v[182:185], v[124:127]
	v_mfma_f32_16x16x32_bf16 v[40:43], v[136:139], v[198:201], v[40:43]
	v_mfma_f32_16x16x32_bf16 v[36:39], v[136:139], v[218:221], v[36:39]
	v_mfma_f32_16x16x32_bf16 v[112:115], v[156:159], v[218:221], v[112:115]
	v_mfma_f32_16x16x32_bf16 v[116:119], v[156:159], v[198:201], v[116:119]


; #define PG8_MMA(ai, bj, At, Bt) do { __builtin_amdgcn_s_setprio(1); _Pragma("unroll") for (int m = 0; m < 4; ++m) _Pragma("unroll") for (int n = 0; n < 2; ++n) _Pragma("unroll") for (int k = 0; k < 2; ++k) \
;         acc[ai][bj][m][n] = __builtin_amdgcn_mfma_f32_16x16x32_bf16(Bt[n][k], At[m][k], acc[ai][bj][m][n], 0, 0, 0); __builtin_amdgcn_s_setprio(0); } while (0)
; #define PG8_WAIT_V(n) asm volatile("s_waitcnt vmcnt(" #n ")" ::: "memory")
; #define PG8_WAIT_L(n) asm volatile("s_waitcnt lgkmcnt(" #n ")" ::: "memory")
; #define PG8_BAR __builtin_amdgcn_s_barrier()
; #define PG8_SCHED __builtin_amdgcn_sched_barrier(0)
; template <class Epi, bool ALIGN_EPI>
; __device__ __forceinline__ void gemm_phase(LAS unsigned char* lds, const Gemm g, const StaticOrder& S, const Epi& E, const int tid) {
;     ...
;             PG8_WAIT_V(8); PG8_WAIT_L(0); PG8_BAR; PG8_MMA(0, 0, At, B0); PG8_MMA(0, 1, At, B1); PG8_BAR; PG8_SCHED;
	v_mfma_f32_16x16x32_bf16 v[80:83], v[162:165], v[178:181], v[80:83]
	v_mfma_f32_16x16x32_bf16 v[68:71], v[162:165], v[186:189], v[68:71]
	v_mfma_f32_16x16x32_bf16 v[108:111], v[170:173], v[186:189], v[108:111]
	v_mfma_f32_16x16x32_bf16 v[128:131], v[170:173], v[178:181], v[128:131]
	v_mfma_f32_16x16x32_bf16 v[60:63], v[162:165], v[194:197], v[60:63]
	v_mfma_f32_16x16x32_bf16 v[48:51], v[162:165], v[214:217], v[48:51]
	v_mfma_f32_16x16x32_bf16 v[100:103], v[170:173], v[214:217], v[100:103]
	v_mfma_f32_16x16x32_bf16 v[104:107], v[170:173], v[194:197], v[104:107]
	v_mfma_f32_16x16x32_bf16 v[80:83], v[166:169], v[182:185], v[80:83]
	v_mfma_f32_16x16x32_bf16 v[68:71], v[166:169], v[190:193], v[68:71]
	v_mfma_f32_16x16x32_bf16 v[108:111], v[174:177], v[190:193], v[108:111]
	v_mfma_f32_16x16x32_bf16 v[128:131], v[174:177], v[182:185], v[128:131]
	v_mfma_f32_16x16x32_bf16 v[60:63], v[166:169], v[198:201], v[60:63]
	v_mfma_f32_16x16x32_bf16 v[48:51], v[166:169], v[218:221], v[48:51]
	v_mfma_f32_16x16x32_bf16 v[100:103], v[174:177], v[218:221], v[100:103]
	v_mfma_f32_16x16x32_bf16 v[104:107], v[174:177], v[198:201], v[104:107]

; #define PG8_STAGE(bufoff, gbase, voff) do { _Pragma("unroll") for (int _i = 0; _i < 2; ++_i) \
;         __builtin_amdgcn_global_load_lds((const unsigned*)((const char*)(gbase) + (voff)[_i]), (LAS unsigned*)(lds + (bufoff) + ldsw + _i * 8192), 16, 0, 0); } while (0)
; #define PG8_LDA(dst, b, h) do { _Pragma("unroll") for (int m = 0; m < 4; ++m) _Pragma("unroll") for (int k = 0; k < 2; ++k) dst[m][k] = *(const LAS bf16x8*)(lds + PG8_SA(b, h) + aoff + m * 2048 + k * 1024); } while (0)
; #define PG8_MMA(ai, bj, At, Bt) do { __builtin_amdgcn_s_setprio(1); _Pragma("unroll") for (int m = 0; m < 4; ++m) _Pragma("unroll") for (int n = 0; n < 2; ++n) _Pragma("unroll") for (int k = 0; k < 2; ++k) \
;         acc[ai][bj][m][n] = __builtin_amdgcn_mfma_f32_16x16x32_bf16(Bt[n][k], At[m][k], acc[ai][bj][m][n], 0, 0, 0); __builtin_amdgcn_s_setprio(0); } while (0)
; #define PG8_WAIT_V(n) asm volatile("s_waitcnt vmcnt(" #n ")" ::: "memory")
; #define PG8_WAIT_L(n) asm volatile("s_waitcnt lgkmcnt(" #n ")" ::: "memory")
; #define PG8_BAR __builtin_amdgcn_s_barrier()
; #define PG8_SCHED __builtin_amdgcn_sched_barrier(0)
; template <class Epi, bool ALIGN_EPI>
; __device__ __forceinline__ void gemm_phase(LAS unsigned char* lds, const Gemm g, const StaticOrder& S, const Epi& E, const int tid) {
;     ...
;             PG8_WAIT_V(8); PG8_WAIT_L(0); PG8_BAR; PG8_MMA(0, 0, At, B0); PG8_MMA(0, 1, At, B1); PG8_BAR; PG8_SCHED;
;             PG8_LDA(At, 0, 1); PG8_STAGE(PG8_SB(0, 0), b2, voffB); PG8_STAGE(PG8_SB(0, 1), b2 + hstepB, voffB); PG8_STAGE(PG8_SA(0, 0), a2, voffA);
	s_barrier
	s_add_i32 s90, s90, s71
	s_mov_b32 m0, s90
	ds_read_b128 v[178:181], v161 offset:16384
	ds_read_b128 v[182:185], v161 offset:17408
	ds_read_b128 v[186:189], v161 offset:18432
	ds_read_b128 v[190:193], v161 offset:19456


; #define PG8_STAGE(bufoff, gbase, voff) do { _Pragma("unroll") for (int _i = 0; _i < 2; ++_i) \
;         __builtin_amdgcn_global_load_lds((const unsigned*)((const char*)(gbase) + (voff)[_i]), (LAS unsigned*)(lds + (bufoff) + ldsw + _i * 8192), 16, 0, 0); } while (0)
; #define PG8_LDA(dst, b, h) do { _Pragma("unroll") for (int m = 0; m < 4; ++m) _Pragma("unroll") for (int k = 0; k < 2; ++k) dst[m][k] = *(const LAS bf16x8*)(lds + PG8_SA(b, h) + aoff + m * 2048 + k * 1024); } while (0)
; #define PG8_MMA(ai, bj, At, Bt) do { __builtin_amdgcn_s_setprio(1); _Pragma("unroll") for (int m = 0; m < 4; ++m) _Pragma("unroll") for (int n = 0; n < 2; ++n) _Pragma("unroll") for (int k = 0; k < 2; ++k) \
;         acc[ai][bj][m][n] = __builtin_amdgcn_mfma_f32_16x16x32_bf16(Bt[n][k], At[m][k], acc[ai][bj][m][n], 0, 0, 0); __builtin_amdgcn_s_setprio(0); } while (0)
; #define PG8_WAIT_V(n) asm volatile("s_waitcnt vmcnt(" #n ")" ::: "memory")
; #define PG8_WAIT_L(n) asm volatile("s_waitcnt lgkmcnt(" #n ")" ::: "memory")
; #define PG8_BAR __builtin_amdgcn_s_barrier()
; #define PG8_SCHED __builtin_amdgcn_sched_barrier(0)
; template <class Epi, bool ALIGN_EPI>
; __device__ __forceinline__ void gemm_phase(LAS unsigned char* lds, const Gemm g, const StaticOrder& S, const Epi& E, const int tid) {
;     ...
;             PG8_LDA(At, 0, 1); PG8_STAGE(PG8_SB(0, 0), b2, voffB); PG8_STAGE(PG8_SB(0, 1), b2 + hstepB, voffB); PG8_STAGE(PG8_SA(0, 0), a2, voffA);
;             PG8_WAIT_V(8); PG8_WAIT_L(0); PG8_BAR; PG8_MMA(1, 0, At, B0); PG8_MMA(1, 1, At, B1); PG8_BAR; PG8_SCHED;
	global_load_lds_dwordx4 v144, s[52:53]
	s_add_i32 m0, s90, 0x2000
	s_add_u32 s90, s52, 0x4000
	s_addc_u32 s91, s53, 0
	s_add_i32 s92, s92, s71
	global_load_lds_dwordx4 v140, s[52:53]
	s_mov_b32 m0, s92
	ds_read_b128 v[218:221], v161 offset:23552
	global_load_lds_dwordx4 v144, s[90:91]
	s_add_i32 m0, s92, 0x2000
	ds_read_b128 v[214:217], v161 offset:22528
	global_load_lds_dwordx4 v140, s[90:91]
	s_mov_b32 m0, s72
	ds_read_b128 v[198:201], v161 offset:21504
	global_load_lds_dwordx4 v146, s[54:55]
	s_mov_b32 m0, s73
	ds_read_b128 v[194:197], v161 offset:20480
	global_load_lds_dwordx4 v142, s[54:55]
	s_waitcnt vmcnt(8)
	s_waitcnt lgkmcnt(0)
	s_barrier


; #define PG8_MMA(ai, bj, At, Bt) do { __builtin_amdgcn_s_setprio(1); _Pragma("unroll") for (int m = 0; m < 4; ++m) _Pragma("unroll") for (int n = 0; n < 2; ++n) _Pragma("unroll") for (int k = 0; k < 2; ++k) \
;         acc[ai][bj][m][n] = __builtin_amdgcn_mfma_f32_16x16x32_bf16(Bt[n][k], At[m][k], acc[ai][bj][m][n], 0, 0, 0); __builtin_amdgcn_s_setprio(0); } while (0)
; #define PG8_WAIT_V(n) asm volatile("s_waitcnt vmcnt(" #n ")" ::: "memory")
; #define PG8_WAIT_L(n) asm volatile("s_waitcnt lgkmcnt(" #n ")" ::: "memory")
; #define PG8_BAR __builtin_amdgcn_s_barrier()
; #define PG8_SCHED __builtin_amdgcn_sched_barrier(0)
; template <class Epi, bool ALIGN_EPI>
; __device__ __forceinline__ void gemm_phase(LAS unsigned char* lds, const Gemm g, const StaticOrder& S, const Epi& E, const int tid) {
;     ...
;             PG8_WAIT_V(8); PG8_WAIT_L(0); PG8_BAR; PG8_MMA(1, 0, At, B0); PG8_MMA(1, 1, At, B1); PG8_BAR; PG8_SCHED;
	v_mfma_f32_16x16x32_bf16 v[24:27], v[132:135], v[178:181], v[24:27]
	v_mfma_f32_16x16x32_bf16 v[16:19], v[132:135], v[186:189], v[16:19]
	v_mfma_f32_16x16x32_bf16 v[84:87], v[152:155], v[186:189], v[84:87]
	v_mfma_f32_16x16x32_bf16 v[92:95], v[152:155], v[178:181], v[92:95]
	v_mfma_f32_16x16x32_bf16 v[8:11], v[132:135], v[194:197], v[8:11]
	v_mfma_f32_16x16x32_bf16 v[2:5], v[132:135], v[214:217], v[4:7]
	v_mfma_f32_16x16x32_bf16 v[64:67], v[152:155], v[214:217], v[64:67]
	v_mfma_f32_16x16x32_bf16 v[76:79], v[152:155], v[194:197], v[76:79]
	v_mfma_f32_16x16x32_bf16 v[24:27], v[136:139], v[182:185], v[24:27]
	v_mfma_f32_16x16x32_bf16 v[16:19], v[136:139], v[190:193], v[16:19]
	v_mfma_f32_16x16x32_bf16 v[84:87], v[156:159], v[190:193], v[84:87]
	v_mfma_f32_16x16x32_bf16 v[92:95], v[156:159], v[182:185], v[92:95]
	v_mfma_f32_16x16x32_bf16 v[8:11], v[136:139], v[198:201], v[8:11]
	v_mfma_f32_16x16x32_bf16 v[2:5], v[136:139], v[218:221], v[2:5]
	v_mfma_f32_16x16x32_bf16 v[64:67], v[156:159], v[218:221], v[64:67]
	v_mfma_f32_16x16x32_bf16 v[76:79], v[156:159], v[198:201], v[76:79]


; #define PG8_MMA(ai, bj, At, Bt) do { __builtin_amdgcn_s_setprio(1); _Pragma("unroll") for (int m = 0; m < 4; ++m) _Pragma("unroll") for (int n = 0; n < 2; ++n) _Pragma("unroll") for (int k = 0; k < 2; ++k) \
;         acc[ai][bj][m][n] = __builtin_amdgcn_mfma_f32_16x16x32_bf16(Bt[n][k], At[m][k], acc[ai][bj][m][n], 0, 0, 0); __builtin_amdgcn_s_setprio(0); } while (0)
; #define PG8_WAIT_V(n) asm volatile("s_waitcnt vmcnt(" #n ")" ::: "memory")
; #define PG8_WAIT_L(n) asm volatile("s_waitcnt lgkmcnt(" #n ")" ::: "memory")
; #define PG8_BAR __builtin_amdgcn_s_barrier()
; #define PG8_SCHED __builtin_amdgcn_sched_barrier(0)
; template <class Epi, bool ALIGN_EPI>
; __device__ __forceinline__ void gemm_phase(LAS unsigned char* lds, const Gemm g, const StaticOrder& S, const Epi& E, const int tid) {
;     ...
;             PG8_WAIT_V(8); PG8_WAIT_L(0); PG8_BAR; PG8_MMA(1, 0, At, B0); PG8_MMA(1, 1, At, B1); PG8_BAR; PG8_SCHED;
	v_mfma_f32_16x16x32_bf16 v[32:35], v[162:165], v[178:181], v[32:35]
	v_mfma_f32_16x16x32_bf16 v[28:31], v[162:165], v[186:189], v[28:31]
	v_mfma_f32_16x16x32_bf16 v[96:99], v[170:173], v[186:189], v[96:99]
	v_mfma_f32_16x16x32_bf16 v[72:75], v[170:173], v[178:181], v[72:75]
	v_mfma_f32_16x16x32_bf16 v[20:23], v[162:165], v[194:197], v[20:23]
	v_mfma_f32_16x16x32_bf16 v[12:15], v[162:165], v[214:217], v[12:15]
	v_mfma_f32_16x16x32_bf16 v[44:47], v[170:173], v[214:217], v[44:47]
	v_mfma_f32_16x16x32_bf16 v[56:59], v[170:173], v[194:197], v[56:59]
	v_mfma_f32_16x16x32_bf16 v[32:35], v[166:169], v[182:185], v[32:35]
	v_mfma_f32_16x16x32_bf16 v[28:31], v[166:169], v[190:193], v[28:31]
	v_mfma_f32_16x16x32_bf16 v[96:99], v[174:177], v[190:193], v[96:99]
	v_mfma_f32_16x16x32_bf16 v[72:75], v[174:177], v[182:185], v[72:75]
	v_mfma_f32_16x16x32_bf16 v[20:23], v[166:169], v[198:201], v[20:23]
	v_mfma_f32_16x16x32_bf16 v[12:15], v[166:169], v[218:221], v[12:15]
	v_mfma_f32_16x16x32_bf16 v[44:47], v[174:177], v[218:221], v[44:47]
	v_mfma_f32_16x16x32_bf16 v[56:59], v[174:177], v[198:201], v[56:59]

; #define PG8_STAGE(bufoff, gbase, voff) do { _Pragma("unroll") for (int _i = 0; _i < 2; ++_i) \
;         __builtin_amdgcn_global_load_lds((const unsigned*)((const char*)(gbase) + (voff)[_i]), (LAS unsigned*)(lds + (bufoff) + ldsw + _i * 8192), 16, 0, 0); } while (0)
; #define PG8_LDA(dst, b, h) do { _Pragma("unroll") for (int m = 0; m < 4; ++m) _Pragma("unroll") for (int k = 0; k < 2; ++k) dst[m][k] = *(const LAS bf16x8*)(lds + PG8_SA(b, h) + aoff + m * 2048 + k * 1024); } while (0)
; #define PG8_LDB(dst, b, h) do { _Pragma("unroll") for (int n = 0; n < 2; ++n) _Pragma("unroll") for (int k = 0; k < 2; ++k) dst[n][k] = *(const LAS bf16x8*)(lds + PG8_SB(b, h) + boff + n * 2048 + k * 1024); } while (0)
; #define PG8_MMA(ai, bj, At, Bt) do { __builtin_amdgcn_s_setprio(1); _Pragma("unroll") for (int m = 0; m < 4; ++m) _Pragma("unroll") for (int n = 0; n < 2; ++n) _Pragma("unroll") for (int k = 0; k < 2; ++k) \
;         acc[ai][bj][m][n] = __builtin_amdgcn_mfma_f32_16x16x32_bf16(Bt[n][k], At[m][k], acc[ai][bj][m][n], 0, 0, 0); __builtin_amdgcn_s_setprio(0); } while (0)
; #define PG8_WAIT_V(n) asm volatile("s_waitcnt vmcnt(" #n ")" ::: "memory")
; #define PG8_WAIT_L(n) asm volatile("s_waitcnt lgkmcnt(" #n ")" ::: "memory")
; #define PG8_BAR __builtin_amdgcn_s_barrier()
; #define PG8_SCHED __builtin_amdgcn_sched_barrier(0)
; template <class Epi, bool ALIGN_EPI>
; __device__ __forceinline__ void gemm_phase(LAS unsigned char* lds, const Gemm g, const StaticOrder& S, const Epi& E, const int tid) {
;     ...
;             PG8_WAIT_V(8); PG8_WAIT_L(0); PG8_BAR; PG8_MMA(1, 0, At, B0); PG8_MMA(1, 1, At, B1); PG8_BAR; PG8_SCHED;
;             PG8_LDB(B0, 1, 0); PG8_LDB(B1, 1, 1); PG8_SCHED; PG8_LDA(At, 1, 0); PG8_STAGE(PG8_SA(0, 1), a2 + hstepA, voffA);
	s_barrier
	s_add_i32 s90, 0, 0x18000
	v_add_u32_e32 v0, s90, v160
	s_add_i32 s91, 0, 0x1c000
	ds_read_b128 v[132:135], v0
	ds_read_b128 v[136:139], v0 offset:1024
	ds_read_b128 v[152:155], v0 offset:2048
	ds_read_b128 v[156:159], v0 offset:3072
	v_add_u32_e32 v0, s91, v160
	ds_read_b128 v[162:165], v0
	ds_read_b128 v[166:169], v0 offset:1024
	ds_read_b128 v[170:173], v0 offset:2048
	ds_read_b128 v[174:177], v0 offset:3072
	s_add_u32 s54, s54, 0x4000
	s_addc_u32 s55, s55, 0
	s_mov_b32 m0, s74
	ds_read_b128 v[178:181], v161 offset:32768
	ds_read_b128 v[182:185], v161 offset:33792
	ds_read_b128 v[186:189], v161 offset:34816
	ds_read_b128 v[190:193], v161 offset:35840
	ds_read_b128 v[194:197], v161 offset:36864
	ds_read_b128 v[198:201], v161 offset:37888
	ds_read_b128 v[214:217], v161 offset:38912

; #define PG8_STAGE(bufoff, gbase, voff) do { _Pragma("unroll") for (int _i = 0; _i < 2; ++_i) \
;         __builtin_amdgcn_global_load_lds((const unsigned*)((const char*)(gbase) + (voff)[_i]), (LAS unsigned*)(lds + (bufoff) + ldsw + _i * 8192), 16, 0, 0); } while (0)
; #define PG8_LDA(dst, b, h) do { _Pragma("unroll") for (int m = 0; m < 4; ++m) _Pragma("unroll") for (int k = 0; k < 2; ++k) dst[m][k] = *(const LAS bf16x8*)(lds + PG8_SA(b, h) + aoff + m * 2048 + k * 1024); } while (0)
; #define PG8_LDB(dst, b, h) do { _Pragma("unroll") for (int n = 0; n < 2; ++n) _Pragma("unroll") for (int k = 0; k < 2; ++k) dst[n][k] = *(const LAS bf16x8*)(lds + PG8_SB(b, h) + boff + n * 2048 + k * 1024); } while (0)
; #define PG8_MMA(ai, bj, At, Bt) do { __builtin_amdgcn_s_setprio(1); _Pragma("unroll") for (int m = 0; m < 4; ++m) _Pragma("unroll") for (int n = 0; n < 2; ++n) _Pragma("unroll") for (int k = 0; k < 2; ++k) \
;         acc[ai][bj][m][n] = __builtin_amdgcn_mfma_f32_16x16x32_bf16(Bt[n][k], At[m][k], acc[ai][bj][m][n], 0, 0, 0); __builtin_amdgcn_s_setprio(0); } while (0)
; #define PG8_WAIT_V(n) asm volatile("s_waitcnt vmcnt(" #n ")" ::: "memory")
; #define PG8_WAIT_L(n) asm volatile("s_waitcnt lgkmcnt(" #n ")" ::: "memory")
; #define PG8_BAR __builtin_amdgcn_s_barrier()
; #define PG8_SCHED __builtin_amdgcn_sched_barrier(0)
; template <class Epi, bool ALIGN_EPI>
; __device__ __forceinline__ void gemm_phase(LAS unsigned char* lds, const Gemm g, const StaticOrder& S, const Epi& E, const int tid) {
;     ...
;             PG8_LDB(B0, 1, 0); PG8_LDB(B1, 1, 1); PG8_SCHED; PG8_LDA(At, 1, 0); PG8_STAGE(PG8_SA(0, 1), a2 + hstepA, voffA);
;             PG8_WAIT_V(8); PG8_WAIT_L(0); PG8_BAR; PG8_MMA(0, 0, At, B0); PG8_MMA(0, 1, At, B1); PG8_BAR; PG8_SCHED;
	global_load_lds_dwordx4 v146, s[54:55]
	s_mov_b32 m0, s75
	ds_read_b128 v[218:221], v161 offset:39936
	global_load_lds_dwordx4 v142, s[54:55]
	s_waitcnt vmcnt(8)
	s_waitcnt lgkmcnt(0)
	s_barrier


; #define PG8_MMA(ai, bj, At, Bt) do { __builtin_amdgcn_s_setprio(1); _Pragma("unroll") for (int m = 0; m < 4; ++m) _Pragma("unroll") for (int n = 0; n < 2; ++n) _Pragma("unroll") for (int k = 0; k < 2; ++k) \
;         acc[ai][bj][m][n] = __builtin_amdgcn_mfma_f32_16x16x32_bf16(Bt[n][k], At[m][k], acc[ai][bj][m][n], 0, 0, 0); __builtin_amdgcn_s_setprio(0); } while (0)
; #define PG8_WAIT_V(n) asm volatile("s_waitcnt vmcnt(" #n ")" ::: "memory")
; #define PG8_WAIT_L(n) asm volatile("s_waitcnt lgkmcnt(" #n ")" ::: "memory")
; #define PG8_BAR __builtin_amdgcn_s_barrier()
; #define PG8_SCHED __builtin_amdgcn_sched_barrier(0)
; template <class Epi, bool ALIGN_EPI>
; __device__ __forceinline__ void gemm_phase(LAS unsigned char* lds, const Gemm g, const StaticOrder& S, const Epi& E, const int tid) {
;     ...
;             PG8_WAIT_V(8); PG8_WAIT_L(0); PG8_BAR; PG8_MMA(0, 0, At, B0); PG8_MMA(0, 1, At, B1); PG8_BAR; PG8_SCHED;
	v_mfma_f32_16x16x32_bf16 v[88:91], v[132:135], v[178:181], v[88:91]
	v_mfma_f32_16x16x32_bf16 v[52:55], v[132:135], v[186:189], v[52:55]
	v_mfma_f32_16x16x32_bf16 v[120:123], v[152:155], v[186:189], v[120:123]
	v_mfma_f32_16x16x32_bf16 v[124:127], v[152:155], v[178:181], v[124:127]
	v_mfma_f32_16x16x32_bf16 v[40:43], v[132:135], v[194:197], v[40:43]
	v_mfma_f32_16x16x32_bf16 v[36:39], v[132:135], v[214:217], v[36:39]
	v_mfma_f32_16x16x32_bf16 v[112:115], v[152:155], v[214:217], v[112:115]
	v_mfma_f32_16x16x32_bf16 v[116:119], v[152:155], v[194:197], v[116:119]
	v_mfma_f32_16x16x32_bf16 v[88:91], v[136:139], v[182:185], v[88:91]
	v_mfma_f32_16x16x32_bf16 v[52:55], v[136:139], v[190:193], v[52:55]
	v_mfma_f32_16x16x32_bf16 v[120:123], v[156:159], v[190:193], v[120:123]
	v_mfma_f32_16x16x32_bf16 v[124:127], v[156:159], v[182:185], v[124:127]
	v_mfma_f32_16x16x32_bf16 v[40:43], v[136:139], v[198:201], v[40:43]
	v_mfma_f32_16x16x32_bf16 v[36:39], v[136:139], v[218:221], v[36:39]
	v_mfma_f32_16x16x32_bf16 v[112:115], v[156:159], v[218:221], v[112:115]
	v_mfma_f32_16x16x32_bf16 v[116:119], v[156:159], v[198:201], v[116:119]


; #define PG8_MMA(ai, bj, At, Bt) do { __builtin_amdgcn_s_setprio(1); _Pragma("unroll") for (int m = 0; m < 4; ++m) _Pragma("unroll") for (int n = 0; n < 2; ++n) _Pragma("unroll") for (int k = 0; k < 2; ++k) \
;         acc[ai][bj][m][n] = __builtin_amdgcn_mfma_f32_16x16x32_bf16(Bt[n][k], At[m][k], acc[ai][bj][m][n], 0, 0, 0); __builtin_amdgcn_s_setprio(0); } while (0)
; #define PG8_WAIT_V(n) asm volatile("s_waitcnt vmcnt(" #n ")" ::: "memory")
; #define PG8_WAIT_L(n) asm volatile("s_waitcnt lgkmcnt(" #n ")" ::: "memory")
; #define PG8_BAR __builtin_amdgcn_s_barrier()
; #define PG8_SCHED __builtin_amdgcn_sched_barrier(0)
; template <class Epi, bool ALIGN_EPI>
; __device__ __forceinline__ void gemm_phase(LAS unsigned char* lds, const Gemm g, const StaticOrder& S, const Epi& E, const int tid) {
;     ...
;             PG8_WAIT_V(8); PG8_WAIT_L(0); PG8_BAR; PG8_MMA(0, 0, At, B0); PG8_MMA(0, 1, At, B1); PG8_BAR; PG8_SCHED;
	v_mfma_f32_16x16x32_bf16 v[80:83], v[162:165], v[178:181], v[80:83]
	v_mfma_f32_16x16x32_bf16 v[68:71], v[162:165], v[186:189], v[68:71]
	v_mfma_f32_16x16x32_bf16 v[108:111], v[170:173], v[186:189], v[108:111]
	v_mfma_f32_16x16x32_bf16 v[128:131], v[170:173], v[178:181], v[128:131]
	v_mfma_f32_16x16x32_bf16 v[60:63], v[162:165], v[194:197], v[60:63]
	v_mfma_f32_16x16x32_bf16 v[48:51], v[162:165], v[214:217], v[48:51]
	v_mfma_f32_16x16x32_bf16 v[100:103], v[170:173], v[214:217], v[100:103]
	v_mfma_f32_16x16x32_bf16 v[104:107], v[170:173], v[194:197], v[104:107]
	v_mfma_f32_16x16x32_bf16 v[80:83], v[166:169], v[182:185], v[80:83]
	v_mfma_f32_16x16x32_bf16 v[68:71], v[166:169], v[190:193], v[68:71]
	v_mfma_f32_16x16x32_bf16 v[108:111], v[174:177], v[190:193], v[108:111]
	v_mfma_f32_16x16x32_bf16 v[128:131], v[174:177], v[182:185], v[128:131]
	v_mfma_f32_16x16x32_bf16 v[60:63], v[166:169], v[198:201], v[60:63]
	v_mfma_f32_16x16x32_bf16 v[48:51], v[166:169], v[218:221], v[48:51]
	v_mfma_f32_16x16x32_bf16 v[100:103], v[174:177], v[218:221], v[100:103]
	v_mfma_f32_16x16x32_bf16 v[104:107], v[174:177], v[198:201], v[104:107]

; #define PG8_STAGE(bufoff, gbase, voff) do { _Pragma("unroll") for (int _i = 0; _i < 2; ++_i) \
;         __builtin_amdgcn_global_load_lds((const unsigned*)((const char*)(gbase) + (voff)[_i]), (LAS unsigned*)(lds + (bufoff) + ldsw + _i * 8192), 16, 0, 0); } while (0)
; #define PG8_LDA(dst, b, h) do { _Pragma("unroll") for (int m = 0; m < 4; ++m) _Pragma("unroll") for (int k = 0; k < 2; ++k) dst[m][k] = *(const LAS bf16x8*)(lds + PG8_SA(b, h) + aoff + m * 2048 + k * 1024); } while (0)
; #define PG8_MMA(ai, bj, At, Bt) do { __builtin_amdgcn_s_setprio(1); _Pragma("unroll") for (int m = 0; m < 4; ++m) _Pragma("unroll") for (int n = 0; n < 2; ++n) _Pragma("unroll") for (int k = 0; k < 2; ++k) \
;         acc[ai][bj][m][n] = __builtin_amdgcn_mfma_f32_16x16x32_bf16(Bt[n][k], At[m][k], acc[ai][bj][m][n], 0, 0, 0); __builtin_amdgcn_s_setprio(0); } while (0)
; #define PG8_WAIT_V(n) asm volatile("s_waitcnt vmcnt(" #n ")" ::: "memory")
; #define PG8_WAIT_L(n) asm volatile("s_waitcnt lgkmcnt(" #n ")" ::: "memory")
; #define PG8_BAR __builtin_amdgcn_s_barrier()
; #define PG8_SCHED __builtin_amdgcn_sched_barrier(0)
; template <class Epi, bool ALIGN_EPI>
; __device__ __forceinline__ void gemm_phase(LAS unsigned char* lds, const Gemm g, const StaticOrder& S, const Epi& E, const int tid) {
;     ...
;             PG8_WAIT_V(8); PG8_WAIT_L(0); PG8_BAR; PG8_MMA(0, 0, At, B0); PG8_MMA(0, 1, At, B1); PG8_BAR; PG8_SCHED;
;             PG8_LDA(At, 1, 1); PG8_STAGE(PG8_SB(1, 0), b3, voffB); PG8_STAGE(PG8_SB(1, 1), b3 + hstepB, voffB); PG8_STAGE(PG8_SA(1, 0), a3, voffA);
	s_barrier
	s_add_u32 s54, s52, 0x8000
	s_addc_u32 s55, s53, 0
	s_add_i32 s90, s90, s71
	s_mov_b32 m0, s90
	ds_read_b128 v[178:181], v161 offset:49152
	ds_read_b128 v[182:185], v161 offset:50176
	ds_read_b128 v[186:189], v161 offset:51200
	ds_read_b128 v[190:193], v161 offset:52224


; #define PG8_STAGE(bufoff, gbase, voff) do { _Pragma("unroll") for (int _i = 0; _i < 2; ++_i) \
;         __builtin_amdgcn_global_load_lds((const unsigned*)((const char*)(gbase) + (voff)[_i]), (LAS unsigned*)(lds + (bufoff) + ldsw + _i * 8192), 16, 0, 0); } while (0)
; #define PG8_LDA(dst, b, h) do { _Pragma("unroll") for (int m = 0; m < 4; ++m) _Pragma("unroll") for (int k = 0; k < 2; ++k) dst[m][k] = *(const LAS bf16x8*)(lds + PG8_SA(b, h) + aoff + m * 2048 + k * 1024); } while (0)
; #define PG8_MMA(ai, bj, At, Bt) do { __builtin_amdgcn_s_setprio(1); _Pragma("unroll") for (int m = 0; m < 4; ++m) _Pragma("unroll") for (int n = 0; n < 2; ++n) _Pragma("unroll") for (int k = 0; k < 2; ++k) \
;         acc[ai][bj][m][n] = __builtin_amdgcn_mfma_f32_16x16x32_bf16(Bt[n][k], At[m][k], acc[ai][bj][m][n], 0, 0, 0); __builtin_amdgcn_s_setprio(0); } while (0)
; #define PG8_WAIT_V(n) asm volatile("s_waitcnt vmcnt(" #n ")" ::: "memory")
; #define PG8_WAIT_L(n) asm volatile("s_waitcnt lgkmcnt(" #n ")" ::: "memory")
; #define PG8_BAR __builtin_amdgcn_s_barrier()
; #define PG8_SCHED __builtin_amdgcn_sched_barrier(0)
; template <class Epi, bool ALIGN_EPI>
; __device__ __forceinline__ void gemm_phase(LAS unsigned char* lds, const Gemm g, const StaticOrder& S, const Epi& E, const int tid) {
;     ...
;             PG8_LDA(At, 1, 1); PG8_STAGE(PG8_SB(1, 0), b3, voffB); PG8_STAGE(PG8_SB(1, 1), b3 + hstepB, voffB); PG8_STAGE(PG8_SA(1, 0), a3, voffA);
;             PG8_WAIT_V(8); PG8_WAIT_L(0); PG8_BAR; PG8_MMA(1, 0, At, B0); PG8_MMA(1, 1, At, B1); PG8_BAR; PG8_SCHED;
	global_load_lds_dwordx4 v144, s[54:55]
	s_add_i32 m0, s90, 0x2000
	s_add_u32 s52, s52, 0xc000
	s_addc_u32 s53, s53, 0
	global_load_lds_dwordx4 v140, s[54:55]
	s_add_i32 s54, s91, s71
	s_mov_b32 m0, s54
	ds_read_b128 v[218:221], v161 offset:56320
	global_load_lds_dwordx4 v144, s[52:53]
	s_add_i32 m0, s54, 0x2000
	ds_read_b128 v[214:217], v161 offset:55296
	global_load_lds_dwordx4 v140, s[52:53]
	s_mov_b32 m0, s79
	ds_read_b128 v[198:201], v161 offset:54272
	global_load_lds_dwordx4 v146, s[50:51]
	s_mov_b32 m0, s80
	ds_read_b128 v[194:197], v161 offset:53248
	global_load_lds_dwordx4 v142, s[50:51]
	s_waitcnt vmcnt(8)
	s_waitcnt lgkmcnt(0)
	s_barrier


; #define PG8_MMA(ai, bj, At, Bt) do { __builtin_amdgcn_s_setprio(1); _Pragma("unroll") for (int m = 0; m < 4; ++m) _Pragma("unroll") for (int n = 0; n < 2; ++n) _Pragma("unroll") for (int k = 0; k < 2; ++k) \
;         acc[ai][bj][m][n] = __builtin_amdgcn_mfma_f32_16x16x32_bf16(Bt[n][k], At[m][k], acc[ai][bj][m][n], 0, 0, 0); __builtin_amdgcn_s_setprio(0); } while (0)
; #define PG8_WAIT_V(n) asm volatile("s_waitcnt vmcnt(" #n ")" ::: "memory")
; #define PG8_WAIT_L(n) asm volatile("s_waitcnt lgkmcnt(" #n ")" ::: "memory")
; #define PG8_BAR __builtin_amdgcn_s_barrier()
; #define PG8_SCHED __builtin_amdgcn_sched_barrier(0)
; template <class Epi, bool ALIGN_EPI>
; __device__ __forceinline__ void gemm_phase(LAS unsigned char* lds, const Gemm g, const StaticOrder& S, const Epi& E, const int tid) {
;     ...
;             PG8_WAIT_V(8); PG8_WAIT_L(0); PG8_BAR; PG8_MMA(1, 0, At, B0); PG8_MMA(1, 1, At, B1); PG8_BAR; PG8_SCHED;
	v_mfma_f32_16x16x32_bf16 v[24:27], v[132:135], v[178:181], v[24:27]
	v_mfma_f32_16x16x32_bf16 v[16:19], v[132:135], v[186:189], v[16:19]
	v_mfma_f32_16x16x32_bf16 v[84:87], v[152:155], v[186:189], v[84:87]
	v_mfma_f32_16x16x32_bf16 v[92:95], v[152:155], v[178:181], v[92:95]
	v_mfma_f32_16x16x32_bf16 v[6:9], v[132:135], v[194:197], v[8:11]
	v_mfma_f32_16x16x32_bf16 v[2:5], v[132:135], v[214:217], v[2:5]
	v_mfma_f32_16x16x32_bf16 v[64:67], v[152:155], v[214:217], v[64:67]
	v_mfma_f32_16x16x32_bf16 v[76:79], v[152:155], v[194:197], v[76:79]
	v_mfma_f32_16x16x32_bf16 v[24:27], v[136:139], v[182:185], v[24:27]
	v_mfma_f32_16x16x32_bf16 v[16:19], v[136:139], v[190:193], v[16:19]
	v_mfma_f32_16x16x32_bf16 v[84:87], v[156:159], v[190:193], v[84:87]
	v_mfma_f32_16x16x32_bf16 v[92:95], v[156:159], v[182:185], v[92:95]
	v_mfma_f32_16x16x32_bf16 v[8:11], v[136:139], v[198:201], v[6:9]
	v_mfma_f32_16x16x32_bf16 v[4:7], v[136:139], v[218:221], v[2:5]
	v_mfma_f32_16x16x32_bf16 v[64:67], v[156:159], v[218:221], v[64:67]
	v_mfma_f32_16x16x32_bf16 v[76:79], v[156:159], v[198:201], v[76:79]


; #define PG8_MMA(ai, bj, At, Bt) do { __builtin_amdgcn_s_setprio(1); _Pragma("unroll") for (int m = 0; m < 4; ++m) _Pragma("unroll") for (int n = 0; n < 2; ++n) _Pragma("unroll") for (int k = 0; k < 2; ++k) \
;         acc[ai][bj][m][n] = __builtin_amdgcn_mfma_f32_16x16x32_bf16(Bt[n][k], At[m][k], acc[ai][bj][m][n], 0, 0, 0); __builtin_amdgcn_s_setprio(0); } while (0)
; #define PG8_WAIT_V(n) asm volatile("s_waitcnt vmcnt(" #n ")" ::: "memory")
; #define PG8_WAIT_L(n) asm volatile("s_waitcnt lgkmcnt(" #n ")" ::: "memory")
; #define PG8_BAR __builtin_amdgcn_s_barrier()
; #define PG8_SCHED __builtin_amdgcn_sched_barrier(0)
; template <class Epi, bool ALIGN_EPI>
; __device__ __forceinline__ void gemm_phase(LAS unsigned char* lds, const Gemm g, const StaticOrder& S, const Epi& E, const int tid) {
;     ...
;             PG8_WAIT_V(8); PG8_WAIT_L(0); PG8_BAR; PG8_MMA(1, 0, At, B0); PG8_MMA(1, 1, At, B1); PG8_BAR; PG8_SCHED;
	v_mfma_f32_16x16x32_bf16 v[32:35], v[162:165], v[178:181], v[32:35]
	v_mfma_f32_16x16x32_bf16 v[28:31], v[162:165], v[186:189], v[28:31]
	v_mfma_f32_16x16x32_bf16 v[96:99], v[170:173], v[186:189], v[96:99]
	v_mfma_f32_16x16x32_bf16 v[72:75], v[170:173], v[178:181], v[72:75]
	v_mfma_f32_16x16x32_bf16 v[20:23], v[162:165], v[194:197], v[20:23]
	v_mfma_f32_16x16x32_bf16 v[12:15], v[162:165], v[214:217], v[12:15]
	v_mfma_f32_16x16x32_bf16 v[44:47], v[170:173], v[214:217], v[44:47]
	v_mfma_f32_16x16x32_bf16 v[56:59], v[170:173], v[194:197], v[56:59]
	v_mfma_f32_16x16x32_bf16 v[32:35], v[166:169], v[182:185], v[32:35]
	v_mfma_f32_16x16x32_bf16 v[28:31], v[166:169], v[190:193], v[28:31]
	v_mfma_f32_16x16x32_bf16 v[96:99], v[174:177], v[190:193], v[96:99]
	v_mfma_f32_16x16x32_bf16 v[72:75], v[174:177], v[182:185], v[72:75]
	v_mfma_f32_16x16x32_bf16 v[20:23], v[166:169], v[198:201], v[20:23]
	v_mfma_f32_16x16x32_bf16 v[12:15], v[166:169], v[218:221], v[12:15]
	v_mfma_f32_16x16x32_bf16 v[44:47], v[174:177], v[218:221], v[44:47]
	v_mfma_f32_16x16x32_bf16 v[56:59], v[174:177], v[198:201], v[56:59]

; #define PG8_MMA(ai, bj, At, Bt) do { __builtin_amdgcn_s_setprio(1); _Pragma("unroll") for (int m = 0; m < 4; ++m) _Pragma("unroll") for (int n = 0; n < 2; ++n) _Pragma("unroll") for (int k = 0; k < 2; ++k) \
;         acc[ai][bj][m][n] = __builtin_amdgcn_mfma_f32_16x16x32_bf16(Bt[n][k], At[m][k], acc[ai][bj][m][n], 0, 0, 0); __builtin_amdgcn_s_setprio(0); } while (0)
; #define PG8_WAIT_V(n) asm volatile("s_waitcnt vmcnt(" #n ")" ::: "memory")
; #define PG8_WAIT_L(n) asm volatile("s_waitcnt lgkmcnt(" #n ")" ::: "memory")
; #define PG8_BAR __builtin_amdgcn_s_barrier()
; #define PG8_SCHED __builtin_amdgcn_sched_barrier(0)
; template <class Epi, bool ALIGN_EPI>
; __device__ __forceinline__ void gemm_phase(LAS unsigned char* lds, const Gemm g, const StaticOrder& S, const Epi& E, const int tid) {
;     ...
;             PG8_WAIT_V(8); PG8_WAIT_L(0); PG8_BAR; PG8_MMA(1, 0, At, B0); PG8_MMA(1, 1, At, B1); PG8_BAR; PG8_SCHED;
;         }
;         if constexpr (ALIGN_EPI) { if (wr == 0) PG8_BAR; }
	s_barrier
	s_add_i32 s89, s89, 2
	s_add_u32 s48, s48, 0x10000
	s_addc_u32 s49, s49, 0
	s_add_u32 vcc_hi, vcc_hi, 0x10000
	s_addc_u32 s88, s88, 0
	s_cmp_gt_u32 s89, 29
	s_cbranch_scc0 .LBB0_211
	s_and_b64 vcc, exec, s[22:23]
	s_cbranch_vccz .LBB0_214
	s_barrier

; #define PG8_STAGE(bufoff, gbase, voff) do { _Pragma("unroll") for (int _i = 0; _i < 2; ++_i) \
;         __builtin_amdgcn_global_load_lds((const unsigned*)((const char*)(gbase) + (voff)[_i]), (LAS unsigned*)(lds + (bufoff) + ldsw + _i * 8192), 16, 0, 0); } while (0)
; #define PG8_LDA(dst, b, h) do { _Pragma("unroll") for (int m = 0; m < 4; ++m) _Pragma("unroll") for (int k = 0; k < 2; ++k) dst[m][k] = *(const LAS bf16x8*)(lds + PG8_SA(b, h) + aoff + m * 2048 + k * 1024); } while (0)
; #define PG8_LDB(dst, b, h) do { _Pragma("unroll") for (int n = 0; n < 2; ++n) _Pragma("unroll") for (int k = 0; k < 2; ++k) dst[n][k] = *(const LAS bf16x8*)(lds + PG8_SB(b, h) + boff + n * 2048 + k * 1024); } while (0)
; #define PG8_SCHED __builtin_amdgcn_sched_barrier(0)
; template <class Epi, bool ALIGN_EPI>
; __device__ __forceinline__ void gemm_phase(LAS unsigned char* lds, const Gemm g, const StaticOrder& S, const Epi& E, const int tid) {
;     ...
;             const bool last = (t == nt - 2);
;             const char* a1 = cA + (size_t)(t + 1) * kstepA;
;             const char* a2 = last ? nA : cA + (size_t)(t + 2) * kstepA; const char* b2 = last ? nB : cB + (size_t)(t + 2) * kstepB;
;             const char* a3 = a2 + kstepA; const char* b3 = b2 + kstepB;
;             PG8_LDB(B0, 0, 0); PG8_LDB(B1, 0, 1); PG8_SCHED; PG8_LDA(At, 0, 0); PG8_STAGE(PG8_SA(1, 1), a1 + hstepA, voffA);
.LBB0_294:
	s_add_u32 s22, s10, 0x4000
	s_addc_u32 s23, s11, 0
	s_cmpk_eq_i32 s86, 0x54
	s_cselect_b32 s42, s48, s22
	s_cselect_b32 s43, s49, s23
	s_cselect_b32 s34, s50, s84
	s_cselect_b32 s35, s51, s85
	s_add_u32 s22, s42, 0x8000
	s_addc_u32 s23, s43, 0
	s_add_i32 s87, 0, 0x10000
	v_add_u32_e32 v0, s87, v154
	s_add_i32 s90, 0, 0x14000
	s_waitcnt lgkmcnt(0)
	ds_read_b128 v[132:135], v0
	ds_read_b128 v[148:151], v0 offset:1024
	ds_read_b128 v[156:159], v0 offset:2048
	ds_read_b128 v[160:163], v0 offset:3072
	v_add_u32_e32 v0, s90, v154
	ds_read_b128 v[164:167], v0
	ds_read_b128 v[168:171], v0 offset:1024
	ds_read_b128 v[172:175], v0 offset:2048
	ds_read_b128 v[176:179], v0 offset:3072
	s_add_i32 m0, s57, 0xc000
	ds_read_b128 v[180:183], v155
	ds_read_b128 v[184:187], v155 offset:1024
	ds_read_b128 v[188:191], v155 offset:2048
	ds_read_b128 v[192:195], v155 offset:3072
	ds_read_b128 v[196:199], v155 offset:4096
	ds_read_b128 v[214:217], v155 offset:5120
	ds_read_b128 v[218:221], v155 offset:6144

; #define PG8_STAGE(bufoff, gbase, voff) do { _Pragma("unroll") for (int _i = 0; _i < 2; ++_i) \
;         __builtin_amdgcn_global_load_lds((const unsigned*)((const char*)(gbase) + (voff)[_i]), (LAS unsigned*)(lds + (bufoff) + ldsw + _i * 8192), 16, 0, 0); } while (0)
; #define PG8_LDA(dst, b, h) do { _Pragma("unroll") for (int m = 0; m < 4; ++m) _Pragma("unroll") for (int k = 0; k < 2; ++k) dst[m][k] = *(const LAS bf16x8*)(lds + PG8_SA(b, h) + aoff + m * 2048 + k * 1024); } while (0)
; #define PG8_LDB(dst, b, h) do { _Pragma("unroll") for (int n = 0; n < 2; ++n) _Pragma("unroll") for (int k = 0; k < 2; ++k) dst[n][k] = *(const LAS bf16x8*)(lds + PG8_SB(b, h) + boff + n * 2048 + k * 1024); } while (0)
; #define PG8_MMA(ai, bj, At, Bt) do { __builtin_amdgcn_s_setprio(1); _Pragma("unroll") for (int m = 0; m < 4; ++m) _Pragma("unroll") for (int n = 0; n < 2; ++n) _Pragma("unroll") for (int k = 0; k < 2; ++k) \
;         acc[ai][bj][m][n] = __builtin_amdgcn_mfma_f32_16x16x32_bf16(Bt[n][k], At[m][k], acc[ai][bj][m][n], 0, 0, 0); __builtin_amdgcn_s_setprio(0); } while (0)
; #define PG8_WAIT_V(n) asm volatile("s_waitcnt vmcnt(" #n ")" ::: "memory")
; #define PG8_WAIT_L(n) asm volatile("s_waitcnt lgkmcnt(" #n ")" ::: "memory")
; #define PG8_BAR __builtin_amdgcn_s_barrier()
; #define PG8_SCHED __builtin_amdgcn_sched_barrier(0)
; template <class Epi, bool ALIGN_EPI>
; __device__ __forceinline__ void gemm_phase(LAS unsigned char* lds, const Gemm g, const StaticOrder& S, const Epi& E, const int tid) {
;     ...
;             PG8_LDB(B0, 0, 0); PG8_LDB(B1, 0, 1); PG8_SCHED; PG8_LDA(At, 0, 0); PG8_STAGE(PG8_SA(1, 1), a1 + hstepA, voffA);
;             PG8_WAIT_V(8); PG8_WAIT_L(0); PG8_BAR; PG8_MMA(0, 0, At, B0); PG8_MMA(0, 1, At, B1); PG8_BAR; PG8_SCHED;
	global_load_lds_dwordx4 v144, s[10:11]
	s_add_i32 m0, s57, 0xe000
	ds_read_b128 v[222:225], v155 offset:7168
	global_load_lds_dwordx4 v146, s[10:11]
	s_waitcnt vmcnt(8)
	s_waitcnt lgkmcnt(0)
	s_barrier


; #define PG8_MMA(ai, bj, At, Bt) do { __builtin_amdgcn_s_setprio(1); _Pragma("unroll") for (int m = 0; m < 4; ++m) _Pragma("unroll") for (int n = 0; n < 2; ++n) _Pragma("unroll") for (int k = 0; k < 2; ++k) \
;         acc[ai][bj][m][n] = __builtin_amdgcn_mfma_f32_16x16x32_bf16(Bt[n][k], At[m][k], acc[ai][bj][m][n], 0, 0, 0); __builtin_amdgcn_s_setprio(0); } while (0)
; #define PG8_WAIT_V(n) asm volatile("s_waitcnt vmcnt(" #n ")" ::: "memory")
; #define PG8_WAIT_L(n) asm volatile("s_waitcnt lgkmcnt(" #n ")" ::: "memory")
; #define PG8_BAR __builtin_amdgcn_s_barrier()
; #define PG8_SCHED __builtin_amdgcn_sched_barrier(0)
; template <class Epi, bool ALIGN_EPI>
; __device__ __forceinline__ void gemm_phase(LAS unsigned char* lds, const Gemm g, const StaticOrder& S, const Epi& E, const int tid) {
;     ...
;             PG8_WAIT_V(8); PG8_WAIT_L(0); PG8_BAR; PG8_MMA(0, 0, At, B0); PG8_MMA(0, 1, At, B1); PG8_BAR; PG8_SCHED;
	v_mfma_f32_16x16x32_bf16 v[8:11], v[132:135], v[180:183], v[8:11]
	v_mfma_f32_16x16x32_bf16 v[52:55], v[132:135], v[188:191], v[52:55]
	v_mfma_f32_16x16x32_bf16 v[48:51], v[156:159], v[188:191], v[48:51]
	v_mfma_f32_16x16x32_bf16 v[56:59], v[156:159], v[180:183], v[56:59]
	v_mfma_f32_16x16x32_bf16 v[44:47], v[132:135], v[196:199], v[44:47]
	v_mfma_f32_16x16x32_bf16 v[36:39], v[132:135], v[218:221], v[36:39]
	v_mfma_f32_16x16x32_bf16 v[32:35], v[156:159], v[218:221], v[32:35]
	v_mfma_f32_16x16x32_bf16 v[40:43], v[156:159], v[196:199], v[40:43]
	v_mfma_f32_16x16x32_bf16 v[8:11], v[148:151], v[184:187], v[8:11]
	v_mfma_f32_16x16x32_bf16 v[52:55], v[148:151], v[192:195], v[52:55]
	v_mfma_f32_16x16x32_bf16 v[48:51], v[160:163], v[192:195], v[48:51]
	v_mfma_f32_16x16x32_bf16 v[56:59], v[160:163], v[184:187], v[56:59]
	v_mfma_f32_16x16x32_bf16 v[44:47], v[148:151], v[214:217], v[44:47]
	v_mfma_f32_16x16x32_bf16 v[36:39], v[148:151], v[222:225], v[36:39]
	v_mfma_f32_16x16x32_bf16 v[32:35], v[160:163], v[222:225], v[32:35]
	v_mfma_f32_16x16x32_bf16 v[40:43], v[160:163], v[214:217], v[40:43]


; #define PG8_MMA(ai, bj, At, Bt) do { __builtin_amdgcn_s_setprio(1); _Pragma("unroll") for (int m = 0; m < 4; ++m) _Pragma("unroll") for (int n = 0; n < 2; ++n) _Pragma("unroll") for (int k = 0; k < 2; ++k) \
;         acc[ai][bj][m][n] = __builtin_amdgcn_mfma_f32_16x16x32_bf16(Bt[n][k], At[m][k], acc[ai][bj][m][n], 0, 0, 0); __builtin_amdgcn_s_setprio(0); } while (0)
; #define PG8_WAIT_V(n) asm volatile("s_waitcnt vmcnt(" #n ")" ::: "memory")
; #define PG8_WAIT_L(n) asm volatile("s_waitcnt lgkmcnt(" #n ")" ::: "memory")
; #define PG8_BAR __builtin_amdgcn_s_barrier()
; #define PG8_SCHED __builtin_amdgcn_sched_barrier(0)
; template <class Epi, bool ALIGN_EPI>
; __device__ __forceinline__ void gemm_phase(LAS unsigned char* lds, const Gemm g, const StaticOrder& S, const Epi& E, const int tid) {
;     ...
;             PG8_WAIT_V(8); PG8_WAIT_L(0); PG8_BAR; PG8_MMA(0, 0, At, B0); PG8_MMA(0, 1, At, B1); PG8_BAR; PG8_SCHED;
	v_mfma_f32_16x16x32_bf16 v[2:5], v[164:167], v[180:183], v[4:7]
	v_mfma_f32_16x16x32_bf16 v[96:99], v[164:167], v[188:191], v[96:99]
	v_mfma_f32_16x16x32_bf16 v[92:95], v[172:175], v[188:191], v[92:95]
	v_mfma_f32_16x16x32_bf16 v[28:31], v[172:175], v[180:183], v[28:31]
	v_mfma_f32_16x16x32_bf16 v[88:91], v[164:167], v[196:199], v[88:91]
	v_mfma_f32_16x16x32_bf16 v[80:83], v[164:167], v[218:221], v[80:83]
	v_mfma_f32_16x16x32_bf16 v[76:79], v[172:175], v[218:221], v[76:79]
	v_mfma_f32_16x16x32_bf16 v[84:87], v[172:175], v[196:199], v[84:87]
	v_mfma_f32_16x16x32_bf16 v[2:5], v[168:171], v[184:187], v[2:5]
	v_mfma_f32_16x16x32_bf16 v[96:99], v[168:171], v[192:195], v[96:99]
	v_mfma_f32_16x16x32_bf16 v[92:95], v[176:179], v[192:195], v[92:95]
	v_mfma_f32_16x16x32_bf16 v[28:31], v[176:179], v[184:187], v[28:31]
	v_mfma_f32_16x16x32_bf16 v[88:91], v[168:171], v[214:217], v[88:91]
	v_mfma_f32_16x16x32_bf16 v[80:83], v[168:171], v[222:225], v[80:83]
	v_mfma_f32_16x16x32_bf16 v[76:79], v[176:179], v[222:225], v[76:79]
	v_mfma_f32_16x16x32_bf16 v[84:87], v[176:179], v[214:217], v[84:87]

; #define PG8_STAGE(bufoff, gbase, voff) do { _Pragma("unroll") for (int _i = 0; _i < 2; ++_i) \
;         __builtin_amdgcn_global_load_lds((const unsigned*)((const char*)(gbase) + (voff)[_i]), (LAS unsigned*)(lds + (bufoff) + ldsw + _i * 8192), 16, 0, 0); } while (0)
; #define PG8_LDA(dst, b, h) do { _Pragma("unroll") for (int m = 0; m < 4; ++m) _Pragma("unroll") for (int k = 0; k < 2; ++k) dst[m][k] = *(const LAS bf16x8*)(lds + PG8_SA(b, h) + aoff + m * 2048 + k * 1024); } while (0)
; #define PG8_MMA(ai, bj, At, Bt) do { __builtin_amdgcn_s_setprio(1); _Pragma("unroll") for (int m = 0; m < 4; ++m) _Pragma("unroll") for (int n = 0; n < 2; ++n) _Pragma("unroll") for (int k = 0; k < 2; ++k) \
;         acc[ai][bj][m][n] = __builtin_amdgcn_mfma_f32_16x16x32_bf16(Bt[n][k], At[m][k], acc[ai][bj][m][n], 0, 0, 0); __builtin_amdgcn_s_setprio(0); } while (0)
; #define PG8_WAIT_V(n) asm volatile("s_waitcnt vmcnt(" #n ")" ::: "memory")
; #define PG8_WAIT_L(n) asm volatile("s_waitcnt lgkmcnt(" #n ")" ::: "memory")
; #define PG8_BAR __builtin_amdgcn_s_barrier()
; #define PG8_SCHED __builtin_amdgcn_sched_barrier(0)
; template <class Epi, bool ALIGN_EPI>
; __device__ __forceinline__ void gemm_phase(LAS unsigned char* lds, const Gemm g, const StaticOrder& S, const Epi& E, const int tid) {
;     ...
;             PG8_WAIT_V(8); PG8_WAIT_L(0); PG8_BAR; PG8_MMA(0, 0, At, B0); PG8_MMA(0, 1, At, B1); PG8_BAR; PG8_SCHED;
;             PG8_LDA(At, 0, 1); PG8_STAGE(PG8_SB(0, 0), b2, voffB); PG8_STAGE(PG8_SB(0, 1), b2 + hstepB, voffB); PG8_STAGE(PG8_SA(0, 0), a2, voffA);
	s_barrier
	s_add_i32 s87, s87, s56
	s_mov_b32 m0, s87
	ds_read_b128 v[180:183], v155 offset:16384
	ds_read_b128 v[184:187], v155 offset:17408
	ds_read_b128 v[188:191], v155 offset:18432
	ds_read_b128 v[192:195], v155 offset:19456


; #define PG8_STAGE(bufoff, gbase, voff) do { _Pragma("unroll") for (int _i = 0; _i < 2; ++_i) \
;         __builtin_amdgcn_global_load_lds((const unsigned*)((const char*)(gbase) + (voff)[_i]), (LAS unsigned*)(lds + (bufoff) + ldsw + _i * 8192), 16, 0, 0); } while (0)
; #define PG8_LDA(dst, b, h) do { _Pragma("unroll") for (int m = 0; m < 4; ++m) _Pragma("unroll") for (int k = 0; k < 2; ++k) dst[m][k] = *(const LAS bf16x8*)(lds + PG8_SA(b, h) + aoff + m * 2048 + k * 1024); } while (0)
; #define PG8_MMA(ai, bj, At, Bt) do { __builtin_amdgcn_s_setprio(1); _Pragma("unroll") for (int m = 0; m < 4; ++m) _Pragma("unroll") for (int n = 0; n < 2; ++n) _Pragma("unroll") for (int k = 0; k < 2; ++k) \
;         acc[ai][bj][m][n] = __builtin_amdgcn_mfma_f32_16x16x32_bf16(Bt[n][k], At[m][k], acc[ai][bj][m][n], 0, 0, 0); __builtin_amdgcn_s_setprio(0); } while (0)
; #define PG8_WAIT_V(n) asm volatile("s_waitcnt vmcnt(" #n ")" ::: "memory")
; #define PG8_WAIT_L(n) asm volatile("s_waitcnt lgkmcnt(" #n ")" ::: "memory")
; #define PG8_BAR __builtin_amdgcn_s_barrier()
; #define PG8_SCHED __builtin_amdgcn_sched_barrier(0)
; template <class Epi, bool ALIGN_EPI>
; __device__ __forceinline__ void gemm_phase(LAS unsigned char* lds, const Gemm g, const StaticOrder& S, const Epi& E, const int tid) {
;     ...
;             PG8_LDA(At, 0, 1); PG8_STAGE(PG8_SB(0, 0), b2, voffB); PG8_STAGE(PG8_SB(0, 1), b2 + hstepB, voffB); PG8_STAGE(PG8_SA(0, 0), a2, voffA);
;             PG8_WAIT_V(8); PG8_WAIT_L(0); PG8_BAR; PG8_MMA(1, 0, At, B0); PG8_MMA(1, 1, At, B1); PG8_BAR; PG8_SCHED;
	global_load_lds_dwordx4 v140, s[34:35]
	s_add_i32 m0, s87, 0x2000
	s_add_u32 s88, s34, 0x4000
	s_addc_u32 s89, s35, 0
	s_add_i32 s87, s90, s56
	global_load_lds_dwordx4 v136, s[34:35]
	s_mov_b32 m0, s87
	ds_read_b128 v[222:225], v155 offset:23552
	global_load_lds_dwordx4 v140, s[88:89]
	s_add_i32 m0, s87, 0x2000
	ds_read_b128 v[218:221], v155 offset:22528
	global_load_lds_dwordx4 v136, s[88:89]
	s_mov_b32 m0, s57
	ds_read_b128 v[214:217], v155 offset:21504
	global_load_lds_dwordx4 v142, s[42:43]
	s_mov_b32 m0, s60
	ds_read_b128 v[196:199], v155 offset:20480
	global_load_lds_dwordx4 v138, s[42:43]
	s_waitcnt vmcnt(8)
	s_waitcnt lgkmcnt(0)
	s_barrier


; #define PG8_MMA(ai, bj, At, Bt) do { __builtin_amdgcn_s_setprio(1); _Pragma("unroll") for (int m = 0; m < 4; ++m) _Pragma("unroll") for (int n = 0; n < 2; ++n) _Pragma("unroll") for (int k = 0; k < 2; ++k) \
;         acc[ai][bj][m][n] = __builtin_amdgcn_mfma_f32_16x16x32_bf16(Bt[n][k], At[m][k], acc[ai][bj][m][n], 0, 0, 0); __builtin_amdgcn_s_setprio(0); } while (0)
; #define PG8_WAIT_V(n) asm volatile("s_waitcnt vmcnt(" #n ")" ::: "memory")
; #define PG8_WAIT_L(n) asm volatile("s_waitcnt lgkmcnt(" #n ")" ::: "memory")
; #define PG8_BAR __builtin_amdgcn_s_barrier()
; #define PG8_SCHED __builtin_amdgcn_sched_barrier(0)
; template <class Epi, bool ALIGN_EPI>
; __device__ __forceinline__ void gemm_phase(LAS unsigned char* lds, const Gemm g, const StaticOrder& S, const Epi& E, const int tid) {
;     ...
;             PG8_WAIT_V(8); PG8_WAIT_L(0); PG8_BAR; PG8_MMA(1, 0, At, B0); PG8_MMA(1, 1, At, B1); PG8_BAR; PG8_SCHED;
	v_mfma_f32_16x16x32_bf16 v[24:27], v[132:135], v[180:183], v[24:27]
	v_mfma_f32_16x16x32_bf16 v[64:67], v[132:135], v[188:191], v[64:67]
	v_mfma_f32_16x16x32_bf16 v[72:75], v[156:159], v[188:191], v[72:75]
	v_mfma_f32_16x16x32_bf16 v[20:23], v[156:159], v[180:183], v[20:23]
	v_mfma_f32_16x16x32_bf16 v[16:19], v[132:135], v[196:199], v[16:19]
	v_mfma_f32_16x16x32_bf16 v[60:63], v[132:135], v[218:221], v[60:63]
	v_mfma_f32_16x16x32_bf16 v[68:71], v[156:159], v[218:221], v[68:71]
	v_mfma_f32_16x16x32_bf16 v[12:15], v[156:159], v[196:199], v[12:15]
	v_mfma_f32_16x16x32_bf16 v[24:27], v[148:151], v[184:187], v[24:27]
	v_mfma_f32_16x16x32_bf16 v[64:67], v[148:151], v[192:195], v[64:67]
	v_mfma_f32_16x16x32_bf16 v[72:75], v[160:163], v[192:195], v[72:75]
	v_mfma_f32_16x16x32_bf16 v[20:23], v[160:163], v[184:187], v[20:23]
	v_mfma_f32_16x16x32_bf16 v[16:19], v[148:151], v[214:217], v[16:19]
	v_mfma_f32_16x16x32_bf16 v[60:63], v[148:151], v[222:225], v[60:63]
	v_mfma_f32_16x16x32_bf16 v[68:71], v[160:163], v[222:225], v[68:71]
	v_mfma_f32_16x16x32_bf16 v[12:15], v[160:163], v[214:217], v[12:15]


; #define PG8_MMA(ai, bj, At, Bt) do { __builtin_amdgcn_s_setprio(1); _Pragma("unroll") for (int m = 0; m < 4; ++m) _Pragma("unroll") for (int n = 0; n < 2; ++n) _Pragma("unroll") for (int k = 0; k < 2; ++k) \
;         acc[ai][bj][m][n] = __builtin_amdgcn_mfma_f32_16x16x32_bf16(Bt[n][k], At[m][k], acc[ai][bj][m][n], 0, 0, 0); __builtin_amdgcn_s_setprio(0); } while (0)
; #define PG8_WAIT_V(n) asm volatile("s_waitcnt vmcnt(" #n ")" ::: "memory")
; #define PG8_WAIT_L(n) asm volatile("s_waitcnt lgkmcnt(" #n ")" ::: "memory")
; #define PG8_BAR __builtin_amdgcn_s_barrier()
; #define PG8_SCHED __builtin_amdgcn_sched_barrier(0)
; template <class Epi, bool ALIGN_EPI>
; __device__ __forceinline__ void gemm_phase(LAS unsigned char* lds, const Gemm g, const StaticOrder& S, const Epi& E, const int tid) {
;     ...
;             PG8_WAIT_V(8); PG8_WAIT_L(0); PG8_BAR; PG8_MMA(1, 0, At, B0); PG8_MMA(1, 1, At, B1); PG8_BAR; PG8_SCHED;
	v_mfma_f32_16x16x32_bf16 v[128:131], v[164:167], v[180:183], v[128:131]
	v_mfma_f32_16x16x32_bf16 v[120:123], v[164:167], v[188:191], v[120:123]
	v_mfma_f32_16x16x32_bf16 v[116:119], v[172:175], v[188:191], v[116:119]
	v_mfma_f32_16x16x32_bf16 v[124:127], v[172:175], v[180:183], v[124:127]
	v_mfma_f32_16x16x32_bf16 v[112:115], v[164:167], v[196:199], v[112:115]
	v_mfma_f32_16x16x32_bf16 v[104:107], v[164:167], v[218:221], v[104:107]
	v_mfma_f32_16x16x32_bf16 v[100:103], v[172:175], v[218:221], v[100:103]
	v_mfma_f32_16x16x32_bf16 v[108:111], v[172:175], v[196:199], v[108:111]
	v_mfma_f32_16x16x32_bf16 v[128:131], v[168:171], v[184:187], v[128:131]
	v_mfma_f32_16x16x32_bf16 v[120:123], v[168:171], v[192:195], v[120:123]
	v_mfma_f32_16x16x32_bf16 v[116:119], v[176:179], v[192:195], v[116:119]
	v_mfma_f32_16x16x32_bf16 v[124:127], v[176:179], v[184:187], v[124:127]
	v_mfma_f32_16x16x32_bf16 v[112:115], v[168:171], v[214:217], v[112:115]
	v_mfma_f32_16x16x32_bf16 v[104:107], v[168:171], v[222:225], v[104:107]
	v_mfma_f32_16x16x32_bf16 v[100:103], v[176:179], v[222:225], v[100:103]
	v_mfma_f32_16x16x32_bf16 v[108:111], v[176:179], v[214:217], v[108:111]

; #define PG8_STAGE(bufoff, gbase, voff) do { _Pragma("unroll") for (int _i = 0; _i < 2; ++_i) \
;         __builtin_amdgcn_global_load_lds((const unsigned*)((const char*)(gbase) + (voff)[_i]), (LAS unsigned*)(lds + (bufoff) + ldsw + _i * 8192), 16, 0, 0); } while (0)
; #define PG8_LDA(dst, b, h) do { _Pragma("unroll") for (int m = 0; m < 4; ++m) _Pragma("unroll") for (int k = 0; k < 2; ++k) dst[m][k] = *(const LAS bf16x8*)(lds + PG8_SA(b, h) + aoff + m * 2048 + k * 1024); } while (0)
; #define PG8_LDB(dst, b, h) do { _Pragma("unroll") for (int n = 0; n < 2; ++n) _Pragma("unroll") for (int k = 0; k < 2; ++k) dst[n][k] = *(const LAS bf16x8*)(lds + PG8_SB(b, h) + boff + n * 2048 + k * 1024); } while (0)
; #define PG8_MMA(ai, bj, At, Bt) do { __builtin_amdgcn_s_setprio(1); _Pragma("unroll") for (int m = 0; m < 4; ++m) _Pragma("unroll") for (int n = 0; n < 2; ++n) _Pragma("unroll") for (int k = 0; k < 2; ++k) \
;         acc[ai][bj][m][n] = __builtin_amdgcn_mfma_f32_16x16x32_bf16(Bt[n][k], At[m][k], acc[ai][bj][m][n], 0, 0, 0); __builtin_amdgcn_s_setprio(0); } while (0)
; #define PG8_WAIT_V(n) asm volatile("s_waitcnt vmcnt(" #n ")" ::: "memory")
; #define PG8_WAIT_L(n) asm volatile("s_waitcnt lgkmcnt(" #n ")" ::: "memory")
; #define PG8_BAR __builtin_amdgcn_s_barrier()
; #define PG8_SCHED __builtin_amdgcn_sched_barrier(0)
; template <class Epi, bool ALIGN_EPI>
; __device__ __forceinline__ void gemm_phase(LAS unsigned char* lds, const Gemm g, const StaticOrder& S, const Epi& E, const int tid) {
;     ...
;             PG8_WAIT_V(8); PG8_WAIT_L(0); PG8_BAR; PG8_MMA(1, 0, At, B0); PG8_MMA(1, 1, At, B1); PG8_BAR; PG8_SCHED;
;             PG8_LDB(B0, 1, 0); PG8_LDB(B1, 1, 1); PG8_SCHED; PG8_LDA(At, 1, 0); PG8_STAGE(PG8_SA(0, 1), a2 + hstepA, voffA);
	s_barrier
	s_add_i32 s87, 0, 0x18000
	v_add_u32_e32 v0, s87, v154
	s_add_i32 s88, 0, 0x1c000
	ds_read_b128 v[132:135], v0
	ds_read_b128 v[148:151], v0 offset:1024
	ds_read_b128 v[156:159], v0 offset:2048
	ds_read_b128 v[160:163], v0 offset:3072
	v_add_u32_e32 v0, s88, v154
	ds_read_b128 v[164:167], v0
	ds_read_b128 v[168:171], v0 offset:1024
	ds_read_b128 v[172:175], v0 offset:2048
	ds_read_b128 v[176:179], v0 offset:3072
	s_add_u32 s42, s42, 0x4000
	s_addc_u32 s43, s43, 0
	s_mov_b32 m0, s61
	ds_read_b128 v[180:183], v155 offset:32768
	ds_read_b128 v[184:187], v155 offset:33792
	ds_read_b128 v[188:191], v155 offset:34816
	ds_read_b128 v[192:195], v155 offset:35840
	ds_read_b128 v[196:199], v155 offset:36864
	ds_read_b128 v[214:217], v155 offset:37888
	ds_read_b128 v[218:221], v155 offset:38912

; #define PG8_STAGE(bufoff, gbase, voff) do { _Pragma("unroll") for (int _i = 0; _i < 2; ++_i) \
;         __builtin_amdgcn_global_load_lds((const unsigned*)((const char*)(gbase) + (voff)[_i]), (LAS unsigned*)(lds + (bufoff) + ldsw + _i * 8192), 16, 0, 0); } while (0)
; #define PG8_LDA(dst, b, h) do { _Pragma("unroll") for (int m = 0; m < 4; ++m) _Pragma("unroll") for (int k = 0; k < 2; ++k) dst[m][k] = *(const LAS bf16x8*)(lds + PG8_SA(b, h) + aoff + m * 2048 + k * 1024); } while (0)
; #define PG8_LDB(dst, b, h) do { _Pragma("unroll") for (int n = 0; n < 2; ++n) _Pragma("unroll") for (int k = 0; k < 2; ++k) dst[n][k] = *(const LAS bf16x8*)(lds + PG8_SB(b, h) + boff + n * 2048 + k * 1024); } while (0)
; #define PG8_MMA(ai, bj, At, Bt) do { __builtin_amdgcn_s_setprio(1); _Pragma("unroll") for (int m = 0; m < 4; ++m) _Pragma("unroll") for (int n = 0; n < 2; ++n) _Pragma("unroll") for (int k = 0; k < 2; ++k) \
;         acc[ai][bj][m][n] = __builtin_amdgcn_mfma_f32_16x16x32_bf16(Bt[n][k], At[m][k], acc[ai][bj][m][n], 0, 0, 0); __builtin_amdgcn_s_setprio(0); } while (0)
; #define PG8_WAIT_V(n) asm volatile("s_waitcnt vmcnt(" #n ")" ::: "memory")
; #define PG8_WAIT_L(n) asm volatile("s_waitcnt lgkmcnt(" #n ")" ::: "memory")
; #define PG8_BAR __builtin_amdgcn_s_barrier()
; #define PG8_SCHED __builtin_amdgcn_sched_barrier(0)
; template <class Epi, bool ALIGN_EPI>
; __device__ __forceinline__ void gemm_phase(LAS unsigned char* lds, const Gemm g, const StaticOrder& S, const Epi& E, const int tid) {
;     ...
;             PG8_LDB(B0, 1, 0); PG8_LDB(B1, 1, 1); PG8_SCHED; PG8_LDA(At, 1, 0); PG8_STAGE(PG8_SA(0, 1), a2 + hstepA, voffA);
;             PG8_WAIT_V(8); PG8_WAIT_L(0); PG8_BAR; PG8_MMA(0, 0, At, B0); PG8_MMA(0, 1, At, B1); PG8_BAR; PG8_SCHED;
	global_load_lds_dwordx4 v142, s[42:43]
	s_mov_b32 m0, s71
	ds_read_b128 v[222:225], v155 offset:39936
	global_load_lds_dwordx4 v138, s[42:43]
	s_waitcnt vmcnt(8)
	s_waitcnt lgkmcnt(0)
	s_barrier


; #define PG8_MMA(ai, bj, At, Bt) do { __builtin_amdgcn_s_setprio(1); _Pragma("unroll") for (int m = 0; m < 4; ++m) _Pragma("unroll") for (int n = 0; n < 2; ++n) _Pragma("unroll") for (int k = 0; k < 2; ++k) \
;         acc[ai][bj][m][n] = __builtin_amdgcn_mfma_f32_16x16x32_bf16(Bt[n][k], At[m][k], acc[ai][bj][m][n], 0, 0, 0); __builtin_amdgcn_s_setprio(0); } while (0)
; #define PG8_WAIT_V(n) asm volatile("s_waitcnt vmcnt(" #n ")" ::: "memory")
; #define PG8_WAIT_L(n) asm volatile("s_waitcnt lgkmcnt(" #n ")" ::: "memory")
; #define PG8_BAR __builtin_amdgcn_s_barrier()
; #define PG8_SCHED __builtin_amdgcn_sched_barrier(0)
; template <class Epi, bool ALIGN_EPI>
; __device__ __forceinline__ void gemm_phase(LAS unsigned char* lds, const Gemm g, const StaticOrder& S, const Epi& E, const int tid) {
;     ...
;             PG8_WAIT_V(8); PG8_WAIT_L(0); PG8_BAR; PG8_MMA(0, 0, At, B0); PG8_MMA(0, 1, At, B1); PG8_BAR; PG8_SCHED;
	v_mfma_f32_16x16x32_bf16 v[6:9], v[132:135], v[180:183], v[8:11]
	v_mfma_f32_16x16x32_bf16 v[52:55], v[132:135], v[188:191], v[52:55]
	v_mfma_f32_16x16x32_bf16 v[48:51], v[156:159], v[188:191], v[48:51]
	v_mfma_f32_16x16x32_bf16 v[56:59], v[156:159], v[180:183], v[56:59]
	v_mfma_f32_16x16x32_bf16 v[44:47], v[132:135], v[196:199], v[44:47]
	v_mfma_f32_16x16x32_bf16 v[36:39], v[132:135], v[218:221], v[36:39]
	v_mfma_f32_16x16x32_bf16 v[32:35], v[156:159], v[218:221], v[32:35]
	v_mfma_f32_16x16x32_bf16 v[40:43], v[156:159], v[196:199], v[40:43]
	v_mfma_f32_16x16x32_bf16 v[8:11], v[148:151], v[184:187], v[6:9]
	v_mfma_f32_16x16x32_bf16 v[52:55], v[148:151], v[192:195], v[52:55]
	v_mfma_f32_16x16x32_bf16 v[48:51], v[160:163], v[192:195], v[48:51]
	v_mfma_f32_16x16x32_bf16 v[56:59], v[160:163], v[184:187], v[56:59]
	v_mfma_f32_16x16x32_bf16 v[44:47], v[148:151], v[214:217], v[44:47]
	v_mfma_f32_16x16x32_bf16 v[36:39], v[148:151], v[222:225], v[36:39]
	v_mfma_f32_16x16x32_bf16 v[32:35], v[160:163], v[222:225], v[32:35]
	v_mfma_f32_16x16x32_bf16 v[40:43], v[160:163], v[214:217], v[40:43]


; #define PG8_MMA(ai, bj, At, Bt) do { __builtin_amdgcn_s_setprio(1); _Pragma("unroll") for (int m = 0; m < 4; ++m) _Pragma("unroll") for (int n = 0; n < 2; ++n) _Pragma("unroll") for (int k = 0; k < 2; ++k) \
;         acc[ai][bj][m][n] = __builtin_amdgcn_mfma_f32_16x16x32_bf16(Bt[n][k], At[m][k], acc[ai][bj][m][n], 0, 0, 0); __builtin_amdgcn_s_setprio(0); } while (0)
; #define PG8_WAIT_V(n) asm volatile("s_waitcnt vmcnt(" #n ")" ::: "memory")
; #define PG8_WAIT_L(n) asm volatile("s_waitcnt lgkmcnt(" #n ")" ::: "memory")
; #define PG8_BAR __builtin_amdgcn_s_barrier()
; #define PG8_SCHED __builtin_amdgcn_sched_barrier(0)
; template <class Epi, bool ALIGN_EPI>
; __device__ __forceinline__ void gemm_phase(LAS unsigned char* lds, const Gemm g, const StaticOrder& S, const Epi& E, const int tid) {
;     ...
;             PG8_WAIT_V(8); PG8_WAIT_L(0); PG8_BAR; PG8_MMA(0, 0, At, B0); PG8_MMA(0, 1, At, B1); PG8_BAR; PG8_SCHED;
	v_mfma_f32_16x16x32_bf16 v[2:5], v[164:167], v[180:183], v[2:5]
	v_mfma_f32_16x16x32_bf16 v[96:99], v[164:167], v[188:191], v[96:99]
	v_mfma_f32_16x16x32_bf16 v[92:95], v[172:175], v[188:191], v[92:95]
	v_mfma_f32_16x16x32_bf16 v[28:31], v[172:175], v[180:183], v[28:31]
	v_mfma_f32_16x16x32_bf16 v[88:91], v[164:167], v[196:199], v[88:91]
	v_mfma_f32_16x16x32_bf16 v[80:83], v[164:167], v[218:221], v[80:83]
	v_mfma_f32_16x16x32_bf16 v[76:79], v[172:175], v[218:221], v[76:79]
	v_mfma_f32_16x16x32_bf16 v[84:87], v[172:175], v[196:199], v[84:87]
	v_mfma_f32_16x16x32_bf16 v[4:7], v[168:171], v[184:187], v[2:5]
	v_mfma_f32_16x16x32_bf16 v[96:99], v[168:171], v[192:195], v[96:99]
	v_mfma_f32_16x16x32_bf16 v[92:95], v[176:179], v[192:195], v[92:95]
	v_mfma_f32_16x16x32_bf16 v[28:31], v[176:179], v[184:187], v[28:31]
	v_mfma_f32_16x16x32_bf16 v[88:91], v[168:171], v[214:217], v[88:91]
	v_mfma_f32_16x16x32_bf16 v[80:83], v[168:171], v[222:225], v[80:83]
	v_mfma_f32_16x16x32_bf16 v[76:79], v[176:179], v[222:225], v[76:79]
	v_mfma_f32_16x16x32_bf16 v[84:87], v[176:179], v[214:217], v[84:87]

; #define PG8_STAGE(bufoff, gbase, voff) do { _Pragma("unroll") for (int _i = 0; _i < 2; ++_i) \
;         __builtin_amdgcn_global_load_lds((const unsigned*)((const char*)(gbase) + (voff)[_i]), (LAS unsigned*)(lds + (bufoff) + ldsw + _i * 8192), 16, 0, 0); } while (0)
; #define PG8_LDA(dst, b, h) do { _Pragma("unroll") for (int m = 0; m < 4; ++m) _Pragma("unroll") for (int k = 0; k < 2; ++k) dst[m][k] = *(const LAS bf16x8*)(lds + PG8_SA(b, h) + aoff + m * 2048 + k * 1024); } while (0)
; #define PG8_MMA(ai, bj, At, Bt) do { __builtin_amdgcn_s_setprio(1); _Pragma("unroll") for (int m = 0; m < 4; ++m) _Pragma("unroll") for (int n = 0; n < 2; ++n) _Pragma("unroll") for (int k = 0; k < 2; ++k) \
;         acc[ai][bj][m][n] = __builtin_amdgcn_mfma_f32_16x16x32_bf16(Bt[n][k], At[m][k], acc[ai][bj][m][n], 0, 0, 0); __builtin_amdgcn_s_setprio(0); } while (0)
; #define PG8_WAIT_V(n) asm volatile("s_waitcnt vmcnt(" #n ")" ::: "memory")
; #define PG8_WAIT_L(n) asm volatile("s_waitcnt lgkmcnt(" #n ")" ::: "memory")
; #define PG8_BAR __builtin_amdgcn_s_barrier()
; #define PG8_SCHED __builtin_amdgcn_sched_barrier(0)
; template <class Epi, bool ALIGN_EPI>
; __device__ __forceinline__ void gemm_phase(LAS unsigned char* lds, const Gemm g, const StaticOrder& S, const Epi& E, const int tid) {
;     ...
;             PG8_WAIT_V(8); PG8_WAIT_L(0); PG8_BAR; PG8_MMA(0, 0, At, B0); PG8_MMA(0, 1, At, B1); PG8_BAR; PG8_SCHED;
;             PG8_LDA(At, 1, 1); PG8_STAGE(PG8_SB(1, 0), b3, voffB); PG8_STAGE(PG8_SB(1, 1), b3 + hstepB, voffB); PG8_STAGE(PG8_SA(1, 0), a3, voffA);
	s_barrier
	s_add_u32 s42, s34, 0x8000
	s_addc_u32 s43, s35, 0
	s_add_i32 s87, s87, s56
	s_mov_b32 m0, s87
	ds_read_b128 v[180:183], v155 offset:49152
	ds_read_b128 v[184:187], v155 offset:50176
	ds_read_b128 v[188:191], v155 offset:51200
	ds_read_b128 v[192:195], v155 offset:52224


; #define PG8_STAGE(bufoff, gbase, voff) do { _Pragma("unroll") for (int _i = 0; _i < 2; ++_i) \
;         __builtin_amdgcn_global_load_lds((const unsigned*)((const char*)(gbase) + (voff)[_i]), (LAS unsigned*)(lds + (bufoff) + ldsw + _i * 8192), 16, 0, 0); } while (0)
; #define PG8_LDA(dst, b, h) do { _Pragma("unroll") for (int m = 0; m < 4; ++m) _Pragma("unroll") for (int k = 0; k < 2; ++k) dst[m][k] = *(const LAS bf16x8*)(lds + PG8_SA(b, h) + aoff + m * 2048 + k * 1024); } while (0)
; #define PG8_MMA(ai, bj, At, Bt) do { __builtin_amdgcn_s_setprio(1); _Pragma("unroll") for (int m = 0; m < 4; ++m) _Pragma("unroll") for (int n = 0; n < 2; ++n) _Pragma("unroll") for (int k = 0; k < 2; ++k) \
;         acc[ai][bj][m][n] = __builtin_amdgcn_mfma_f32_16x16x32_bf16(Bt[n][k], At[m][k], acc[ai][bj][m][n], 0, 0, 0); __builtin_amdgcn_s_setprio(0); } while (0)
; #define PG8_WAIT_V(n) asm volatile("s_waitcnt vmcnt(" #n ")" ::: "memory")
; #define PG8_WAIT_L(n) asm volatile("s_waitcnt lgkmcnt(" #n ")" ::: "memory")
; #define PG8_BAR __builtin_amdgcn_s_barrier()
; #define PG8_SCHED __builtin_amdgcn_sched_barrier(0)
; template <class Epi, bool ALIGN_EPI>
; __device__ __forceinline__ void gemm_phase(LAS unsigned char* lds, const Gemm g, const StaticOrder& S, const Epi& E, const int tid) {
;     ...
;             PG8_LDA(At, 1, 1); PG8_STAGE(PG8_SB(1, 0), b3, voffB); PG8_STAGE(PG8_SB(1, 1), b3 + hstepB, voffB); PG8_STAGE(PG8_SA(1, 0), a3, voffA);
;             PG8_WAIT_V(8); PG8_WAIT_L(0); PG8_BAR; PG8_MMA(1, 0, At, B0); PG8_MMA(1, 1, At, B1); PG8_BAR; PG8_SCHED;
	global_load_lds_dwordx4 v140, s[42:43]
	s_add_i32 m0, s87, 0x2000
	s_add_u32 s34, s34, 0xc000
	s_addc_u32 s35, s35, 0
	global_load_lds_dwordx4 v136, s[42:43]
	s_add_i32 s42, s88, s56
	s_mov_b32 m0, s42
	ds_read_b128 v[222:225], v155 offset:56320
	global_load_lds_dwordx4 v140, s[34:35]
	s_add_i32 m0, s42, 0x2000
	ds_read_b128 v[218:221], v155 offset:55296
	global_load_lds_dwordx4 v136, s[34:35]
	s_mov_b32 m0, s76
	ds_read_b128 v[214:217], v155 offset:54272
	global_load_lds_dwordx4 v142, s[22:23]
	s_mov_b32 m0, s77
	ds_read_b128 v[196:199], v155 offset:53248
	global_load_lds_dwordx4 v138, s[22:23]
	s_waitcnt vmcnt(8)
	s_waitcnt lgkmcnt(0)
	s_barrier


; #define PG8_MMA(ai, bj, At, Bt) do { __builtin_amdgcn_s_setprio(1); _Pragma("unroll") for (int m = 0; m < 4; ++m) _Pragma("unroll") for (int n = 0; n < 2; ++n) _Pragma("unroll") for (int k = 0; k < 2; ++k) \
;         acc[ai][bj][m][n] = __builtin_amdgcn_mfma_f32_16x16x32_bf16(Bt[n][k], At[m][k], acc[ai][bj][m][n], 0, 0, 0); __builtin_amdgcn_s_setprio(0); } while (0)
; #define PG8_WAIT_V(n) asm volatile("s_waitcnt vmcnt(" #n ")" ::: "memory")
; #define PG8_WAIT_L(n) asm volatile("s_waitcnt lgkmcnt(" #n ")" ::: "memory")
; #define PG8_BAR __builtin_amdgcn_s_barrier()
; #define PG8_SCHED __builtin_amdgcn_sched_barrier(0)
; template <class Epi, bool ALIGN_EPI>
; __device__ __forceinline__ void gemm_phase(LAS unsigned char* lds, const Gemm g, const StaticOrder& S, const Epi& E, const int tid) {
;     ...
;             PG8_WAIT_V(8); PG8_WAIT_L(0); PG8_BAR; PG8_MMA(1, 0, At, B0); PG8_MMA(1, 1, At, B1); PG8_BAR; PG8_SCHED;
	v_mfma_f32_16x16x32_bf16 v[24:27], v[132:135], v[180:183], v[24:27]
	v_mfma_f32_16x16x32_bf16 v[64:67], v[132:135], v[188:191], v[64:67]
	v_mfma_f32_16x16x32_bf16 v[72:75], v[156:159], v[188:191], v[72:75]
	v_mfma_f32_16x16x32_bf16 v[20:23], v[156:159], v[180:183], v[20:23]
	v_mfma_f32_16x16x32_bf16 v[16:19], v[132:135], v[196:199], v[16:19]
	v_mfma_f32_16x16x32_bf16 v[60:63], v[132:135], v[218:221], v[60:63]
	v_mfma_f32_16x16x32_bf16 v[68:71], v[156:159], v[218:221], v[68:71]
	v_mfma_f32_16x16x32_bf16 v[12:15], v[156:159], v[196:199], v[12:15]
	v_mfma_f32_16x16x32_bf16 v[24:27], v[148:151], v[184:187], v[24:27]
	v_mfma_f32_16x16x32_bf16 v[64:67], v[148:151], v[192:195], v[64:67]
	v_mfma_f32_16x16x32_bf16 v[72:75], v[160:163], v[192:195], v[72:75]
	v_mfma_f32_16x16x32_bf16 v[20:23], v[160:163], v[184:187], v[20:23]
	v_mfma_f32_16x16x32_bf16 v[16:19], v[148:151], v[214:217], v[16:19]
	v_mfma_f32_16x16x32_bf16 v[60:63], v[148:151], v[222:225], v[60:63]
	v_mfma_f32_16x16x32_bf16 v[68:71], v[160:163], v[222:225], v[68:71]
	v_mfma_f32_16x16x32_bf16 v[12:15], v[160:163], v[214:217], v[12:15]


; #define PG8_MMA(ai, bj, At, Bt) do { __builtin_amdgcn_s_setprio(1); _Pragma("unroll") for (int m = 0; m < 4; ++m) _Pragma("unroll") for (int n = 0; n < 2; ++n) _Pragma("unroll") for (int k = 0; k < 2; ++k) \
;         acc[ai][bj][m][n] = __builtin_amdgcn_mfma_f32_16x16x32_bf16(Bt[n][k], At[m][k], acc[ai][bj][m][n], 0, 0, 0); __builtin_amdgcn_s_setprio(0); } while (0)
; #define PG8_WAIT_V(n) asm volatile("s_waitcnt vmcnt(" #n ")" ::: "memory")
; #define PG8_WAIT_L(n) asm volatile("s_waitcnt lgkmcnt(" #n ")" ::: "memory")
; #define PG8_BAR __builtin_amdgcn_s_barrier()
; #define PG8_SCHED __builtin_amdgcn_sched_barrier(0)
; template <class Epi, bool ALIGN_EPI>
; __device__ __forceinline__ void gemm_phase(LAS unsigned char* lds, const Gemm g, const StaticOrder& S, const Epi& E, const int tid) {
;     ...
;             PG8_WAIT_V(8); PG8_WAIT_L(0); PG8_BAR; PG8_MMA(1, 0, At, B0); PG8_MMA(1, 1, At, B1); PG8_BAR; PG8_SCHED;
	v_mfma_f32_16x16x32_bf16 v[128:131], v[164:167], v[180:183], v[128:131]
	v_mfma_f32_16x16x32_bf16 v[120:123], v[164:167], v[188:191], v[120:123]
	v_mfma_f32_16x16x32_bf16 v[116:119], v[172:175], v[188:191], v[116:119]
	v_mfma_f32_16x16x32_bf16 v[124:127], v[172:175], v[180:183], v[124:127]
	v_mfma_f32_16x16x32_bf16 v[112:115], v[164:167], v[196:199], v[112:115]
	v_mfma_f32_16x16x32_bf16 v[104:107], v[164:167], v[218:221], v[104:107]
	v_mfma_f32_16x16x32_bf16 v[100:103], v[172:175], v[218:221], v[100:103]
	v_mfma_f32_16x16x32_bf16 v[108:111], v[172:175], v[196:199], v[108:111]
	v_mfma_f32_16x16x32_bf16 v[128:131], v[168:171], v[184:187], v[128:131]
	v_mfma_f32_16x16x32_bf16 v[120:123], v[168:171], v[192:195], v[120:123]
	v_mfma_f32_16x16x32_bf16 v[116:119], v[176:179], v[192:195], v[116:119]
	v_mfma_f32_16x16x32_bf16 v[124:127], v[176:179], v[184:187], v[124:127]
	v_mfma_f32_16x16x32_bf16 v[112:115], v[168:171], v[214:217], v[112:115]
	v_mfma_f32_16x16x32_bf16 v[104:107], v[168:171], v[222:225], v[104:107]
	v_mfma_f32_16x16x32_bf16 v[100:103], v[176:179], v[222:225], v[100:103]
	v_mfma_f32_16x16x32_bf16 v[108:111], v[176:179], v[214:217], v[108:111]

; #define PG8_MMA(ai, bj, At, Bt) do { __builtin_amdgcn_s_setprio(1); _Pragma("unroll") for (int m = 0; m < 4; ++m) _Pragma("unroll") for (int n = 0; n < 2; ++n) _Pragma("unroll") for (int k = 0; k < 2; ++k) \
;         acc[ai][bj][m][n] = __builtin_amdgcn_mfma_f32_16x16x32_bf16(Bt[n][k], At[m][k], acc[ai][bj][m][n], 0, 0, 0); __builtin_amdgcn_s_setprio(0); } while (0)
; #define PG8_WAIT_V(n) asm volatile("s_waitcnt vmcnt(" #n ")" ::: "memory")
; #define PG8_WAIT_L(n) asm volatile("s_waitcnt lgkmcnt(" #n ")" ::: "memory")
; #define PG8_BAR __builtin_amdgcn_s_barrier()
; #define PG8_SCHED __builtin_amdgcn_sched_barrier(0)
; template <class Epi, bool ALIGN_EPI>
; __device__ __forceinline__ void gemm_phase(LAS unsigned char* lds, const Gemm g, const StaticOrder& S, const Epi& E, const int tid) {
;     ...
;             PG8_WAIT_V(8); PG8_WAIT_L(0); PG8_BAR; PG8_MMA(1, 0, At, B0); PG8_MMA(1, 1, At, B1); PG8_BAR; PG8_SCHED;
;         }
;         if constexpr (ALIGN_EPI) { if (wr == 0) PG8_BAR; }
;     __device__ __forceinline__ void operator()(f32x4 (&acc)[2][2][4][2], const Unit& u, int wr, int wc, LAS unsigned char* lds, int& rs_pm) const {
;     ...
;                 bf16* const xrow = xb + (((size_t)(u.pm * 32 + u.pn * 4 + (wc >> 1)) * BM + (wr * 64 + fr + ai * HALF + m * 16)) * 64 + (wc & 1) * 32 + 8 * fq);
; #pragma unroll
;                 for (int bj = 0; bj < 2; ++bj) {
;                     const u32x4 xw = *(const u32x4*)(xrow + (size_t)bj * (2 * BM * 64));
	s_barrier
	s_add_i32 s86, s86, 2
	s_add_u32 s84, s84, 0x10000
	s_addc_u32 s85, s85, 0
	s_add_u32 s10, s10, 0x10000
	s_addc_u32 s11, s11, 0
	s_cmpk_gt_u32 s86, 0x55
	s_cbranch_scc0 .LBB0_294
	v_and_b32_e32 v222, 15, v238
	v_lshrrev_b32_e32 v156, 4, v238
	s_lshl_b32 s100, s82, 5
	s_lshl_b32 s101, s83, 2
	v_lshlrev_b32_e32 v222, 7, v222
	s_add_i32 s100, s100, s101
	s_or_b32 s100, s100, s78
	v_lshl_or_b32 v222, v156, 4, v222
	s_ashr_i32 s101, s100, 31
	s_lshl_b64 s[100:101], s[100:101], 15
	s_add_u32 s98, s72, s100
	s_addc_u32 s99, s73, s101
	s_add_u32 s98, s98, s30
	s_addc_u32 s99, s99, s31
	s_lshl_b32 s100, s75, 7
	s_add_u32 s98, s98, s100
	s_addc_u32 s99, s99, 0
	s_lshl_b32 s100, s82, 15
	s_lshl_b32 s101, s75, 7
	s_add_i32 s100, s100, s101
	s_lshl_b32 s101, s83, 4
	s_add_i32 s100, s100, s101
	s_lshl_b32 s101, s74, 2
	s_add_i32 s100, s100, s101
	s_add_u32 s22, s44, s100
	s_addc_u32 s23, s45, 0
	global_load_dwordx4 v[176:179], v222, s[98:99]
	s_add_u32 s100, s98, 0x10000
	s_addc_u32 s101, s99, 0
	global_load_dwordx4 v[180:183], v222, s[100:101]
	global_load_dwordx4 v[184:187], v222, s[98:99] offset:2048
	s_add_u32 s100, s98, 0x10000
	s_addc_u32 s101, s99, 0
	global_load_dwordx4 v[188:191], v222, s[100:101] offset:2048
	s_add_u32 s100, s98, 0x1000
	s_addc_u32 s101, s99, 0
	global_load_dwordx4 v[192:195], v222, s[100:101]
	s_add_u32 s100, s98, 0x11000
	s_addc_u32 s101, s99, 0
	global_load_dwordx4 v[196:199], v222, s[100:101]
	s_add_u32 s100, s98, 0x1000
	s_addc_u32 s101, s99, 0
	global_load_dwordx4 v[214:217], v222, s[100:101] offset:2048
	s_add_u32 s100, s98, 0x11000
	s_addc_u32 s101, s99, 0
	global_load_dwordx4 v[218:221], v222, s[100:101] offset:2048
	s_and_b64 vcc, exec, s[46:47]
	s_cbranch_vccz .LBB0_297
	s_barrier

; #define PG8_STAGE(bufoff, gbase, voff) do { _Pragma("unroll") for (int _i = 0; _i < 2; ++_i) \
;         __builtin_amdgcn_global_load_lds((const unsigned*)((const char*)(gbase) + (voff)[_i]), (LAS unsigned*)(lds + (bufoff) + ldsw + _i * 8192), 16, 0, 0); } while (0)
; #define PG8_LDA(dst, b, h) do { _Pragma("unroll") for (int m = 0; m < 4; ++m) _Pragma("unroll") for (int k = 0; k < 2; ++k) dst[m][k] = *(const LAS bf16x8*)(lds + PG8_SA(b, h) + aoff + m * 2048 + k * 1024); } while (0)
; #define PG8_LDB(dst, b, h) do { _Pragma("unroll") for (int n = 0; n < 2; ++n) _Pragma("unroll") for (int k = 0; k < 2; ++k) dst[n][k] = *(const LAS bf16x8*)(lds + PG8_SB(b, h) + boff + n * 2048 + k * 1024); } while (0)
; #define PG8_SCHED __builtin_amdgcn_sched_barrier(0)
; template <class Epi, bool ALIGN_EPI>
; __device__ __forceinline__ void gemm_phase(LAS unsigned char* lds, const Gemm g, const StaticOrder& S, const Epi& E, const int tid) {
;     ...
;             const bool last = (t == nt - 2);
;             const char* a1 = cA + (size_t)(t + 1) * kstepA;
;             const char* a2 = last ? nA : cA + (size_t)(t + 2) * kstepA; const char* b2 = last ? nB : cB + (size_t)(t + 2) * kstepB;
;             const char* a3 = a2 + kstepA; const char* b3 = b2 + kstepB;
;             PG8_LDB(B0, 0, 0); PG8_LDB(B1, 0, 1); PG8_SCHED; PG8_LDA(At, 0, 0); PG8_STAGE(PG8_SA(1, 1), a1 + hstepA, voffA);
.LBB0_385:
	s_add_u32 s50, s48, 0x4000
	s_addc_u32 s51, s49, 0
	s_cmp_eq_u32 s88, 28
	s_cselect_b32 s54, s84, s50
	s_cselect_b32 s55, s43, s51
	s_cselect_b32 s52, s85, s86
	s_cselect_b32 s53, s41, s87
	s_add_u32 s50, s54, 0x8000
	s_addc_u32 s51, s55, 0
	s_add_i32 s89, 0, 0x10000
	v_add_u32_e32 v0, s89, v167
	s_add_i32 s92, 0, 0x14000
	ds_read_b128 v[132:135], v0
	ds_read_b128 v[136:139], v0 offset:1024
	ds_read_b128 v[152:155], v0 offset:2048
	ds_read_b128 v[156:159], v0 offset:3072
	v_add_u32_e32 v0, s92, v167
	ds_read_b128 v[160:163], v0
	ds_read_b128 v[172:175], v0 offset:1024
	ds_read_b128 v[176:179], v0 offset:2048
	ds_read_b128 v[180:183], v0 offset:3072
	s_add_i32 m0, s71, 0xc000
	ds_read_b128 v[184:187], v171
	ds_read_b128 v[188:191], v171 offset:1024
	ds_read_b128 v[192:195], v171 offset:2048
	ds_read_b128 v[196:199], v171 offset:3072
	ds_read_b128 v[214:217], v171 offset:4096
	ds_read_b128 v[218:221], v171 offset:5120
	ds_read_b128 v[222:225], v171 offset:6144

; #define PG8_STAGE(bufoff, gbase, voff) do { _Pragma("unroll") for (int _i = 0; _i < 2; ++_i) \
;         __builtin_amdgcn_global_load_lds((const unsigned*)((const char*)(gbase) + (voff)[_i]), (LAS unsigned*)(lds + (bufoff) + ldsw + _i * 8192), 16, 0, 0); } while (0)
; #define PG8_LDA(dst, b, h) do { _Pragma("unroll") for (int m = 0; m < 4; ++m) _Pragma("unroll") for (int k = 0; k < 2; ++k) dst[m][k] = *(const LAS bf16x8*)(lds + PG8_SA(b, h) + aoff + m * 2048 + k * 1024); } while (0)
; #define PG8_LDB(dst, b, h) do { _Pragma("unroll") for (int n = 0; n < 2; ++n) _Pragma("unroll") for (int k = 0; k < 2; ++k) dst[n][k] = *(const LAS bf16x8*)(lds + PG8_SB(b, h) + boff + n * 2048 + k * 1024); } while (0)
; #define PG8_MMA(ai, bj, At, Bt) do { __builtin_amdgcn_s_setprio(1); _Pragma("unroll") for (int m = 0; m < 4; ++m) _Pragma("unroll") for (int n = 0; n < 2; ++n) _Pragma("unroll") for (int k = 0; k < 2; ++k) \
;         acc[ai][bj][m][n] = __builtin_amdgcn_mfma_f32_16x16x32_bf16(Bt[n][k], At[m][k], acc[ai][bj][m][n], 0, 0, 0); __builtin_amdgcn_s_setprio(0); } while (0)
; #define PG8_WAIT_V(n) asm volatile("s_waitcnt vmcnt(" #n ")" ::: "memory")
; #define PG8_WAIT_L(n) asm volatile("s_waitcnt lgkmcnt(" #n ")" ::: "memory")
; #define PG8_BAR __builtin_amdgcn_s_barrier()
; #define PG8_SCHED __builtin_amdgcn_sched_barrier(0)
; template <class Epi, bool ALIGN_EPI>
; __device__ __forceinline__ void gemm_phase(LAS unsigned char* lds, const Gemm g, const StaticOrder& S, const Epi& E, const int tid) {
;     ...
;             PG8_LDB(B0, 0, 0); PG8_LDB(B1, 0, 1); PG8_SCHED; PG8_LDA(At, 0, 0); PG8_STAGE(PG8_SA(1, 1), a1 + hstepA, voffA);
;             PG8_WAIT_V(8); PG8_WAIT_L(0); PG8_BAR; PG8_MMA(0, 0, At, B0); PG8_MMA(0, 1, At, B1); PG8_BAR; PG8_SCHED;
	global_load_lds_dwordx4 v148, s[48:49]
	s_add_i32 m0, s71, 0xe000
	ds_read_b128 v[226:229], v171 offset:7168
	global_load_lds_dwordx4 v150, s[48:49]
	s_waitcnt vmcnt(8)
	s_waitcnt lgkmcnt(0)
	s_barrier


; #define PG8_MMA(ai, bj, At, Bt) do { __builtin_amdgcn_s_setprio(1); _Pragma("unroll") for (int m = 0; m < 4; ++m) _Pragma("unroll") for (int n = 0; n < 2; ++n) _Pragma("unroll") for (int k = 0; k < 2; ++k) \
;         acc[ai][bj][m][n] = __builtin_amdgcn_mfma_f32_16x16x32_bf16(Bt[n][k], At[m][k], acc[ai][bj][m][n], 0, 0, 0); __builtin_amdgcn_s_setprio(0); } while (0)
; #define PG8_WAIT_V(n) asm volatile("s_waitcnt vmcnt(" #n ")" ::: "memory")
; #define PG8_WAIT_L(n) asm volatile("s_waitcnt lgkmcnt(" #n ")" ::: "memory")
; #define PG8_BAR __builtin_amdgcn_s_barrier()
; #define PG8_SCHED __builtin_amdgcn_sched_barrier(0)
; template <class Epi, bool ALIGN_EPI>
; __device__ __forceinline__ void gemm_phase(LAS unsigned char* lds, const Gemm g, const StaticOrder& S, const Epi& E, const int tid) {
;     ...
;             PG8_WAIT_V(8); PG8_WAIT_L(0); PG8_BAR; PG8_MMA(0, 0, At, B0); PG8_MMA(0, 1, At, B1); PG8_BAR; PG8_SCHED;
	v_mfma_f32_16x16x32_bf16 v[128:131], v[132:135], v[184:187], v[128:131]
	v_mfma_f32_16x16x32_bf16 v[124:127], v[132:135], v[192:195], v[124:127]
	v_mfma_f32_16x16x32_bf16 v[108:111], v[152:155], v[192:195], v[108:111]
	v_mfma_f32_16x16x32_bf16 v[116:119], v[152:155], v[184:187], v[116:119]
	v_mfma_f32_16x16x32_bf16 v[120:123], v[132:135], v[214:217], v[120:123]
	v_mfma_f32_16x16x32_bf16 v[112:115], v[132:135], v[222:225], v[112:115]
	v_mfma_f32_16x16x32_bf16 v[92:95], v[152:155], v[222:225], v[92:95]
	v_mfma_f32_16x16x32_bf16 v[100:103], v[152:155], v[214:217], v[100:103]
	v_mfma_f32_16x16x32_bf16 v[128:131], v[136:139], v[188:191], v[128:131]
	v_mfma_f32_16x16x32_bf16 v[124:127], v[136:139], v[196:199], v[124:127]
	v_mfma_f32_16x16x32_bf16 v[108:111], v[156:159], v[196:199], v[108:111]
	v_mfma_f32_16x16x32_bf16 v[116:119], v[156:159], v[188:191], v[116:119]
	v_mfma_f32_16x16x32_bf16 v[120:123], v[136:139], v[218:221], v[120:123]
	v_mfma_f32_16x16x32_bf16 v[112:115], v[136:139], v[226:229], v[112:115]
	v_mfma_f32_16x16x32_bf16 v[92:95], v[156:159], v[226:229], v[92:95]
	v_mfma_f32_16x16x32_bf16 v[100:103], v[156:159], v[218:221], v[100:103]


; #define PG8_MMA(ai, bj, At, Bt) do { __builtin_amdgcn_s_setprio(1); _Pragma("unroll") for (int m = 0; m < 4; ++m) _Pragma("unroll") for (int n = 0; n < 2; ++n) _Pragma("unroll") for (int k = 0; k < 2; ++k) \
;         acc[ai][bj][m][n] = __builtin_amdgcn_mfma_f32_16x16x32_bf16(Bt[n][k], At[m][k], acc[ai][bj][m][n], 0, 0, 0); __builtin_amdgcn_s_setprio(0); } while (0)
; #define PG8_WAIT_V(n) asm volatile("s_waitcnt vmcnt(" #n ")" ::: "memory")
; #define PG8_WAIT_L(n) asm volatile("s_waitcnt lgkmcnt(" #n ")" ::: "memory")
; #define PG8_BAR __builtin_amdgcn_s_barrier()
; #define PG8_SCHED __builtin_amdgcn_sched_barrier(0)
; template <class Epi, bool ALIGN_EPI>
; __device__ __forceinline__ void gemm_phase(LAS unsigned char* lds, const Gemm g, const StaticOrder& S, const Epi& E, const int tid) {
;     ...
;             PG8_WAIT_V(8); PG8_WAIT_L(0); PG8_BAR; PG8_MMA(0, 0, At, B0); PG8_MMA(0, 1, At, B1); PG8_BAR; PG8_SCHED;
	v_mfma_f32_16x16x32_bf16 v[104:107], v[160:163], v[184:187], v[104:107]
	v_mfma_f32_16x16x32_bf16 v[96:99], v[160:163], v[192:195], v[96:99]
	v_mfma_f32_16x16x32_bf16 v[68:71], v[176:179], v[192:195], v[68:71]
	v_mfma_f32_16x16x32_bf16 v[80:83], v[176:179], v[184:187], v[80:83]
	v_mfma_f32_16x16x32_bf16 v[88:91], v[160:163], v[214:217], v[88:91]
	v_mfma_f32_16x16x32_bf16 v[76:79], v[160:163], v[222:225], v[76:79]
	v_mfma_f32_16x16x32_bf16 v[48:51], v[176:179], v[222:225], v[48:51]
	v_mfma_f32_16x16x32_bf16 v[60:63], v[176:179], v[214:217], v[60:63]
	v_mfma_f32_16x16x32_bf16 v[104:107], v[172:175], v[188:191], v[104:107]
	v_mfma_f32_16x16x32_bf16 v[96:99], v[172:175], v[196:199], v[96:99]
	v_mfma_f32_16x16x32_bf16 v[68:71], v[180:183], v[196:199], v[68:71]
	v_mfma_f32_16x16x32_bf16 v[80:83], v[180:183], v[188:191], v[80:83]
	v_mfma_f32_16x16x32_bf16 v[88:91], v[172:175], v[218:221], v[88:91]
	v_mfma_f32_16x16x32_bf16 v[76:79], v[172:175], v[226:229], v[76:79]
	v_mfma_f32_16x16x32_bf16 v[48:51], v[180:183], v[226:229], v[48:51]
	v_mfma_f32_16x16x32_bf16 v[60:63], v[180:183], v[218:221], v[60:63]

; #define PG8_STAGE(bufoff, gbase, voff) do { _Pragma("unroll") for (int _i = 0; _i < 2; ++_i) \
;         __builtin_amdgcn_global_load_lds((const unsigned*)((const char*)(gbase) + (voff)[_i]), (LAS unsigned*)(lds + (bufoff) + ldsw + _i * 8192), 16, 0, 0); } while (0)
; #define PG8_LDA(dst, b, h) do { _Pragma("unroll") for (int m = 0; m < 4; ++m) _Pragma("unroll") for (int k = 0; k < 2; ++k) dst[m][k] = *(const LAS bf16x8*)(lds + PG8_SA(b, h) + aoff + m * 2048 + k * 1024); } while (0)
; #define PG8_MMA(ai, bj, At, Bt) do { __builtin_amdgcn_s_setprio(1); _Pragma("unroll") for (int m = 0; m < 4; ++m) _Pragma("unroll") for (int n = 0; n < 2; ++n) _Pragma("unroll") for (int k = 0; k < 2; ++k) \
;         acc[ai][bj][m][n] = __builtin_amdgcn_mfma_f32_16x16x32_bf16(Bt[n][k], At[m][k], acc[ai][bj][m][n], 0, 0, 0); __builtin_amdgcn_s_setprio(0); } while (0)
; #define PG8_WAIT_V(n) asm volatile("s_waitcnt vmcnt(" #n ")" ::: "memory")
; #define PG8_WAIT_L(n) asm volatile("s_waitcnt lgkmcnt(" #n ")" ::: "memory")
; #define PG8_BAR __builtin_amdgcn_s_barrier()
; #define PG8_SCHED __builtin_amdgcn_sched_barrier(0)
; template <class Epi, bool ALIGN_EPI>
; __device__ __forceinline__ void gemm_phase(LAS unsigned char* lds, const Gemm g, const StaticOrder& S, const Epi& E, const int tid) {
;     ...
;             PG8_WAIT_V(8); PG8_WAIT_L(0); PG8_BAR; PG8_MMA(0, 0, At, B0); PG8_MMA(0, 1, At, B1); PG8_BAR; PG8_SCHED;
;             PG8_LDA(At, 0, 1); PG8_STAGE(PG8_SB(0, 0), b2, voffB); PG8_STAGE(PG8_SB(0, 1), b2 + hstepB, voffB); PG8_STAGE(PG8_SA(0, 0), a2, voffA);
	s_barrier
	s_add_i32 s89, s89, s61
	s_mov_b32 m0, s89
	ds_read_b128 v[184:187], v171 offset:16384
	ds_read_b128 v[188:191], v171 offset:17408
	ds_read_b128 v[192:195], v171 offset:18432
	ds_read_b128 v[196:199], v171 offset:19456


; #define PG8_STAGE(bufoff, gbase, voff) do { _Pragma("unroll") for (int _i = 0; _i < 2; ++_i) \
;         __builtin_amdgcn_global_load_lds((const unsigned*)((const char*)(gbase) + (voff)[_i]), (LAS unsigned*)(lds + (bufoff) + ldsw + _i * 8192), 16, 0, 0); } while (0)
; #define PG8_LDA(dst, b, h) do { _Pragma("unroll") for (int m = 0; m < 4; ++m) _Pragma("unroll") for (int k = 0; k < 2; ++k) dst[m][k] = *(const LAS bf16x8*)(lds + PG8_SA(b, h) + aoff + m * 2048 + k * 1024); } while (0)
; #define PG8_MMA(ai, bj, At, Bt) do { __builtin_amdgcn_s_setprio(1); _Pragma("unroll") for (int m = 0; m < 4; ++m) _Pragma("unroll") for (int n = 0; n < 2; ++n) _Pragma("unroll") for (int k = 0; k < 2; ++k) \
;         acc[ai][bj][m][n] = __builtin_amdgcn_mfma_f32_16x16x32_bf16(Bt[n][k], At[m][k], acc[ai][bj][m][n], 0, 0, 0); __builtin_amdgcn_s_setprio(0); } while (0)
; #define PG8_WAIT_V(n) asm volatile("s_waitcnt vmcnt(" #n ")" ::: "memory")
; #define PG8_WAIT_L(n) asm volatile("s_waitcnt lgkmcnt(" #n ")" ::: "memory")
; #define PG8_BAR __builtin_amdgcn_s_barrier()
; #define PG8_SCHED __builtin_amdgcn_sched_barrier(0)
; template <class Epi, bool ALIGN_EPI>
; __device__ __forceinline__ void gemm_phase(LAS unsigned char* lds, const Gemm g, const StaticOrder& S, const Epi& E, const int tid) {
;     ...
;             PG8_LDA(At, 0, 1); PG8_STAGE(PG8_SB(0, 0), b2, voffB); PG8_STAGE(PG8_SB(0, 1), b2 + hstepB, voffB); PG8_STAGE(PG8_SA(0, 0), a2, voffA);
;             PG8_WAIT_V(8); PG8_WAIT_L(0); PG8_BAR; PG8_MMA(1, 0, At, B0); PG8_MMA(1, 1, At, B1); PG8_BAR; PG8_SCHED;
	global_load_lds_dwordx4 v144, s[52:53]
	s_add_i32 m0, s89, 0x2000
	s_add_u32 s90, s52, 0x4000
	s_addc_u32 s91, s53, 0
	s_add_i32 s89, s92, s61
	global_load_lds_dwordx4 v140, s[52:53]
	s_mov_b32 m0, s89
	ds_read_b128 v[226:229], v171 offset:23552
	global_load_lds_dwordx4 v144, s[90:91]
	s_add_i32 m0, s89, 0x2000
	ds_read_b128 v[222:225], v171 offset:22528
	global_load_lds_dwordx4 v140, s[90:91]
	s_mov_b32 m0, s71
	ds_read_b128 v[218:221], v171 offset:21504
	global_load_lds_dwordx4 v146, s[54:55]
	s_mov_b32 m0, s72
	ds_read_b128 v[214:217], v171 offset:20480
	global_load_lds_dwordx4 v142, s[54:55]
	s_waitcnt vmcnt(8)
	s_waitcnt lgkmcnt(0)
	s_barrier


; #define PG8_MMA(ai, bj, At, Bt) do { __builtin_amdgcn_s_setprio(1); _Pragma("unroll") for (int m = 0; m < 4; ++m) _Pragma("unroll") for (int n = 0; n < 2; ++n) _Pragma("unroll") for (int k = 0; k < 2; ++k) \
;         acc[ai][bj][m][n] = __builtin_amdgcn_mfma_f32_16x16x32_bf16(Bt[n][k], At[m][k], acc[ai][bj][m][n], 0, 0, 0); __builtin_amdgcn_s_setprio(0); } while (0)
; #define PG8_WAIT_V(n) asm volatile("s_waitcnt vmcnt(" #n ")" ::: "memory")
; #define PG8_WAIT_L(n) asm volatile("s_waitcnt lgkmcnt(" #n ")" ::: "memory")
; #define PG8_BAR __builtin_amdgcn_s_barrier()
; #define PG8_SCHED __builtin_amdgcn_sched_barrier(0)
; template <class Epi, bool ALIGN_EPI>
; __device__ __forceinline__ void gemm_phase(LAS unsigned char* lds, const Gemm g, const StaticOrder& S, const Epi& E, const int tid) {
;     ...
;             PG8_WAIT_V(8); PG8_WAIT_L(0); PG8_BAR; PG8_MMA(1, 0, At, B0); PG8_MMA(1, 1, At, B1); PG8_BAR; PG8_SCHED;
	v_mfma_f32_16x16x32_bf16 v[84:87], v[132:135], v[184:187], v[84:87]
	v_mfma_f32_16x16x32_bf16 v[72:75], v[132:135], v[192:195], v[72:75]
	v_mfma_f32_16x16x32_bf16 v[44:47], v[152:155], v[192:195], v[44:47]
	v_mfma_f32_16x16x32_bf16 v[56:59], v[152:155], v[184:187], v[56:59]
	v_mfma_f32_16x16x32_bf16 v[64:67], v[132:135], v[214:217], v[64:67]
	v_mfma_f32_16x16x32_bf16 v[52:55], v[132:135], v[222:225], v[52:55]
	v_mfma_f32_16x16x32_bf16 v[28:31], v[152:155], v[222:225], v[28:31]
	v_mfma_f32_16x16x32_bf16 v[36:39], v[152:155], v[214:217], v[36:39]
	v_mfma_f32_16x16x32_bf16 v[84:87], v[136:139], v[188:191], v[84:87]
	v_mfma_f32_16x16x32_bf16 v[72:75], v[136:139], v[196:199], v[72:75]
	v_mfma_f32_16x16x32_bf16 v[44:47], v[156:159], v[196:199], v[44:47]
	v_mfma_f32_16x16x32_bf16 v[56:59], v[156:159], v[188:191], v[56:59]
	v_mfma_f32_16x16x32_bf16 v[64:67], v[136:139], v[218:221], v[64:67]
	v_mfma_f32_16x16x32_bf16 v[52:55], v[136:139], v[226:229], v[52:55]
	v_mfma_f32_16x16x32_bf16 v[28:31], v[156:159], v[226:229], v[28:31]
	v_mfma_f32_16x16x32_bf16 v[36:39], v[156:159], v[218:221], v[36:39]


; #define PG8_MMA(ai, bj, At, Bt) do { __builtin_amdgcn_s_setprio(1); _Pragma("unroll") for (int m = 0; m < 4; ++m) _Pragma("unroll") for (int n = 0; n < 2; ++n) _Pragma("unroll") for (int k = 0; k < 2; ++k) \
;         acc[ai][bj][m][n] = __builtin_amdgcn_mfma_f32_16x16x32_bf16(Bt[n][k], At[m][k], acc[ai][bj][m][n], 0, 0, 0); __builtin_amdgcn_s_setprio(0); } while (0)
; #define PG8_WAIT_V(n) asm volatile("s_waitcnt vmcnt(" #n ")" ::: "memory")
; #define PG8_WAIT_L(n) asm volatile("s_waitcnt lgkmcnt(" #n ")" ::: "memory")
; #define PG8_BAR __builtin_amdgcn_s_barrier()
; #define PG8_SCHED __builtin_amdgcn_sched_barrier(0)
; template <class Epi, bool ALIGN_EPI>
; __device__ __forceinline__ void gemm_phase(LAS unsigned char* lds, const Gemm g, const StaticOrder& S, const Epi& E, const int tid) {
;     ...
;             PG8_WAIT_V(8); PG8_WAIT_L(0); PG8_BAR; PG8_MMA(1, 0, At, B0); PG8_MMA(1, 1, At, B1); PG8_BAR; PG8_SCHED;
	v_mfma_f32_16x16x32_bf16 v[40:43], v[160:163], v[184:187], v[40:43]
	v_mfma_f32_16x16x32_bf16 v[32:35], v[160:163], v[192:195], v[32:35]
	v_mfma_f32_16x16x32_bf16 v[12:15], v[176:179], v[192:195], v[12:15]
	v_mfma_f32_16x16x32_bf16 v[20:23], v[176:179], v[184:187], v[20:23]
	v_mfma_f32_16x16x32_bf16 v[24:27], v[160:163], v[214:217], v[24:27]
	v_mfma_f32_16x16x32_bf16 v[16:19], v[160:163], v[222:225], v[16:19]
	v_mfma_f32_16x16x32_bf16 v[2:5], v[176:179], v[222:225], v[4:7]
	v_mfma_f32_16x16x32_bf16 v[8:11], v[176:179], v[214:217], v[8:11]
	v_mfma_f32_16x16x32_bf16 v[40:43], v[172:175], v[188:191], v[40:43]
	v_mfma_f32_16x16x32_bf16 v[32:35], v[172:175], v[196:199], v[32:35]
	v_mfma_f32_16x16x32_bf16 v[12:15], v[180:183], v[196:199], v[12:15]
	v_mfma_f32_16x16x32_bf16 v[20:23], v[180:183], v[188:191], v[20:23]
	v_mfma_f32_16x16x32_bf16 v[24:27], v[172:175], v[218:221], v[24:27]
	v_mfma_f32_16x16x32_bf16 v[16:19], v[172:175], v[226:229], v[16:19]
	v_mfma_f32_16x16x32_bf16 v[2:5], v[180:183], v[226:229], v[2:5]
	v_mfma_f32_16x16x32_bf16 v[8:11], v[180:183], v[218:221], v[8:11]

; #define PG8_STAGE(bufoff, gbase, voff) do { _Pragma("unroll") for (int _i = 0; _i < 2; ++_i) \
;         __builtin_amdgcn_global_load_lds((const unsigned*)((const char*)(gbase) + (voff)[_i]), (LAS unsigned*)(lds + (bufoff) + ldsw + _i * 8192), 16, 0, 0); } while (0)
; #define PG8_LDA(dst, b, h) do { _Pragma("unroll") for (int m = 0; m < 4; ++m) _Pragma("unroll") for (int k = 0; k < 2; ++k) dst[m][k] = *(const LAS bf16x8*)(lds + PG8_SA(b, h) + aoff + m * 2048 + k * 1024); } while (0)
; #define PG8_LDB(dst, b, h) do { _Pragma("unroll") for (int n = 0; n < 2; ++n) _Pragma("unroll") for (int k = 0; k < 2; ++k) dst[n][k] = *(const LAS bf16x8*)(lds + PG8_SB(b, h) + boff + n * 2048 + k * 1024); } while (0)
; #define PG8_MMA(ai, bj, At, Bt) do { __builtin_amdgcn_s_setprio(1); _Pragma("unroll") for (int m = 0; m < 4; ++m) _Pragma("unroll") for (int n = 0; n < 2; ++n) _Pragma("unroll") for (int k = 0; k < 2; ++k) \
;         acc[ai][bj][m][n] = __builtin_amdgcn_mfma_f32_16x16x32_bf16(Bt[n][k], At[m][k], acc[ai][bj][m][n], 0, 0, 0); __builtin_amdgcn_s_setprio(0); } while (0)
; #define PG8_WAIT_V(n) asm volatile("s_waitcnt vmcnt(" #n ")" ::: "memory")
; #define PG8_WAIT_L(n) asm volatile("s_waitcnt lgkmcnt(" #n ")" ::: "memory")
; #define PG8_BAR __builtin_amdgcn_s_barrier()
; #define PG8_SCHED __builtin_amdgcn_sched_barrier(0)
; template <class Epi, bool ALIGN_EPI>
; __device__ __forceinline__ void gemm_phase(LAS unsigned char* lds, const Gemm g, const StaticOrder& S, const Epi& E, const int tid) {
;     ...
;             PG8_WAIT_V(8); PG8_WAIT_L(0); PG8_BAR; PG8_MMA(1, 0, At, B0); PG8_MMA(1, 1, At, B1); PG8_BAR; PG8_SCHED;
;             PG8_LDB(B0, 1, 0); PG8_LDB(B1, 1, 1); PG8_SCHED; PG8_LDA(At, 1, 0); PG8_STAGE(PG8_SA(0, 1), a2 + hstepA, voffA);
	s_barrier
	s_add_i32 s89, 0, 0x18000
	v_add_u32_e32 v0, s89, v167
	s_add_i32 s90, 0, 0x1c000
	ds_read_b128 v[132:135], v0
	ds_read_b128 v[136:139], v0 offset:1024
	ds_read_b128 v[152:155], v0 offset:2048
	ds_read_b128 v[156:159], v0 offset:3072
	v_add_u32_e32 v0, s90, v167
	ds_read_b128 v[160:163], v0
	ds_read_b128 v[172:175], v0 offset:1024
	ds_read_b128 v[176:179], v0 offset:2048
	ds_read_b128 v[180:183], v0 offset:3072
	s_add_u32 s54, s54, 0x4000
	s_addc_u32 s55, s55, 0
	s_mov_b32 m0, s73
	ds_read_b128 v[184:187], v171 offset:32768
	ds_read_b128 v[188:191], v171 offset:33792
	ds_read_b128 v[192:195], v171 offset:34816
	ds_read_b128 v[196:199], v171 offset:35840
	ds_read_b128 v[214:217], v171 offset:36864
	ds_read_b128 v[218:221], v171 offset:37888
	ds_read_b128 v[222:225], v171 offset:38912

; #define PG8_STAGE(bufoff, gbase, voff) do { _Pragma("unroll") for (int _i = 0; _i < 2; ++_i) \
;         __builtin_amdgcn_global_load_lds((const unsigned*)((const char*)(gbase) + (voff)[_i]), (LAS unsigned*)(lds + (bufoff) + ldsw + _i * 8192), 16, 0, 0); } while (0)
; #define PG8_LDA(dst, b, h) do { _Pragma("unroll") for (int m = 0; m < 4; ++m) _Pragma("unroll") for (int k = 0; k < 2; ++k) dst[m][k] = *(const LAS bf16x8*)(lds + PG8_SA(b, h) + aoff + m * 2048 + k * 1024); } while (0)
; #define PG8_LDB(dst, b, h) do { _Pragma("unroll") for (int n = 0; n < 2; ++n) _Pragma("unroll") for (int k = 0; k < 2; ++k) dst[n][k] = *(const LAS bf16x8*)(lds + PG8_SB(b, h) + boff + n * 2048 + k * 1024); } while (0)
; #define PG8_MMA(ai, bj, At, Bt) do { __builtin_amdgcn_s_setprio(1); _Pragma("unroll") for (int m = 0; m < 4; ++m) _Pragma("unroll") for (int n = 0; n < 2; ++n) _Pragma("unroll") for (int k = 0; k < 2; ++k) \
;         acc[ai][bj][m][n] = __builtin_amdgcn_mfma_f32_16x16x32_bf16(Bt[n][k], At[m][k], acc[ai][bj][m][n], 0, 0, 0); __builtin_amdgcn_s_setprio(0); } while (0)
; #define PG8_WAIT_V(n) asm volatile("s_waitcnt vmcnt(" #n ")" ::: "memory")
; #define PG8_WAIT_L(n) asm volatile("s_waitcnt lgkmcnt(" #n ")" ::: "memory")
; #define PG8_BAR __builtin_amdgcn_s_barrier()
; #define PG8_SCHED __builtin_amdgcn_sched_barrier(0)
; template <class Epi, bool ALIGN_EPI>
; __device__ __forceinline__ void gemm_phase(LAS unsigned char* lds, const Gemm g, const StaticOrder& S, const Epi& E, const int tid) {
;     ...
;             PG8_LDB(B0, 1, 0); PG8_LDB(B1, 1, 1); PG8_SCHED; PG8_LDA(At, 1, 0); PG8_STAGE(PG8_SA(0, 1), a2 + hstepA, voffA);
;             PG8_WAIT_V(8); PG8_WAIT_L(0); PG8_BAR; PG8_MMA(0, 0, At, B0); PG8_MMA(0, 1, At, B1); PG8_BAR; PG8_SCHED;
	global_load_lds_dwordx4 v146, s[54:55]
	s_mov_b32 m0, s74
	ds_read_b128 v[226:229], v171 offset:39936
	global_load_lds_dwordx4 v142, s[54:55]
	s_waitcnt vmcnt(8)
	s_waitcnt lgkmcnt(0)
	s_barrier


; #define PG8_MMA(ai, bj, At, Bt) do { __builtin_amdgcn_s_setprio(1); _Pragma("unroll") for (int m = 0; m < 4; ++m) _Pragma("unroll") for (int n = 0; n < 2; ++n) _Pragma("unroll") for (int k = 0; k < 2; ++k) \
;         acc[ai][bj][m][n] = __builtin_amdgcn_mfma_f32_16x16x32_bf16(Bt[n][k], At[m][k], acc[ai][bj][m][n], 0, 0, 0); __builtin_amdgcn_s_setprio(0); } while (0)
; #define PG8_WAIT_V(n) asm volatile("s_waitcnt vmcnt(" #n ")" ::: "memory")
; #define PG8_WAIT_L(n) asm volatile("s_waitcnt lgkmcnt(" #n ")" ::: "memory")
; #define PG8_BAR __builtin_amdgcn_s_barrier()
; #define PG8_SCHED __builtin_amdgcn_sched_barrier(0)
; template <class Epi, bool ALIGN_EPI>
; __device__ __forceinline__ void gemm_phase(LAS unsigned char* lds, const Gemm g, const StaticOrder& S, const Epi& E, const int tid) {
;     ...
;             PG8_WAIT_V(8); PG8_WAIT_L(0); PG8_BAR; PG8_MMA(0, 0, At, B0); PG8_MMA(0, 1, At, B1); PG8_BAR; PG8_SCHED;
	v_mfma_f32_16x16x32_bf16 v[128:131], v[132:135], v[184:187], v[128:131]
	v_mfma_f32_16x16x32_bf16 v[124:127], v[132:135], v[192:195], v[124:127]
	v_mfma_f32_16x16x32_bf16 v[108:111], v[152:155], v[192:195], v[108:111]
	v_mfma_f32_16x16x32_bf16 v[116:119], v[152:155], v[184:187], v[116:119]
	v_mfma_f32_16x16x32_bf16 v[120:123], v[132:135], v[214:217], v[120:123]
	v_mfma_f32_16x16x32_bf16 v[112:115], v[132:135], v[222:225], v[112:115]
	v_mfma_f32_16x16x32_bf16 v[92:95], v[152:155], v[222:225], v[92:95]
	v_mfma_f32_16x16x32_bf16 v[100:103], v[152:155], v[214:217], v[100:103]
	v_mfma_f32_16x16x32_bf16 v[128:131], v[136:139], v[188:191], v[128:131]
	v_mfma_f32_16x16x32_bf16 v[124:127], v[136:139], v[196:199], v[124:127]
	v_mfma_f32_16x16x32_bf16 v[108:111], v[156:159], v[196:199], v[108:111]
	v_mfma_f32_16x16x32_bf16 v[116:119], v[156:159], v[188:191], v[116:119]
	v_mfma_f32_16x16x32_bf16 v[120:123], v[136:139], v[218:221], v[120:123]
	v_mfma_f32_16x16x32_bf16 v[112:115], v[136:139], v[226:229], v[112:115]
	v_mfma_f32_16x16x32_bf16 v[92:95], v[156:159], v[226:229], v[92:95]
	v_mfma_f32_16x16x32_bf16 v[100:103], v[156:159], v[218:221], v[100:103]


; #define PG8_MMA(ai, bj, At, Bt) do { __builtin_amdgcn_s_setprio(1); _Pragma("unroll") for (int m = 0; m < 4; ++m) _Pragma("unroll") for (int n = 0; n < 2; ++n) _Pragma("unroll") for (int k = 0; k < 2; ++k) \
;         acc[ai][bj][m][n] = __builtin_amdgcn_mfma_f32_16x16x32_bf16(Bt[n][k], At[m][k], acc[ai][bj][m][n], 0, 0, 0); __builtin_amdgcn_s_setprio(0); } while (0)
; #define PG8_WAIT_V(n) asm volatile("s_waitcnt vmcnt(" #n ")" ::: "memory")
; #define PG8_WAIT_L(n) asm volatile("s_waitcnt lgkmcnt(" #n ")" ::: "memory")
; #define PG8_BAR __builtin_amdgcn_s_barrier()
; #define PG8_SCHED __builtin_amdgcn_sched_barrier(0)
; template <class Epi, bool ALIGN_EPI>
; __device__ __forceinline__ void gemm_phase(LAS unsigned char* lds, const Gemm g, const StaticOrder& S, const Epi& E, const int tid) {
;     ...
;             PG8_WAIT_V(8); PG8_WAIT_L(0); PG8_BAR; PG8_MMA(0, 0, At, B0); PG8_MMA(0, 1, At, B1); PG8_BAR; PG8_SCHED;
	v_mfma_f32_16x16x32_bf16 v[104:107], v[160:163], v[184:187], v[104:107]
	v_mfma_f32_16x16x32_bf16 v[96:99], v[160:163], v[192:195], v[96:99]
	v_mfma_f32_16x16x32_bf16 v[68:71], v[176:179], v[192:195], v[68:71]
	v_mfma_f32_16x16x32_bf16 v[80:83], v[176:179], v[184:187], v[80:83]
	v_mfma_f32_16x16x32_bf16 v[88:91], v[160:163], v[214:217], v[88:91]
	v_mfma_f32_16x16x32_bf16 v[76:79], v[160:163], v[222:225], v[76:79]
	v_mfma_f32_16x16x32_bf16 v[48:51], v[176:179], v[222:225], v[48:51]
	v_mfma_f32_16x16x32_bf16 v[60:63], v[176:179], v[214:217], v[60:63]
	v_mfma_f32_16x16x32_bf16 v[104:107], v[172:175], v[188:191], v[104:107]
	v_mfma_f32_16x16x32_bf16 v[96:99], v[172:175], v[196:199], v[96:99]
	v_mfma_f32_16x16x32_bf16 v[68:71], v[180:183], v[196:199], v[68:71]
	v_mfma_f32_16x16x32_bf16 v[80:83], v[180:183], v[188:191], v[80:83]
	v_mfma_f32_16x16x32_bf16 v[88:91], v[172:175], v[218:221], v[88:91]
	v_mfma_f32_16x16x32_bf16 v[76:79], v[172:175], v[226:229], v[76:79]
	v_mfma_f32_16x16x32_bf16 v[48:51], v[180:183], v[226:229], v[48:51]
	v_mfma_f32_16x16x32_bf16 v[60:63], v[180:183], v[218:221], v[60:63]

; #define PG8_STAGE(bufoff, gbase, voff) do { _Pragma("unroll") for (int _i = 0; _i < 2; ++_i) \
;         __builtin_amdgcn_global_load_lds((const unsigned*)((const char*)(gbase) + (voff)[_i]), (LAS unsigned*)(lds + (bufoff) + ldsw + _i * 8192), 16, 0, 0); } while (0)
; #define PG8_LDA(dst, b, h) do { _Pragma("unroll") for (int m = 0; m < 4; ++m) _Pragma("unroll") for (int k = 0; k < 2; ++k) dst[m][k] = *(const LAS bf16x8*)(lds + PG8_SA(b, h) + aoff + m * 2048 + k * 1024); } while (0)
; #define PG8_MMA(ai, bj, At, Bt) do { __builtin_amdgcn_s_setprio(1); _Pragma("unroll") for (int m = 0; m < 4; ++m) _Pragma("unroll") for (int n = 0; n < 2; ++n) _Pragma("unroll") for (int k = 0; k < 2; ++k) \
;         acc[ai][bj][m][n] = __builtin_amdgcn_mfma_f32_16x16x32_bf16(Bt[n][k], At[m][k], acc[ai][bj][m][n], 0, 0, 0); __builtin_amdgcn_s_setprio(0); } while (0)
; #define PG8_WAIT_V(n) asm volatile("s_waitcnt vmcnt(" #n ")" ::: "memory")
; #define PG8_WAIT_L(n) asm volatile("s_waitcnt lgkmcnt(" #n ")" ::: "memory")
; #define PG8_BAR __builtin_amdgcn_s_barrier()
; #define PG8_SCHED __builtin_amdgcn_sched_barrier(0)
; template <class Epi, bool ALIGN_EPI>
; __device__ __forceinline__ void gemm_phase(LAS unsigned char* lds, const Gemm g, const StaticOrder& S, const Epi& E, const int tid) {
;     ...
;             PG8_WAIT_V(8); PG8_WAIT_L(0); PG8_BAR; PG8_MMA(0, 0, At, B0); PG8_MMA(0, 1, At, B1); PG8_BAR; PG8_SCHED;
;             PG8_LDA(At, 1, 1); PG8_STAGE(PG8_SB(1, 0), b3, voffB); PG8_STAGE(PG8_SB(1, 1), b3 + hstepB, voffB); PG8_STAGE(PG8_SA(1, 0), a3, voffA);
	s_barrier
	s_add_u32 s54, s52, 0x8000
	s_addc_u32 s55, s53, 0
	s_add_i32 s89, s89, s61
	s_mov_b32 m0, s89
	ds_read_b128 v[184:187], v171 offset:49152
	ds_read_b128 v[188:191], v171 offset:50176
	ds_read_b128 v[192:195], v171 offset:51200
	ds_read_b128 v[196:199], v171 offset:52224


; #define PG8_STAGE(bufoff, gbase, voff) do { _Pragma("unroll") for (int _i = 0; _i < 2; ++_i) \
;         __builtin_amdgcn_global_load_lds((const unsigned*)((const char*)(gbase) + (voff)[_i]), (LAS unsigned*)(lds + (bufoff) + ldsw + _i * 8192), 16, 0, 0); } while (0)
; #define PG8_LDA(dst, b, h) do { _Pragma("unroll") for (int m = 0; m < 4; ++m) _Pragma("unroll") for (int k = 0; k < 2; ++k) dst[m][k] = *(const LAS bf16x8*)(lds + PG8_SA(b, h) + aoff + m * 2048 + k * 1024); } while (0)
; #define PG8_MMA(ai, bj, At, Bt) do { __builtin_amdgcn_s_setprio(1); _Pragma("unroll") for (int m = 0; m < 4; ++m) _Pragma("unroll") for (int n = 0; n < 2; ++n) _Pragma("unroll") for (int k = 0; k < 2; ++k) \
;         acc[ai][bj][m][n] = __builtin_amdgcn_mfma_f32_16x16x32_bf16(Bt[n][k], At[m][k], acc[ai][bj][m][n], 0, 0, 0); __builtin_amdgcn_s_setprio(0); } while (0)
; #define PG8_WAIT_V(n) asm volatile("s_waitcnt vmcnt(" #n ")" ::: "memory")
; #define PG8_WAIT_L(n) asm volatile("s_waitcnt lgkmcnt(" #n ")" ::: "memory")
; #define PG8_BAR __builtin_amdgcn_s_barrier()
; #define PG8_SCHED __builtin_amdgcn_sched_barrier(0)
; template <class Epi, bool ALIGN_EPI>
; __device__ __forceinline__ void gemm_phase(LAS unsigned char* lds, const Gemm g, const StaticOrder& S, const Epi& E, const int tid) {
;     ...
;             PG8_LDA(At, 1, 1); PG8_STAGE(PG8_SB(1, 0), b3, voffB); PG8_STAGE(PG8_SB(1, 1), b3 + hstepB, voffB); PG8_STAGE(PG8_SA(1, 0), a3, voffA);
;             PG8_WAIT_V(8); PG8_WAIT_L(0); PG8_BAR; PG8_MMA(1, 0, At, B0); PG8_MMA(1, 1, At, B1); PG8_BAR; PG8_SCHED;
	global_load_lds_dwordx4 v144, s[54:55]
	s_add_i32 m0, s89, 0x2000
	s_add_u32 s52, s52, 0xc000
	s_addc_u32 s53, s53, 0
	global_load_lds_dwordx4 v140, s[54:55]
	s_add_i32 s54, s90, s61
	s_mov_b32 m0, s54
	ds_read_b128 v[226:229], v171 offset:56320
	global_load_lds_dwordx4 v144, s[52:53]
	s_add_i32 m0, s54, 0x2000
	ds_read_b128 v[222:225], v171 offset:55296
	global_load_lds_dwordx4 v140, s[52:53]
	s_mov_b32 m0, s77
	ds_read_b128 v[218:221], v171 offset:54272
	global_load_lds_dwordx4 v146, s[50:51]
	s_mov_b32 m0, s78
	ds_read_b128 v[214:217], v171 offset:53248
	global_load_lds_dwordx4 v142, s[50:51]
	s_waitcnt vmcnt(8)
	s_waitcnt lgkmcnt(0)
	s_barrier


; #define PG8_MMA(ai, bj, At, Bt) do { __builtin_amdgcn_s_setprio(1); _Pragma("unroll") for (int m = 0; m < 4; ++m) _Pragma("unroll") for (int n = 0; n < 2; ++n) _Pragma("unroll") for (int k = 0; k < 2; ++k) \
;         acc[ai][bj][m][n] = __builtin_amdgcn_mfma_f32_16x16x32_bf16(Bt[n][k], At[m][k], acc[ai][bj][m][n], 0, 0, 0); __builtin_amdgcn_s_setprio(0); } while (0)
; #define PG8_WAIT_V(n) asm volatile("s_waitcnt vmcnt(" #n ")" ::: "memory")
; #define PG8_WAIT_L(n) asm volatile("s_waitcnt lgkmcnt(" #n ")" ::: "memory")
; #define PG8_BAR __builtin_amdgcn_s_barrier()
; #define PG8_SCHED __builtin_amdgcn_sched_barrier(0)
; template <class Epi, bool ALIGN_EPI>
; __device__ __forceinline__ void gemm_phase(LAS unsigned char* lds, const Gemm g, const StaticOrder& S, const Epi& E, const int tid) {
;     ...
;             PG8_WAIT_V(8); PG8_WAIT_L(0); PG8_BAR; PG8_MMA(1, 0, At, B0); PG8_MMA(1, 1, At, B1); PG8_BAR; PG8_SCHED;
	v_mfma_f32_16x16x32_bf16 v[84:87], v[132:135], v[184:187], v[84:87]
	v_mfma_f32_16x16x32_bf16 v[72:75], v[132:135], v[192:195], v[72:75]
	v_mfma_f32_16x16x32_bf16 v[44:47], v[152:155], v[192:195], v[44:47]
	v_mfma_f32_16x16x32_bf16 v[56:59], v[152:155], v[184:187], v[56:59]
	v_mfma_f32_16x16x32_bf16 v[64:67], v[132:135], v[214:217], v[64:67]
	v_mfma_f32_16x16x32_bf16 v[52:55], v[132:135], v[222:225], v[52:55]
	v_mfma_f32_16x16x32_bf16 v[28:31], v[152:155], v[222:225], v[28:31]
	v_mfma_f32_16x16x32_bf16 v[36:39], v[152:155], v[214:217], v[36:39]
	v_mfma_f32_16x16x32_bf16 v[84:87], v[136:139], v[188:191], v[84:87]
	v_mfma_f32_16x16x32_bf16 v[72:75], v[136:139], v[196:199], v[72:75]
	v_mfma_f32_16x16x32_bf16 v[44:47], v[156:159], v[196:199], v[44:47]
	v_mfma_f32_16x16x32_bf16 v[56:59], v[156:159], v[188:191], v[56:59]
	v_mfma_f32_16x16x32_bf16 v[64:67], v[136:139], v[218:221], v[64:67]
	v_mfma_f32_16x16x32_bf16 v[52:55], v[136:139], v[226:229], v[52:55]
	v_mfma_f32_16x16x32_bf16 v[28:31], v[156:159], v[226:229], v[28:31]
	v_mfma_f32_16x16x32_bf16 v[36:39], v[156:159], v[218:221], v[36:39]


; #define PG8_MMA(ai, bj, At, Bt) do { __builtin_amdgcn_s_setprio(1); _Pragma("unroll") for (int m = 0; m < 4; ++m) _Pragma("unroll") for (int n = 0; n < 2; ++n) _Pragma("unroll") for (int k = 0; k < 2; ++k) \
;         acc[ai][bj][m][n] = __builtin_amdgcn_mfma_f32_16x16x32_bf16(Bt[n][k], At[m][k], acc[ai][bj][m][n], 0, 0, 0); __builtin_amdgcn_s_setprio(0); } while (0)
; #define PG8_WAIT_V(n) asm volatile("s_waitcnt vmcnt(" #n ")" ::: "memory")
; #define PG8_WAIT_L(n) asm volatile("s_waitcnt lgkmcnt(" #n ")" ::: "memory")
; #define PG8_BAR __builtin_amdgcn_s_barrier()
; #define PG8_SCHED __builtin_amdgcn_sched_barrier(0)
; template <class Epi, bool ALIGN_EPI>
; __device__ __forceinline__ void gemm_phase(LAS unsigned char* lds, const Gemm g, const StaticOrder& S, const Epi& E, const int tid) {
;     ...
;             PG8_WAIT_V(8); PG8_WAIT_L(0); PG8_BAR; PG8_MMA(1, 0, At, B0); PG8_MMA(1, 1, At, B1); PG8_BAR; PG8_SCHED;
	v_mfma_f32_16x16x32_bf16 v[40:43], v[160:163], v[184:187], v[40:43]
	v_mfma_f32_16x16x32_bf16 v[32:35], v[160:163], v[192:195], v[32:35]
	v_mfma_f32_16x16x32_bf16 v[12:15], v[176:179], v[192:195], v[12:15]
	v_mfma_f32_16x16x32_bf16 v[20:23], v[176:179], v[184:187], v[20:23]
	v_mfma_f32_16x16x32_bf16 v[24:27], v[160:163], v[214:217], v[24:27]
	v_mfma_f32_16x16x32_bf16 v[16:19], v[160:163], v[222:225], v[16:19]
	v_mfma_f32_16x16x32_bf16 v[2:5], v[176:179], v[222:225], v[2:5]
	v_mfma_f32_16x16x32_bf16 v[6:9], v[176:179], v[214:217], v[8:11]
	v_mfma_f32_16x16x32_bf16 v[40:43], v[172:175], v[188:191], v[40:43]
	v_mfma_f32_16x16x32_bf16 v[32:35], v[172:175], v[196:199], v[32:35]
	v_mfma_f32_16x16x32_bf16 v[20:23], v[180:183], v[188:191], v[20:23]
	v_mfma_f32_16x16x32_bf16 v[12:15], v[180:183], v[196:199], v[12:15]
	v_mfma_f32_16x16x32_bf16 v[24:27], v[172:175], v[218:221], v[24:27]
	v_mfma_f32_16x16x32_bf16 v[16:19], v[172:175], v[226:229], v[16:19]
	v_mfma_f32_16x16x32_bf16 v[8:11], v[180:183], v[218:221], v[6:9]
	v_mfma_f32_16x16x32_bf16 v[4:7], v[180:183], v[226:229], v[2:5]

; #define PG8_MMA(ai, bj, At, Bt) do { __builtin_amdgcn_s_setprio(1); _Pragma("unroll") for (int m = 0; m < 4; ++m) _Pragma("unroll") for (int n = 0; n < 2; ++n) _Pragma("unroll") for (int k = 0; k < 2; ++k) \
;         acc[ai][bj][m][n] = __builtin_amdgcn_mfma_f32_16x16x32_bf16(Bt[n][k], At[m][k], acc[ai][bj][m][n], 0, 0, 0); __builtin_amdgcn_s_setprio(0); } while (0)
; #define PG8_WAIT_V(n) asm volatile("s_waitcnt vmcnt(" #n ")" ::: "memory")
; #define PG8_WAIT_L(n) asm volatile("s_waitcnt lgkmcnt(" #n ")" ::: "memory")
; #define PG8_BAR __builtin_amdgcn_s_barrier()
; #define PG8_SCHED __builtin_amdgcn_sched_barrier(0)
; template <class Epi, bool ALIGN_EPI>
; __device__ __forceinline__ void gemm_phase(LAS unsigned char* lds, const Gemm g, const StaticOrder& S, const Epi& E, const int tid) {
;     ...
;             PG8_WAIT_V(8); PG8_WAIT_L(0); PG8_BAR; PG8_MMA(1, 0, At, B0); PG8_MMA(1, 1, At, B1); PG8_BAR; PG8_SCHED;
;         }
;         if constexpr (ALIGN_EPI) { if (wr == 0) PG8_BAR; }
	s_barrier
	s_add_i32 s88, s88, 2
	s_add_u32 s48, s48, 0x10000
	s_addc_u32 s49, s49, 0
	s_add_u32 s86, s86, 0x10000
	s_addc_u32 s87, s87, 0
	s_cmp_gt_u32 s88, 29
	s_cbranch_scc0 .LBB0_385
	s_and_b64 vcc, exec, s[34:35]
	s_cbranch_vccz .LBB0_388
	s_barrier

; #define PG8_STAGE(bufoff, gbase, voff) do { _Pragma("unroll") for (int _i = 0; _i < 2; ++_i) \
;         __builtin_amdgcn_global_load_lds((const unsigned*)((const char*)(gbase) + (voff)[_i]), (LAS unsigned*)(lds + (bufoff) + ldsw + _i * 8192), 16, 0, 0); } while (0)
; #define PG8_LDA(dst, b, h) do { _Pragma("unroll") for (int m = 0; m < 4; ++m) _Pragma("unroll") for (int k = 0; k < 2; ++k) dst[m][k] = *(const LAS bf16x8*)(lds + PG8_SA(b, h) + aoff + m * 2048 + k * 1024); } while (0)
; #define PG8_LDB(dst, b, h) do { _Pragma("unroll") for (int n = 0; n < 2; ++n) _Pragma("unroll") for (int k = 0; k < 2; ++k) dst[n][k] = *(const LAS bf16x8*)(lds + PG8_SB(b, h) + boff + n * 2048 + k * 1024); } while (0)
; #define PG8_SCHED __builtin_amdgcn_sched_barrier(0)
; template <class Epi, bool ALIGN_EPI>
; __device__ __forceinline__ void gemm_phase(LAS unsigned char* lds, const Gemm g, const StaticOrder& S, const Epi& E, const int tid) {
;     ...
;             const bool last = (t == nt - 2);
;             const char* a1 = cA + (size_t)(t + 1) * kstepA;
;             const char* a2 = last ? nA : cA + (size_t)(t + 2) * kstepA; const char* b2 = last ? nB : cB + (size_t)(t + 2) * kstepB;
;             const char* a3 = a2 + kstepA; const char* b3 = b2 + kstepB;
;             PG8_LDB(B0, 0, 0); PG8_LDB(B1, 0, 1); PG8_SCHED; PG8_LDA(At, 0, 0); PG8_STAGE(PG8_SA(1, 1), a1 + hstepA, voffA);
.LBB0_847:
	s_add_u32 s22, s10, 0xfff80080
	s_addc_u32 s23, s11, -1
	s_add_i32 s87, 0, 0x10000
	s_cmp_eq_u32 s86, 28
	s_cselect_b32 s35, s49, s23
	s_cselect_b32 s34, s82, s22
	v_add_u32_e32 v0, s87, v154
	s_cselect_b32 s23, s47, s85
	s_cselect_b32 s22, s83, s84
	s_add_i32 s90, 0, 0x14000
	s_waitcnt lgkmcnt(0)
	ds_read_b128 v[132:135], v0
	ds_read_b128 v[148:151], v0 offset:1024
	ds_read_b128 v[156:159], v0 offset:2048
	ds_read_b128 v[160:163], v0 offset:3072
	v_add_u32_e32 v0, s90, v154
	ds_read_b128 v[164:167], v0
	ds_read_b128 v[168:171], v0 offset:1024
	ds_read_b128 v[172:175], v0 offset:2048
	ds_read_b128 v[176:179], v0 offset:3072
	s_add_i32 m0, s70, 0xc000
	ds_read_b128 v[180:183], v155
	ds_read_b128 v[184:187], v155 offset:1024
	ds_read_b128 v[188:191], v155 offset:2048
	ds_read_b128 v[192:195], v155 offset:3072
	ds_read_b128 v[196:199], v155 offset:4096
	ds_read_b128 v[214:217], v155 offset:5120
	ds_read_b128 v[218:221], v155 offset:6144

; #define PG8_STAGE(bufoff, gbase, voff) do { _Pragma("unroll") for (int _i = 0; _i < 2; ++_i) \
;         __builtin_amdgcn_global_load_lds((const unsigned*)((const char*)(gbase) + (voff)[_i]), (LAS unsigned*)(lds + (bufoff) + ldsw + _i * 8192), 16, 0, 0); } while (0)
; #define PG8_LDA(dst, b, h) do { _Pragma("unroll") for (int m = 0; m < 4; ++m) _Pragma("unroll") for (int k = 0; k < 2; ++k) dst[m][k] = *(const LAS bf16x8*)(lds + PG8_SA(b, h) + aoff + m * 2048 + k * 1024); } while (0)
; #define PG8_LDB(dst, b, h) do { _Pragma("unroll") for (int n = 0; n < 2; ++n) _Pragma("unroll") for (int k = 0; k < 2; ++k) dst[n][k] = *(const LAS bf16x8*)(lds + PG8_SB(b, h) + boff + n * 2048 + k * 1024); } while (0)
; #define PG8_MMA(ai, bj, At, Bt) do { __builtin_amdgcn_s_setprio(1); _Pragma("unroll") for (int m = 0; m < 4; ++m) _Pragma("unroll") for (int n = 0; n < 2; ++n) _Pragma("unroll") for (int k = 0; k < 2; ++k) \
;         acc[ai][bj][m][n] = __builtin_amdgcn_mfma_f32_16x16x32_bf16(Bt[n][k], At[m][k], acc[ai][bj][m][n], 0, 0, 0); __builtin_amdgcn_s_setprio(0); } while (0)
; #define PG8_WAIT_V(n) asm volatile("s_waitcnt vmcnt(" #n ")" ::: "memory")
; #define PG8_WAIT_L(n) asm volatile("s_waitcnt lgkmcnt(" #n ")" ::: "memory")
; #define PG8_BAR __builtin_amdgcn_s_barrier()
; #define PG8_SCHED __builtin_amdgcn_sched_barrier(0)
; template <class Epi, bool ALIGN_EPI>
; __device__ __forceinline__ void gemm_phase(LAS unsigned char* lds, const Gemm g, const StaticOrder& S, const Epi& E, const int tid) {
;     ...
;             PG8_LDB(B0, 0, 0); PG8_LDB(B1, 0, 1); PG8_SCHED; PG8_LDA(At, 0, 0); PG8_STAGE(PG8_SA(1, 1), a1 + hstepA, voffA);
;             PG8_WAIT_V(8); PG8_WAIT_L(0); PG8_BAR; PG8_MMA(0, 0, At, B0); PG8_MMA(0, 1, At, B1); PG8_BAR; PG8_SCHED;
	global_load_lds_dwordx4 v144, s[10:11]
	s_add_i32 m0, s70, 0xe000
	ds_read_b128 v[222:225], v155 offset:7168
	global_load_lds_dwordx4 v146, s[10:11]
	s_waitcnt vmcnt(8)
	s_waitcnt lgkmcnt(0)
	s_barrier


; #define PG8_MMA(ai, bj, At, Bt) do { __builtin_amdgcn_s_setprio(1); _Pragma("unroll") for (int m = 0; m < 4; ++m) _Pragma("unroll") for (int n = 0; n < 2; ++n) _Pragma("unroll") for (int k = 0; k < 2; ++k) \
;         acc[ai][bj][m][n] = __builtin_amdgcn_mfma_f32_16x16x32_bf16(Bt[n][k], At[m][k], acc[ai][bj][m][n], 0, 0, 0); __builtin_amdgcn_s_setprio(0); } while (0)
; #define PG8_WAIT_V(n) asm volatile("s_waitcnt vmcnt(" #n ")" ::: "memory")
; #define PG8_WAIT_L(n) asm volatile("s_waitcnt lgkmcnt(" #n ")" ::: "memory")
; #define PG8_BAR __builtin_amdgcn_s_barrier()
; #define PG8_SCHED __builtin_amdgcn_sched_barrier(0)
; template <class Epi, bool ALIGN_EPI>
; __device__ __forceinline__ void gemm_phase(LAS unsigned char* lds, const Gemm g, const StaticOrder& S, const Epi& E, const int tid) {
;     ...
;             PG8_WAIT_V(8); PG8_WAIT_L(0); PG8_BAR; PG8_MMA(0, 0, At, B0); PG8_MMA(0, 1, At, B1); PG8_BAR; PG8_SCHED;
	v_mfma_f32_16x16x32_bf16 v[8:11], v[132:135], v[180:183], v[8:11]
	v_mfma_f32_16x16x32_bf16 v[52:55], v[132:135], v[188:191], v[52:55]
	v_mfma_f32_16x16x32_bf16 v[48:51], v[156:159], v[188:191], v[48:51]
	v_mfma_f32_16x16x32_bf16 v[56:59], v[156:159], v[180:183], v[56:59]
	v_mfma_f32_16x16x32_bf16 v[44:47], v[132:135], v[196:199], v[44:47]
	v_mfma_f32_16x16x32_bf16 v[36:39], v[132:135], v[218:221], v[36:39]
	v_mfma_f32_16x16x32_bf16 v[32:35], v[156:159], v[218:221], v[32:35]
	v_mfma_f32_16x16x32_bf16 v[40:43], v[156:159], v[196:199], v[40:43]
	v_mfma_f32_16x16x32_bf16 v[8:11], v[148:151], v[184:187], v[8:11]
	v_mfma_f32_16x16x32_bf16 v[52:55], v[148:151], v[192:195], v[52:55]
	v_mfma_f32_16x16x32_bf16 v[48:51], v[160:163], v[192:195], v[48:51]
	v_mfma_f32_16x16x32_bf16 v[56:59], v[160:163], v[184:187], v[56:59]
	v_mfma_f32_16x16x32_bf16 v[44:47], v[148:151], v[214:217], v[44:47]
	v_mfma_f32_16x16x32_bf16 v[36:39], v[148:151], v[222:225], v[36:39]
	v_mfma_f32_16x16x32_bf16 v[32:35], v[160:163], v[222:225], v[32:35]
	v_mfma_f32_16x16x32_bf16 v[40:43], v[160:163], v[214:217], v[40:43]


; #define PG8_MMA(ai, bj, At, Bt) do { __builtin_amdgcn_s_setprio(1); _Pragma("unroll") for (int m = 0; m < 4; ++m) _Pragma("unroll") for (int n = 0; n < 2; ++n) _Pragma("unroll") for (int k = 0; k < 2; ++k) \
;         acc[ai][bj][m][n] = __builtin_amdgcn_mfma_f32_16x16x32_bf16(Bt[n][k], At[m][k], acc[ai][bj][m][n], 0, 0, 0); __builtin_amdgcn_s_setprio(0); } while (0)
; #define PG8_WAIT_V(n) asm volatile("s_waitcnt vmcnt(" #n ")" ::: "memory")
; #define PG8_WAIT_L(n) asm volatile("s_waitcnt lgkmcnt(" #n ")" ::: "memory")
; #define PG8_BAR __builtin_amdgcn_s_barrier()
; #define PG8_SCHED __builtin_amdgcn_sched_barrier(0)
; template <class Epi, bool ALIGN_EPI>
; __device__ __forceinline__ void gemm_phase(LAS unsigned char* lds, const Gemm g, const StaticOrder& S, const Epi& E, const int tid) {
;     ...
;             PG8_WAIT_V(8); PG8_WAIT_L(0); PG8_BAR; PG8_MMA(0, 0, At, B0); PG8_MMA(0, 1, At, B1); PG8_BAR; PG8_SCHED;
	v_mfma_f32_16x16x32_bf16 v[2:5], v[164:167], v[180:183], v[4:7]
	v_mfma_f32_16x16x32_bf16 v[96:99], v[164:167], v[188:191], v[96:99]
	v_mfma_f32_16x16x32_bf16 v[92:95], v[172:175], v[188:191], v[92:95]
	v_mfma_f32_16x16x32_bf16 v[28:31], v[172:175], v[180:183], v[28:31]
	v_mfma_f32_16x16x32_bf16 v[88:91], v[164:167], v[196:199], v[88:91]
	v_mfma_f32_16x16x32_bf16 v[80:83], v[164:167], v[218:221], v[80:83]
	v_mfma_f32_16x16x32_bf16 v[76:79], v[172:175], v[218:221], v[76:79]
	v_mfma_f32_16x16x32_bf16 v[84:87], v[172:175], v[196:199], v[84:87]
	v_mfma_f32_16x16x32_bf16 v[2:5], v[168:171], v[184:187], v[2:5]
	v_mfma_f32_16x16x32_bf16 v[96:99], v[168:171], v[192:195], v[96:99]
	v_mfma_f32_16x16x32_bf16 v[92:95], v[176:179], v[192:195], v[92:95]
	v_mfma_f32_16x16x32_bf16 v[28:31], v[176:179], v[184:187], v[28:31]
	v_mfma_f32_16x16x32_bf16 v[88:91], v[168:171], v[214:217], v[88:91]
	v_mfma_f32_16x16x32_bf16 v[80:83], v[168:171], v[222:225], v[80:83]
	v_mfma_f32_16x16x32_bf16 v[76:79], v[176:179], v[222:225], v[76:79]
	v_mfma_f32_16x16x32_bf16 v[84:87], v[176:179], v[214:217], v[84:87]

; #define PG8_STAGE(bufoff, gbase, voff) do { _Pragma("unroll") for (int _i = 0; _i < 2; ++_i) \
;         __builtin_amdgcn_global_load_lds((const unsigned*)((const char*)(gbase) + (voff)[_i]), (LAS unsigned*)(lds + (bufoff) + ldsw + _i * 8192), 16, 0, 0); } while (0)
; #define PG8_LDA(dst, b, h) do { _Pragma("unroll") for (int m = 0; m < 4; ++m) _Pragma("unroll") for (int k = 0; k < 2; ++k) dst[m][k] = *(const LAS bf16x8*)(lds + PG8_SA(b, h) + aoff + m * 2048 + k * 1024); } while (0)
; #define PG8_MMA(ai, bj, At, Bt) do { __builtin_amdgcn_s_setprio(1); _Pragma("unroll") for (int m = 0; m < 4; ++m) _Pragma("unroll") for (int n = 0; n < 2; ++n) _Pragma("unroll") for (int k = 0; k < 2; ++k) \
;         acc[ai][bj][m][n] = __builtin_amdgcn_mfma_f32_16x16x32_bf16(Bt[n][k], At[m][k], acc[ai][bj][m][n], 0, 0, 0); __builtin_amdgcn_s_setprio(0); } while (0)
; #define PG8_WAIT_V(n) asm volatile("s_waitcnt vmcnt(" #n ")" ::: "memory")
; #define PG8_WAIT_L(n) asm volatile("s_waitcnt lgkmcnt(" #n ")" ::: "memory")
; #define PG8_BAR __builtin_amdgcn_s_barrier()
; #define PG8_SCHED __builtin_amdgcn_sched_barrier(0)
; template <class Epi, bool ALIGN_EPI>
; __device__ __forceinline__ void gemm_phase(LAS unsigned char* lds, const Gemm g, const StaticOrder& S, const Epi& E, const int tid) {
;     ...
;             PG8_WAIT_V(8); PG8_WAIT_L(0); PG8_BAR; PG8_MMA(0, 0, At, B0); PG8_MMA(0, 1, At, B1); PG8_BAR; PG8_SCHED;
;             PG8_LDA(At, 0, 1); PG8_STAGE(PG8_SB(0, 0), b2, voffB); PG8_STAGE(PG8_SB(0, 1), b2 + hstepB, voffB); PG8_STAGE(PG8_SA(0, 0), a2, voffA);
	s_barrier
	s_add_i32 s87, s87, s61
	s_mov_b32 m0, s87
	ds_read_b128 v[180:183], v155 offset:16384
	ds_read_b128 v[184:187], v155 offset:17408
	ds_read_b128 v[188:191], v155 offset:18432
	ds_read_b128 v[192:195], v155 offset:19456
	ds_read_b128 v[196:199], v155 offset:20480
	ds_read_b128 v[214:217], v155 offset:21504


; #define PG8_STAGE(bufoff, gbase, voff) do { _Pragma("unroll") for (int _i = 0; _i < 2; ++_i) \
;         __builtin_amdgcn_global_load_lds((const unsigned*)((const char*)(gbase) + (voff)[_i]), (LAS unsigned*)(lds + (bufoff) + ldsw + _i * 8192), 16, 0, 0); } while (0)
; #define PG8_LDA(dst, b, h) do { _Pragma("unroll") for (int m = 0; m < 4; ++m) _Pragma("unroll") for (int k = 0; k < 2; ++k) dst[m][k] = *(const LAS bf16x8*)(lds + PG8_SA(b, h) + aoff + m * 2048 + k * 1024); } while (0)
; #define PG8_MMA(ai, bj, At, Bt) do { __builtin_amdgcn_s_setprio(1); _Pragma("unroll") for (int m = 0; m < 4; ++m) _Pragma("unroll") for (int n = 0; n < 2; ++n) _Pragma("unroll") for (int k = 0; k < 2; ++k) \
;         acc[ai][bj][m][n] = __builtin_amdgcn_mfma_f32_16x16x32_bf16(Bt[n][k], At[m][k], acc[ai][bj][m][n], 0, 0, 0); __builtin_amdgcn_s_setprio(0); } while (0)
; #define PG8_WAIT_V(n) asm volatile("s_waitcnt vmcnt(" #n ")" ::: "memory")
; #define PG8_WAIT_L(n) asm volatile("s_waitcnt lgkmcnt(" #n ")" ::: "memory")
; #define PG8_BAR __builtin_amdgcn_s_barrier()
; #define PG8_SCHED __builtin_amdgcn_sched_barrier(0)
; template <class Epi, bool ALIGN_EPI>
; __device__ __forceinline__ void gemm_phase(LAS unsigned char* lds, const Gemm g, const StaticOrder& S, const Epi& E, const int tid) {
;     ...
;             PG8_LDA(At, 0, 1); PG8_STAGE(PG8_SB(0, 0), b2, voffB); PG8_STAGE(PG8_SB(0, 1), b2 + hstepB, voffB); PG8_STAGE(PG8_SA(0, 0), a2, voffA);
;             PG8_WAIT_V(8); PG8_WAIT_L(0); PG8_BAR; PG8_MMA(1, 0, At, B0); PG8_MMA(1, 1, At, B1); PG8_BAR; PG8_SCHED;
	global_load_lds_dwordx4 v140, s[22:23]
	s_add_i32 m0, s87, 0x2000
	s_add_u32 s88, s22, 0x4000
	s_addc_u32 s89, s23, 0
	s_add_i32 s87, s90, s61
	global_load_lds_dwordx4 v136, s[22:23]
	s_mov_b32 m0, s87
	v_lshl_add_u64 v[152:153], s[34:35], 0, v[142:143]
	global_load_lds_dwordx4 v140, s[88:89]
	s_add_i32 m0, s87, 0x2000
	v_lshl_add_u64 v[200:201], s[34:35], 0, v[138:139]
	global_load_lds_dwordx4 v136, s[88:89]
	s_mov_b32 m0, s70
	ds_read_b128 v[222:225], v155 offset:23552
	global_load_lds_dwordx4 v[152:153], off
	s_mov_b32 m0, s71
	ds_read_b128 v[218:221], v155 offset:22528
	global_load_lds_dwordx4 v[200:201], off
	s_waitcnt vmcnt(8)
	s_waitcnt lgkmcnt(0)
	s_barrier


; #define PG8_MMA(ai, bj, At, Bt) do { __builtin_amdgcn_s_setprio(1); _Pragma("unroll") for (int m = 0; m < 4; ++m) _Pragma("unroll") for (int n = 0; n < 2; ++n) _Pragma("unroll") for (int k = 0; k < 2; ++k) \
;         acc[ai][bj][m][n] = __builtin_amdgcn_mfma_f32_16x16x32_bf16(Bt[n][k], At[m][k], acc[ai][bj][m][n], 0, 0, 0); __builtin_amdgcn_s_setprio(0); } while (0)
; #define PG8_WAIT_V(n) asm volatile("s_waitcnt vmcnt(" #n ")" ::: "memory")
; #define PG8_WAIT_L(n) asm volatile("s_waitcnt lgkmcnt(" #n ")" ::: "memory")
; #define PG8_BAR __builtin_amdgcn_s_barrier()
; #define PG8_SCHED __builtin_amdgcn_sched_barrier(0)
; template <class Epi, bool ALIGN_EPI>
; __device__ __forceinline__ void gemm_phase(LAS unsigned char* lds, const Gemm g, const StaticOrder& S, const Epi& E, const int tid) {
;     ...
;             PG8_WAIT_V(8); PG8_WAIT_L(0); PG8_BAR; PG8_MMA(1, 0, At, B0); PG8_MMA(1, 1, At, B1); PG8_BAR; PG8_SCHED;
	v_mfma_f32_16x16x32_bf16 v[24:27], v[132:135], v[180:183], v[24:27]
	v_mfma_f32_16x16x32_bf16 v[64:67], v[132:135], v[188:191], v[64:67]
	v_mfma_f32_16x16x32_bf16 v[72:75], v[156:159], v[188:191], v[72:75]
	v_mfma_f32_16x16x32_bf16 v[20:23], v[156:159], v[180:183], v[20:23]
	v_mfma_f32_16x16x32_bf16 v[16:19], v[132:135], v[196:199], v[16:19]
	v_mfma_f32_16x16x32_bf16 v[60:63], v[132:135], v[218:221], v[60:63]
	v_mfma_f32_16x16x32_bf16 v[68:71], v[156:159], v[218:221], v[68:71]
	v_mfma_f32_16x16x32_bf16 v[12:15], v[156:159], v[196:199], v[12:15]
	v_mfma_f32_16x16x32_bf16 v[24:27], v[148:151], v[184:187], v[24:27]
	v_mfma_f32_16x16x32_bf16 v[64:67], v[148:151], v[192:195], v[64:67]
	v_mfma_f32_16x16x32_bf16 v[72:75], v[160:163], v[192:195], v[72:75]
	v_mfma_f32_16x16x32_bf16 v[20:23], v[160:163], v[184:187], v[20:23]
	v_mfma_f32_16x16x32_bf16 v[16:19], v[148:151], v[214:217], v[16:19]
	v_mfma_f32_16x16x32_bf16 v[60:63], v[148:151], v[222:225], v[60:63]
	v_mfma_f32_16x16x32_bf16 v[68:71], v[160:163], v[222:225], v[68:71]
	v_mfma_f32_16x16x32_bf16 v[12:15], v[160:163], v[214:217], v[12:15]


; #define PG8_MMA(ai, bj, At, Bt) do { __builtin_amdgcn_s_setprio(1); _Pragma("unroll") for (int m = 0; m < 4; ++m) _Pragma("unroll") for (int n = 0; n < 2; ++n) _Pragma("unroll") for (int k = 0; k < 2; ++k) \
;         acc[ai][bj][m][n] = __builtin_amdgcn_mfma_f32_16x16x32_bf16(Bt[n][k], At[m][k], acc[ai][bj][m][n], 0, 0, 0); __builtin_amdgcn_s_setprio(0); } while (0)
; #define PG8_WAIT_V(n) asm volatile("s_waitcnt vmcnt(" #n ")" ::: "memory")
; #define PG8_WAIT_L(n) asm volatile("s_waitcnt lgkmcnt(" #n ")" ::: "memory")
; #define PG8_BAR __builtin_amdgcn_s_barrier()
; #define PG8_SCHED __builtin_amdgcn_sched_barrier(0)
; template <class Epi, bool ALIGN_EPI>
; __device__ __forceinline__ void gemm_phase(LAS unsigned char* lds, const Gemm g, const StaticOrder& S, const Epi& E, const int tid) {
;     ...
;             PG8_WAIT_V(8); PG8_WAIT_L(0); PG8_BAR; PG8_MMA(1, 0, At, B0); PG8_MMA(1, 1, At, B1); PG8_BAR; PG8_SCHED;
	v_mfma_f32_16x16x32_bf16 v[128:131], v[164:167], v[180:183], v[128:131]
	v_mfma_f32_16x16x32_bf16 v[120:123], v[164:167], v[188:191], v[120:123]
	v_mfma_f32_16x16x32_bf16 v[116:119], v[172:175], v[188:191], v[116:119]
	v_mfma_f32_16x16x32_bf16 v[124:127], v[172:175], v[180:183], v[124:127]
	v_mfma_f32_16x16x32_bf16 v[112:115], v[164:167], v[196:199], v[112:115]
	v_mfma_f32_16x16x32_bf16 v[104:107], v[164:167], v[218:221], v[104:107]
	v_mfma_f32_16x16x32_bf16 v[100:103], v[172:175], v[218:221], v[100:103]
	v_mfma_f32_16x16x32_bf16 v[108:111], v[172:175], v[196:199], v[108:111]
	v_mfma_f32_16x16x32_bf16 v[128:131], v[168:171], v[184:187], v[128:131]
	v_mfma_f32_16x16x32_bf16 v[120:123], v[168:171], v[192:195], v[120:123]
	v_mfma_f32_16x16x32_bf16 v[116:119], v[176:179], v[192:195], v[116:119]
	v_mfma_f32_16x16x32_bf16 v[124:127], v[176:179], v[184:187], v[124:127]
	v_mfma_f32_16x16x32_bf16 v[112:115], v[168:171], v[214:217], v[112:115]
	v_mfma_f32_16x16x32_bf16 v[104:107], v[168:171], v[222:225], v[104:107]
	v_mfma_f32_16x16x32_bf16 v[100:103], v[176:179], v[222:225], v[100:103]
	v_mfma_f32_16x16x32_bf16 v[108:111], v[176:179], v[214:217], v[108:111]

; #define PG8_STAGE(bufoff, gbase, voff) do { _Pragma("unroll") for (int _i = 0; _i < 2; ++_i) \
;         __builtin_amdgcn_global_load_lds((const unsigned*)((const char*)(gbase) + (voff)[_i]), (LAS unsigned*)(lds + (bufoff) + ldsw + _i * 8192), 16, 0, 0); } while (0)
; #define PG8_LDA(dst, b, h) do { _Pragma("unroll") for (int m = 0; m < 4; ++m) _Pragma("unroll") for (int k = 0; k < 2; ++k) dst[m][k] = *(const LAS bf16x8*)(lds + PG8_SA(b, h) + aoff + m * 2048 + k * 1024); } while (0)
; #define PG8_LDB(dst, b, h) do { _Pragma("unroll") for (int n = 0; n < 2; ++n) _Pragma("unroll") for (int k = 0; k < 2; ++k) dst[n][k] = *(const LAS bf16x8*)(lds + PG8_SB(b, h) + boff + n * 2048 + k * 1024); } while (0)
; #define PG8_SCHED __builtin_amdgcn_sched_barrier(0)
; template <class Epi, bool ALIGN_EPI>
; __device__ __forceinline__ void gemm_phase(LAS unsigned char* lds, const Gemm g, const StaticOrder& S, const Epi& E, const int tid) {
;     ...
;             PG8_LDB(B0, 1, 0); PG8_LDB(B1, 1, 1); PG8_SCHED; PG8_LDA(At, 1, 0); PG8_STAGE(PG8_SA(0, 1), a2 + hstepA, voffA);
	s_barrier
	s_add_i32 s87, 0, 0x18000
	v_add_u32_e32 v0, s87, v154
	s_add_i32 s88, 0, 0x1c000
	ds_read_b128 v[132:135], v0
	ds_read_b128 v[148:151], v0 offset:1024
	ds_read_b128 v[156:159], v0 offset:2048
	ds_read_b128 v[160:163], v0 offset:3072
	v_add_u32_e32 v0, s88, v154
	ds_read_b128 v[164:167], v0
	ds_read_b128 v[168:171], v0 offset:1024
	ds_read_b128 v[172:175], v0 offset:2048
	ds_read_b128 v[176:179], v0 offset:3072
	s_add_u32 s34, s34, 0x80000
	s_addc_u32 s35, s35, 0
	s_mov_b32 m0, s72
	ds_read_b128 v[180:183], v155 offset:32768
	ds_read_b128 v[184:187], v155 offset:33792
	ds_read_b128 v[188:191], v155 offset:34816
	ds_read_b128 v[192:195], v155 offset:35840
	ds_read_b128 v[196:199], v155 offset:36864
	ds_read_b128 v[214:217], v155 offset:37888
	ds_read_b128 v[218:221], v155 offset:38912

; #define PG8_STAGE(bufoff, gbase, voff) do { _Pragma("unroll") for (int _i = 0; _i < 2; ++_i) \
;         __builtin_amdgcn_global_load_lds((const unsigned*)((const char*)(gbase) + (voff)[_i]), (LAS unsigned*)(lds + (bufoff) + ldsw + _i * 8192), 16, 0, 0); } while (0)
; #define PG8_LDA(dst, b, h) do { _Pragma("unroll") for (int m = 0; m < 4; ++m) _Pragma("unroll") for (int k = 0; k < 2; ++k) dst[m][k] = *(const LAS bf16x8*)(lds + PG8_SA(b, h) + aoff + m * 2048 + k * 1024); } while (0)
; #define PG8_LDB(dst, b, h) do { _Pragma("unroll") for (int n = 0; n < 2; ++n) _Pragma("unroll") for (int k = 0; k < 2; ++k) dst[n][k] = *(const LAS bf16x8*)(lds + PG8_SB(b, h) + boff + n * 2048 + k * 1024); } while (0)
; #define PG8_MMA(ai, bj, At, Bt) do { __builtin_amdgcn_s_setprio(1); _Pragma("unroll") for (int m = 0; m < 4; ++m) _Pragma("unroll") for (int n = 0; n < 2; ++n) _Pragma("unroll") for (int k = 0; k < 2; ++k) \
;         acc[ai][bj][m][n] = __builtin_amdgcn_mfma_f32_16x16x32_bf16(Bt[n][k], At[m][k], acc[ai][bj][m][n], 0, 0, 0); __builtin_amdgcn_s_setprio(0); } while (0)
; #define PG8_WAIT_V(n) asm volatile("s_waitcnt vmcnt(" #n ")" ::: "memory")
; #define PG8_WAIT_L(n) asm volatile("s_waitcnt lgkmcnt(" #n ")" ::: "memory")
; #define PG8_BAR __builtin_amdgcn_s_barrier()
; #define PG8_SCHED __builtin_amdgcn_sched_barrier(0)
; template <class Epi, bool ALIGN_EPI>
; __device__ __forceinline__ void gemm_phase(LAS unsigned char* lds, const Gemm g, const StaticOrder& S, const Epi& E, const int tid) {
;     ...
;             PG8_LDB(B0, 1, 0); PG8_LDB(B1, 1, 1); PG8_SCHED; PG8_LDA(At, 1, 0); PG8_STAGE(PG8_SA(0, 1), a2 + hstepA, voffA);
;             PG8_WAIT_V(8); PG8_WAIT_L(0); PG8_BAR; PG8_MMA(0, 0, At, B0); PG8_MMA(0, 1, At, B1); PG8_BAR; PG8_SCHED;
	global_load_lds_dwordx4 v142, s[34:35]
	s_mov_b32 m0, s73
	ds_read_b128 v[222:225], v155 offset:39936
	global_load_lds_dwordx4 v138, s[34:35]
	s_waitcnt vmcnt(8)
	s_waitcnt lgkmcnt(0)
	s_barrier


; #define PG8_MMA(ai, bj, At, Bt) do { __builtin_amdgcn_s_setprio(1); _Pragma("unroll") for (int m = 0; m < 4; ++m) _Pragma("unroll") for (int n = 0; n < 2; ++n) _Pragma("unroll") for (int k = 0; k < 2; ++k) \
;         acc[ai][bj][m][n] = __builtin_amdgcn_mfma_f32_16x16x32_bf16(Bt[n][k], At[m][k], acc[ai][bj][m][n], 0, 0, 0); __builtin_amdgcn_s_setprio(0); } while (0)
; #define PG8_WAIT_V(n) asm volatile("s_waitcnt vmcnt(" #n ")" ::: "memory")
; #define PG8_WAIT_L(n) asm volatile("s_waitcnt lgkmcnt(" #n ")" ::: "memory")
; #define PG8_BAR __builtin_amdgcn_s_barrier()
; #define PG8_SCHED __builtin_amdgcn_sched_barrier(0)
; template <class Epi, bool ALIGN_EPI>
; __device__ __forceinline__ void gemm_phase(LAS unsigned char* lds, const Gemm g, const StaticOrder& S, const Epi& E, const int tid) {
;     ...
;             PG8_WAIT_V(8); PG8_WAIT_L(0); PG8_BAR; PG8_MMA(0, 0, At, B0); PG8_MMA(0, 1, At, B1); PG8_BAR; PG8_SCHED;
	v_mfma_f32_16x16x32_bf16 v[6:9], v[132:135], v[180:183], v[8:11]
	v_mfma_f32_16x16x32_bf16 v[52:55], v[132:135], v[188:191], v[52:55]
	v_mfma_f32_16x16x32_bf16 v[48:51], v[156:159], v[188:191], v[48:51]
	v_mfma_f32_16x16x32_bf16 v[56:59], v[156:159], v[180:183], v[56:59]
	v_mfma_f32_16x16x32_bf16 v[44:47], v[132:135], v[196:199], v[44:47]
	v_mfma_f32_16x16x32_bf16 v[36:39], v[132:135], v[218:221], v[36:39]
	v_mfma_f32_16x16x32_bf16 v[32:35], v[156:159], v[218:221], v[32:35]
	v_mfma_f32_16x16x32_bf16 v[40:43], v[156:159], v[196:199], v[40:43]
	v_mfma_f32_16x16x32_bf16 v[8:11], v[148:151], v[184:187], v[6:9]
	v_mfma_f32_16x16x32_bf16 v[52:55], v[148:151], v[192:195], v[52:55]
	v_mfma_f32_16x16x32_bf16 v[48:51], v[160:163], v[192:195], v[48:51]
	v_mfma_f32_16x16x32_bf16 v[56:59], v[160:163], v[184:187], v[56:59]
	v_mfma_f32_16x16x32_bf16 v[44:47], v[148:151], v[214:217], v[44:47]
	v_mfma_f32_16x16x32_bf16 v[36:39], v[148:151], v[222:225], v[36:39]
	v_mfma_f32_16x16x32_bf16 v[32:35], v[160:163], v[222:225], v[32:35]
	v_mfma_f32_16x16x32_bf16 v[40:43], v[160:163], v[214:217], v[40:43]


; #define PG8_MMA(ai, bj, At, Bt) do { __builtin_amdgcn_s_setprio(1); _Pragma("unroll") for (int m = 0; m < 4; ++m) _Pragma("unroll") for (int n = 0; n < 2; ++n) _Pragma("unroll") for (int k = 0; k < 2; ++k) \
;         acc[ai][bj][m][n] = __builtin_amdgcn_mfma_f32_16x16x32_bf16(Bt[n][k], At[m][k], acc[ai][bj][m][n], 0, 0, 0); __builtin_amdgcn_s_setprio(0); } while (0)
; #define PG8_WAIT_V(n) asm volatile("s_waitcnt vmcnt(" #n ")" ::: "memory")
; #define PG8_WAIT_L(n) asm volatile("s_waitcnt lgkmcnt(" #n ")" ::: "memory")
; #define PG8_BAR __builtin_amdgcn_s_barrier()
; #define PG8_SCHED __builtin_amdgcn_sched_barrier(0)
; template <class Epi, bool ALIGN_EPI>
; __device__ __forceinline__ void gemm_phase(LAS unsigned char* lds, const Gemm g, const StaticOrder& S, const Epi& E, const int tid) {
;     ...
;             PG8_WAIT_V(8); PG8_WAIT_L(0); PG8_BAR; PG8_MMA(0, 0, At, B0); PG8_MMA(0, 1, At, B1); PG8_BAR; PG8_SCHED;
	v_mfma_f32_16x16x32_bf16 v[2:5], v[164:167], v[180:183], v[2:5]
	v_mfma_f32_16x16x32_bf16 v[96:99], v[164:167], v[188:191], v[96:99]
	v_mfma_f32_16x16x32_bf16 v[92:95], v[172:175], v[188:191], v[92:95]
	v_mfma_f32_16x16x32_bf16 v[28:31], v[172:175], v[180:183], v[28:31]
	v_mfma_f32_16x16x32_bf16 v[88:91], v[164:167], v[196:199], v[88:91]
	v_mfma_f32_16x16x32_bf16 v[80:83], v[164:167], v[218:221], v[80:83]
	v_mfma_f32_16x16x32_bf16 v[76:79], v[172:175], v[218:221], v[76:79]
	v_mfma_f32_16x16x32_bf16 v[84:87], v[172:175], v[196:199], v[84:87]
	v_mfma_f32_16x16x32_bf16 v[4:7], v[168:171], v[184:187], v[2:5]
	v_mfma_f32_16x16x32_bf16 v[96:99], v[168:171], v[192:195], v[96:99]
	v_mfma_f32_16x16x32_bf16 v[92:95], v[176:179], v[192:195], v[92:95]
	v_mfma_f32_16x16x32_bf16 v[28:31], v[176:179], v[184:187], v[28:31]
	v_mfma_f32_16x16x32_bf16 v[88:91], v[168:171], v[214:217], v[88:91]
	v_mfma_f32_16x16x32_bf16 v[80:83], v[168:171], v[222:225], v[80:83]
	v_mfma_f32_16x16x32_bf16 v[76:79], v[176:179], v[222:225], v[76:79]
	v_mfma_f32_16x16x32_bf16 v[84:87], v[176:179], v[214:217], v[84:87]

; #define PG8_STAGE(bufoff, gbase, voff) do { _Pragma("unroll") for (int _i = 0; _i < 2; ++_i) \
;         __builtin_amdgcn_global_load_lds((const unsigned*)((const char*)(gbase) + (voff)[_i]), (LAS unsigned*)(lds + (bufoff) + ldsw + _i * 8192), 16, 0, 0); } while (0)
; #define PG8_LDA(dst, b, h) do { _Pragma("unroll") for (int m = 0; m < 4; ++m) _Pragma("unroll") for (int k = 0; k < 2; ++k) dst[m][k] = *(const LAS bf16x8*)(lds + PG8_SA(b, h) + aoff + m * 2048 + k * 1024); } while (0)
; template <class Epi, bool ALIGN_EPI>
; __device__ __forceinline__ void gemm_phase(LAS unsigned char* lds, const Gemm g, const StaticOrder& S, const Epi& E, const int tid) {
;     ...
;             PG8_LDA(At, 1, 1); PG8_STAGE(PG8_SB(1, 0), b3, voffB); PG8_STAGE(PG8_SB(1, 1), b3 + hstepB, voffB); PG8_STAGE(PG8_SA(1, 0), a3, voffA);
	s_barrier
	s_add_u32 s34, s22, 0x8000
	s_addc_u32 s35, s23, 0
	s_add_i32 s87, s87, s61
	s_mov_b32 m0, s87
	ds_read_b128 v[180:183], v155 offset:49152
	ds_read_b128 v[184:187], v155 offset:50176
	ds_read_b128 v[188:191], v155 offset:51200
	ds_read_b128 v[192:195], v155 offset:52224


; #define PG8_STAGE(bufoff, gbase, voff) do { _Pragma("unroll") for (int _i = 0; _i < 2; ++_i) \
;         __builtin_amdgcn_global_load_lds((const unsigned*)((const char*)(gbase) + (voff)[_i]), (LAS unsigned*)(lds + (bufoff) + ldsw + _i * 8192), 16, 0, 0); } while (0)
; #define PG8_LDA(dst, b, h) do { _Pragma("unroll") for (int m = 0; m < 4; ++m) _Pragma("unroll") for (int k = 0; k < 2; ++k) dst[m][k] = *(const LAS bf16x8*)(lds + PG8_SA(b, h) + aoff + m * 2048 + k * 1024); } while (0)
; #define PG8_MMA(ai, bj, At, Bt) do { __builtin_amdgcn_s_setprio(1); _Pragma("unroll") for (int m = 0; m < 4; ++m) _Pragma("unroll") for (int n = 0; n < 2; ++n) _Pragma("unroll") for (int k = 0; k < 2; ++k) \
;         acc[ai][bj][m][n] = __builtin_amdgcn_mfma_f32_16x16x32_bf16(Bt[n][k], At[m][k], acc[ai][bj][m][n], 0, 0, 0); __builtin_amdgcn_s_setprio(0); } while (0)
; #define PG8_WAIT_V(n) asm volatile("s_waitcnt vmcnt(" #n ")" ::: "memory")
; #define PG8_WAIT_L(n) asm volatile("s_waitcnt lgkmcnt(" #n ")" ::: "memory")
; #define PG8_BAR __builtin_amdgcn_s_barrier()
; #define PG8_SCHED __builtin_amdgcn_sched_barrier(0)
; template <class Epi, bool ALIGN_EPI>
; __device__ __forceinline__ void gemm_phase(LAS unsigned char* lds, const Gemm g, const StaticOrder& S, const Epi& E, const int tid) {
;     ...
;             PG8_LDA(At, 1, 1); PG8_STAGE(PG8_SB(1, 0), b3, voffB); PG8_STAGE(PG8_SB(1, 1), b3 + hstepB, voffB); PG8_STAGE(PG8_SA(1, 0), a3, voffA);
;             PG8_WAIT_V(8); PG8_WAIT_L(0); PG8_BAR; PG8_MMA(1, 0, At, B0); PG8_MMA(1, 1, At, B1); PG8_BAR; PG8_SCHED;
	global_load_lds_dwordx4 v140, s[34:35]
	s_add_i32 m0, s87, 0x2000
	s_add_u32 s22, s22, 0xc000
	s_addc_u32 s23, s23, 0
	global_load_lds_dwordx4 v136, s[34:35]
	s_add_i32 s34, s88, s61
	s_mov_b32 m0, s34
	ds_read_b128 v[222:225], v155 offset:56320
	global_load_lds_dwordx4 v140, s[22:23]
	s_add_i32 m0, s34, 0x2000
	ds_read_b128 v[218:221], v155 offset:55296
	global_load_lds_dwordx4 v136, s[22:23]
	v_lshl_add_u64 v[2:3], v[152:153], 0, s[6:7]
	s_mov_b32 m0, s78
	ds_read_b128 v[214:217], v155 offset:54272
	global_load_lds_dwordx4 v[2:3], off
	v_lshl_add_u64 v[2:3], v[200:201], 0, s[6:7]
	s_mov_b32 m0, s79
	ds_read_b128 v[196:199], v155 offset:53248
	global_load_lds_dwordx4 v[2:3], off
	s_waitcnt vmcnt(8)
	s_waitcnt lgkmcnt(0)
	s_barrier


; #define PG8_MMA(ai, bj, At, Bt) do { __builtin_amdgcn_s_setprio(1); _Pragma("unroll") for (int m = 0; m < 4; ++m) _Pragma("unroll") for (int n = 0; n < 2; ++n) _Pragma("unroll") for (int k = 0; k < 2; ++k) \
;         acc[ai][bj][m][n] = __builtin_amdgcn_mfma_f32_16x16x32_bf16(Bt[n][k], At[m][k], acc[ai][bj][m][n], 0, 0, 0); __builtin_amdgcn_s_setprio(0); } while (0)
; #define PG8_WAIT_V(n) asm volatile("s_waitcnt vmcnt(" #n ")" ::: "memory")
; #define PG8_WAIT_L(n) asm volatile("s_waitcnt lgkmcnt(" #n ")" ::: "memory")
; #define PG8_BAR __builtin_amdgcn_s_barrier()
; #define PG8_SCHED __builtin_amdgcn_sched_barrier(0)
; template <class Epi, bool ALIGN_EPI>
; __device__ __forceinline__ void gemm_phase(LAS unsigned char* lds, const Gemm g, const StaticOrder& S, const Epi& E, const int tid) {
;     ...
;             PG8_WAIT_V(8); PG8_WAIT_L(0); PG8_BAR; PG8_MMA(1, 0, At, B0); PG8_MMA(1, 1, At, B1); PG8_BAR; PG8_SCHED;
	v_mfma_f32_16x16x32_bf16 v[24:27], v[132:135], v[180:183], v[24:27]
	v_mfma_f32_16x16x32_bf16 v[64:67], v[132:135], v[188:191], v[64:67]
	v_mfma_f32_16x16x32_bf16 v[72:75], v[156:159], v[188:191], v[72:75]
	v_mfma_f32_16x16x32_bf16 v[20:23], v[156:159], v[180:183], v[20:23]
	v_mfma_f32_16x16x32_bf16 v[16:19], v[132:135], v[196:199], v[16:19]
	v_mfma_f32_16x16x32_bf16 v[60:63], v[132:135], v[218:221], v[60:63]
	v_mfma_f32_16x16x32_bf16 v[68:71], v[156:159], v[218:221], v[68:71]
	v_mfma_f32_16x16x32_bf16 v[12:15], v[156:159], v[196:199], v[12:15]
	v_mfma_f32_16x16x32_bf16 v[24:27], v[148:151], v[184:187], v[24:27]
	v_mfma_f32_16x16x32_bf16 v[64:67], v[148:151], v[192:195], v[64:67]
	v_mfma_f32_16x16x32_bf16 v[72:75], v[160:163], v[192:195], v[72:75]
	v_mfma_f32_16x16x32_bf16 v[20:23], v[160:163], v[184:187], v[20:23]
	v_mfma_f32_16x16x32_bf16 v[16:19], v[148:151], v[214:217], v[16:19]
	v_mfma_f32_16x16x32_bf16 v[60:63], v[148:151], v[222:225], v[60:63]
	v_mfma_f32_16x16x32_bf16 v[68:71], v[160:163], v[222:225], v[68:71]
	v_mfma_f32_16x16x32_bf16 v[12:15], v[160:163], v[214:217], v[12:15]


; #define PG8_MMA(ai, bj, At, Bt) do { __builtin_amdgcn_s_setprio(1); _Pragma("unroll") for (int m = 0; m < 4; ++m) _Pragma("unroll") for (int n = 0; n < 2; ++n) _Pragma("unroll") for (int k = 0; k < 2; ++k) \
;         acc[ai][bj][m][n] = __builtin_amdgcn_mfma_f32_16x16x32_bf16(Bt[n][k], At[m][k], acc[ai][bj][m][n], 0, 0, 0); __builtin_amdgcn_s_setprio(0); } while (0)
; #define PG8_WAIT_V(n) asm volatile("s_waitcnt vmcnt(" #n ")" ::: "memory")
; #define PG8_WAIT_L(n) asm volatile("s_waitcnt lgkmcnt(" #n ")" ::: "memory")
; #define PG8_BAR __builtin_amdgcn_s_barrier()
; #define PG8_SCHED __builtin_amdgcn_sched_barrier(0)
; template <class Epi, bool ALIGN_EPI>
; __device__ __forceinline__ void gemm_phase(LAS unsigned char* lds, const Gemm g, const StaticOrder& S, const Epi& E, const int tid) {
;     ...
;             PG8_WAIT_V(8); PG8_WAIT_L(0); PG8_BAR; PG8_MMA(1, 0, At, B0); PG8_MMA(1, 1, At, B1); PG8_BAR; PG8_SCHED;
	v_mfma_f32_16x16x32_bf16 v[128:131], v[164:167], v[180:183], v[128:131]
	v_mfma_f32_16x16x32_bf16 v[120:123], v[164:167], v[188:191], v[120:123]
	v_mfma_f32_16x16x32_bf16 v[116:119], v[172:175], v[188:191], v[116:119]
	v_mfma_f32_16x16x32_bf16 v[124:127], v[172:175], v[180:183], v[124:127]
	v_mfma_f32_16x16x32_bf16 v[112:115], v[164:167], v[196:199], v[112:115]
	v_mfma_f32_16x16x32_bf16 v[104:107], v[164:167], v[218:221], v[104:107]
	v_mfma_f32_16x16x32_bf16 v[100:103], v[172:175], v[218:221], v[100:103]
	v_mfma_f32_16x16x32_bf16 v[108:111], v[172:175], v[196:199], v[108:111]
	v_mfma_f32_16x16x32_bf16 v[128:131], v[168:171], v[184:187], v[128:131]
	v_mfma_f32_16x16x32_bf16 v[120:123], v[168:171], v[192:195], v[120:123]
	v_mfma_f32_16x16x32_bf16 v[116:119], v[176:179], v[192:195], v[116:119]
	v_mfma_f32_16x16x32_bf16 v[124:127], v[176:179], v[184:187], v[124:127]
	v_mfma_f32_16x16x32_bf16 v[112:115], v[168:171], v[214:217], v[112:115]
	v_mfma_f32_16x16x32_bf16 v[104:107], v[168:171], v[222:225], v[104:107]
	v_mfma_f32_16x16x32_bf16 v[100:103], v[176:179], v[222:225], v[100:103]
	v_mfma_f32_16x16x32_bf16 v[108:111], v[176:179], v[214:217], v[108:111]

; #define PG8_BAR __builtin_amdgcn_s_barrier()
; template <class Epi, bool ALIGN_EPI>
; __device__ __forceinline__ void gemm_phase(LAS unsigned char* lds, const Gemm g, const StaticOrder& S, const Epi& E, const int tid) {
;     ...
;         for (int t = 0; t < nt; t += 2) {
;             const bool last = (t == nt - 2);
;             const char* a1 = cA + (size_t)(t + 1) * kstepA;
;             const char* a2 = last ? nA : cA + (size_t)(t + 2) * kstepA; const char* b2 = last ? nB : cB + (size_t)(t + 2) * kstepB;
;             const char* a3 = a2 + kstepA; const char* b3 = b2 + kstepB;
;             PG8_LDB(B0, 0, 0); PG8_LDB(B1, 0, 1); PG8_SCHED; PG8_LDA(At, 0, 0); PG8_STAGE(PG8_SA(1, 1), a1 + hstepA, voffA);
;             PG8_WAIT_V(8); PG8_WAIT_L(0); PG8_BAR; PG8_MMA(0, 0, At, B0); PG8_MMA(0, 1, At, B1); PG8_BAR; PG8_SCHED;
;             PG8_LDA(At, 0, 1); PG8_STAGE(PG8_SB(0, 0), b2, voffB); PG8_STAGE(PG8_SB(0, 1), b2 + hstepB, voffB); PG8_STAGE(PG8_SA(0, 0), a2, voffA);
;             PG8_WAIT_V(8); PG8_WAIT_L(0); PG8_BAR; PG8_MMA(1, 0, At, B0); PG8_MMA(1, 1, At, B1); PG8_BAR; PG8_SCHED;
;             PG8_LDB(B0, 1, 0); PG8_LDB(B1, 1, 1); PG8_SCHED; PG8_LDA(At, 1, 0); PG8_STAGE(PG8_SA(0, 1), a2 + hstepA, voffA);
;             PG8_WAIT_V(8); PG8_WAIT_L(0); PG8_BAR; PG8_MMA(0, 0, At, B0); PG8_MMA(0, 1, At, B1); PG8_BAR; PG8_SCHED;
;             PG8_LDA(At, 1, 1); PG8_STAGE(PG8_SB(1, 0), b3, voffB); PG8_STAGE(PG8_SB(1, 1), b3 + hstepB, voffB); PG8_STAGE(PG8_SA(1, 0), a3, voffA);
;             PG8_WAIT_V(8); PG8_WAIT_L(0); PG8_BAR; PG8_MMA(1, 0, At, B0); PG8_MMA(1, 1, At, B1); PG8_BAR; PG8_SCHED;
;         }
;         if constexpr (ALIGN_EPI) { if (wr == 0) PG8_BAR; }
;         E(acc, cur, wr, wc, lds, rs_pm);
;     __device__ __forceinline__ void operator()(f32x4 (&acc)[2][2][4][2], const Unit& u, int wr, int wc, LAS unsigned char* lds, int& rs_pm) const {
;         int fr, fq; epi_lane(fr, fq);
;         const int row0 = u.pm * BM + wr * 64 + fr, col0 = u.pn * BM + wc * 32 + 8 * fq; u32x4 zb = zero_frag();
; #pragma unroll
;         for (int ai = 0; ai < 2; ++ai)
; #pragma unroll
;             for (int m = 0; m < 4; ++m) { float ss = 0.f;
;                 bf16* const xrow = xb + (((size_t)(u.pm * 32 + u.pn * 4 + (wc >> 1)) * BM + (wr * 64 + fr + ai * HALF + m * 16)) * 64 + (wc & 1) * 32 + 8 * fq);
; #pragma unroll
;                 for (int bj = 0; bj < 2; ++bj) {
	s_barrier
	s_add_i32 s86, s86, 2
	s_add_u32 s10, s10, 0x100
	s_addc_u32 s11, s11, 0
	s_add_u32 s84, s84, 0x10000
	s_addc_u32 s85, s85, 0
	s_cmp_gt_u32 s86, 29
	s_cbranch_scc0 .LBB0_847
	v_and_b32_e32 v222, 15, v238
	v_lshrrev_b32_e32 v156, 4, v238
	s_lshl_b32 s100, s40, 5
	s_lshl_b32 s101, s41, 2
	v_lshlrev_b32_e32 v222, 7, v222
	s_add_i32 s100, s100, s101
	s_or_b32 s100, s100, s80
	v_lshl_or_b32 v222, v156, 4, v222
	s_ashr_i32 s101, s100, 31
	s_lshl_b64 s[100:101], s[100:101], 15
	s_add_u32 s98, s74, s100
	s_addc_u32 s99, s75, s101
	s_add_u32 s98, s98, s30
	s_addc_u32 s99, s99, s31
	s_lshl_b32 s100, s77, 7
	s_add_u32 s98, s98, s100
	s_addc_u32 s99, s99, 0
	s_lshl_b32 s100, s40, 15
	s_lshl_b32 s101, s77, 7
	s_add_i32 s100, s100, s101
	s_lshl_b32 s101, s41, 4
	s_add_i32 s100, s100, s101
	s_lshl_b32 s101, s76, 2
	s_add_i32 s100, s100, s101
	s_add_u32 s22, s42, s100
	s_addc_u32 s23, s43, 0
	global_load_dwordx4 v[176:179], v222, s[98:99]
	s_add_u32 s100, s98, 0x10000
	s_addc_u32 s101, s99, 0
	global_load_dwordx4 v[180:183], v222, s[100:101]
	global_load_dwordx4 v[184:187], v222, s[98:99] offset:2048
	s_add_u32 s100, s98, 0x10000
	s_addc_u32 s101, s99, 0
	global_load_dwordx4 v[188:191], v222, s[100:101] offset:2048
	s_add_u32 s100, s98, 0x1000
	s_addc_u32 s101, s99, 0
	global_load_dwordx4 v[192:195], v222, s[100:101]
	s_add_u32 s100, s98, 0x11000
	s_addc_u32 s101, s99, 0
	global_load_dwordx4 v[196:199], v222, s[100:101]
	s_add_u32 s100, s98, 0x1000
	s_addc_u32 s101, s99, 0
	global_load_dwordx4 v[214:217], v222, s[100:101] offset:2048
	s_add_u32 s100, s98, 0x11000
	s_addc_u32 s101, s99, 0
	global_load_dwordx4 v[218:221], v222, s[100:101] offset:2048
	s_and_b64 vcc, exec, s[44:45]
	s_cbranch_vccz .LBB0_850
	s_barrier
